# stack1: hand-slimmed GLA chain step (scalar-base LDS-DMA issue, scalar-base o stores), attention QK LDS read double-buffering + deferred work-queue atomic, SP4 4-barrier GEMM loops in all four GEMMs
# baseline (speedup 1.0000x reference)
; DI void phase_attn(const Params& P, int l, LAS unsigned char* lds) {
;     ...
;             asm volatile("s_waitcnt vmcnt(0)" ::: "memory");
;             if (t == t_lo + 1 && tid == 0) slot[2] = pend;
;             asm volatile("s_waitcnt lgkmcnt(0)" ::: "memory");
;             __builtin_amdgcn_s_barrier();
;             asm volatile("" ::: "memory");
;             if (t == t_lo && tid == 0) pend = (int)__hip_atomic_fetch_add(qctr, 1u, __ATOMIC_RELAXED, __HIP_MEMORY_SCOPE_AGENT);
;             {
;               if (t + 1 < t_hi) AT_ISSUE(item, t + 1, (e + 1) & 1);
;               else if (inext < AT_NITEM) { const int ni = inext; AT_ISSUE(ni, (((ni >> 2) & 31) == 0 ? 1 : 0), (e + 1) & 1); }
.LBB0_475:
	s_add_i32 s24, s92, s88
	s_waitcnt vmcnt(0)
	s_cmp_eq_u32 s24, 0
	s_cselect_b64 s[24:25], -1, 0
	s_and_b64 s[26:27], s[0:1], s[24:25]
	s_and_saveexec_b64 s[24:25], s[26:27]
	v_mov_b32_e32 v66, s44
	v_mov_b32_e32 v218, v255
	ds_write_b32 v66, v218
	s_or_b64 exec, exec, s[24:25]
	s_waitcnt lgkmcnt(0)
	s_barrier
	s_cmp_eq_u32 s70, 0
	s_cselect_b64 s[24:25], -1, 0
	s_and_b64 s[26:27], s[0:1], s[24:25]
	s_and_saveexec_b64 s[24:25], s[26:27]
	s_cbranch_execz .LBB0_481
	s_mov_b64 s[28:29], exec
	v_mbcnt_lo_u32_b32 v66, s28, 0
	v_mbcnt_hi_u32_b32 v66, s29, v66
	v_cmp_eq_u32_e32 vcc, 0, v66
	s_and_saveexec_b64 s[26:27], vcc
	s_cbranch_execz .LBB0_480
	s_bcnt1_i32_b64 s28, s[28:29]
	v_mov_b32_e32 v67, s28
	global_atomic_add v255, v159, v67, s[2:3] sc0
.LBB0_480:
	s_or_b64 exec, exec, s[26:27]
.LBB0_481:
	s_or_b64 exec, exec, s[24:25]
	s_add_i32 s24, s4, s88
	s_add_i32 s24, s24, 1
	s_cmp_ge_u32 s24, s87
	s_cbranch_scc0 .LBB0_493
	s_mov_b64 s[24:25], 0
	s_and_b64 vcc, exec, s[20:21]
	s_mov_b64 s[26:27], 0
	s_cbranch_vccnz .LBB0_494
	s_and_b64 vcc, exec, s[24:25]
	v_mov_b64_e32 v[66:67], v[190:191]
	s_cbranch_vccnz .LBB0_495

; #define LAS __attribute__((address_space(3)))
; DI int crow(int r, int hi) { return (r & 3) + 8 * (r >> 2) + 4 * hi; }
; DI void qkt(f32x16& p0, f32x16& p1, const LAS char* Ks, const bf16x8* qr, int r32, int hi) {
;     for (int i = 0; i < 16; ++i) { p0[i] = 0.f; p1[i] = 0.f; }
; #pragma unroll
;     for (int d0 = 0; d0 < 8; ++d0) { const int cb = (d0 * 16 + hi * 8) * 2;
;         const bf16x8 b0 = *(const LAS bf16x8*)(Ks + KSWZ(r32, cb));
;         const bf16x8 b1 = *(const LAS bf16x8*)(Ks + KSWZ(32 + r32, cb));
;         p0 = __builtin_amdgcn_mfma_f32_32x32x16_bf16(b0, qr[d0], p0, 0, 0, 0);
;         p1 = __builtin_amdgcn_mfma_f32_32x32x16_bf16(b1, qr[d0], p1, 0, 0, 0); }
; }
; DI void phase_attn(const Params& P, int l, LAS unsigned char* lds) {
;     ...
;             for (int h2 = 0; h2 < 2; ++h2) {
;                 const int kp0 = (n - 1 + t) * 128 + h2 * 64;
;                 if (kp0 + 63 >= rq - 128 && kp0 <= rq + 159) {
;                     f32x16 p0, p1;
;                     qkt(p0, p1, Bf + h2 * 16384, qr, r32, hi);
;                     const LAS float* tq = tg + (kp0 - rq);
;                     float pmax = -1e30f;
; #pragma unroll
;                     for (int r = 0; r < 16; ++r) { p0[r] += tq[crow(r, hi)]; p1[r] += tq[32 + crow(r, hi)]; pmax = fmaxf(pmax, fmaxf(p0[r], p1[r])); }
;                     pmax = fmaxf(pmax, __shfl_xor(pmax, 32));
.LBB0_486:
	s_and_b32 s25, s91, 0x10000
	s_add_i32 s24, s71, s93
	v_add_u32_e32 v66, s25, v206
	v_add_u32_e32 v223, s25, v215
	s_add_i32 s25, s24, 63
	s_cmp_lt_i32 s25, s89
	s_cselect_b64 s[26:27], -1, 0
	s_cmp_gt_i32 s24, s90
	s_cselect_b64 s[28:29], -1, 0
	s_or_b64 s[26:27], s[26:27], s[28:29]
	s_and_b64 vcc, exec, s[26:27]
	v_add_u32_e32 v232, v66, v147
	v_add_u32_e32 v231, v66, v208
	v_add_u32_e32 v230, v66, v209
	v_add_u32_e32 v229, v66, v210
	v_add_u32_e32 v228, v66, v211
	v_add_u32_e32 v227, v66, v212
	v_add_u32_e32 v226, v66, v213
	v_add_u32_e32 v225, v66, v214
	v_add_u32_e32 v224, s70, v219
	s_cbranch_vccnz .LBB0_490
	ds_read_b128 v[66:69], v232
	ds_read_b128 v[82:85], v232 offset:8192
	ds_read_b128 v[234:237], v231
	ds_read_b128 v[238:241], v231 offset:8192
	v_add_u32_e32 v233, 0x20180, v224
	v_add_u32_e32 v244, 0x20208, v224
	ds_read_b128 v[246:249], v230
	ds_read_b128 v[250:253], v230 offset:8192
	s_waitcnt lgkmcnt(4)
	v_mfma_f32_32x32x16_bf16 v[66:81], v[66:69], v[126:129], 0
	v_mfma_f32_32x32x16_bf16 v[82:97], v[82:85], v[126:129], 0
	s_waitcnt lgkmcnt(2)
	v_mfma_f32_32x32x16_bf16 v[66:81], v[234:237], v[122:125], v[66:81]
	v_mfma_f32_32x32x16_bf16 v[82:97], v[238:241], v[122:125], v[82:97]
	ds_read_b128 v[234:237], v229
	ds_read_b128 v[238:241], v229 offset:8192
	s_waitcnt lgkmcnt(2)
	v_mfma_f32_32x32x16_bf16 v[66:81], v[246:249], v[118:121], v[66:81]
	v_mfma_f32_32x32x16_bf16 v[82:97], v[250:253], v[118:121], v[82:97]
	ds_read_b128 v[246:249], v228
	ds_read_b128 v[250:253], v228 offset:8192
	s_waitcnt lgkmcnt(2)
	v_mfma_f32_32x32x16_bf16 v[66:81], v[234:237], v[114:117], v[66:81]
	v_mfma_f32_32x32x16_bf16 v[82:97], v[238:241], v[114:117], v[82:97]
	ds_read_b128 v[234:237], v227
	ds_read_b128 v[238:241], v227 offset:8192
	s_waitcnt lgkmcnt(2)
	v_mfma_f32_32x32x16_bf16 v[66:81], v[246:249], v[110:113], v[66:81]
	v_mfma_f32_32x32x16_bf16 v[82:97], v[250:253], v[110:113], v[82:97]
	ds_read_b128 v[246:249], v226
	ds_read_b128 v[250:253], v226 offset:8192
	s_waitcnt lgkmcnt(2)
	v_mfma_f32_32x32x16_bf16 v[66:81], v[234:237], v[106:109], v[66:81]
	v_mfma_f32_32x32x16_bf16 v[82:97], v[238:241], v[106:109], v[82:97]
	ds_read_b128 v[234:237], v225
	ds_read_b128 v[238:241], v225 offset:8192
	s_waitcnt lgkmcnt(2)
	v_mfma_f32_32x32x16_bf16 v[66:81], v[246:249], v[102:105], v[66:81]
	v_mfma_f32_32x32x16_bf16 v[82:97], v[250:253], v[102:105], v[82:97]
	ds_read2_b32 v[242:243], v233 offset1:1
	v_add_u32_e32 v233, 0x20200, v224
	s_waitcnt lgkmcnt(0)
	v_mfma_f32_32x32x16_bf16 v[66:81], v[234:237], v[98:101], v[66:81]
	v_add_u32_e32 v236, 0x20188, v224
	ds_read2_b32 v[234:235], v233 offset1:1
	ds_read2_b32 v[236:237], v236 offset1:1
	ds_read2_b32 v[244:245], v244 offset1:1
	v_mfma_f32_32x32x16_bf16 v[82:97], v[238:241], v[98:101], v[82:97]
	s_nop 6
	v_add_f32_e32 v233, v66, v242
	v_add_f32_e32 v238, v67, v243
	s_waitcnt lgkmcnt(0)
	v_add_f32_e32 v236, v68, v236
	v_add_f32_e32 v237, v69, v237
	v_add_f32_e32 v234, v82, v234
	v_add_f32_e32 v235, v83, v235
	v_max_f32_e32 v66, v233, v234
	v_max_f32_e32 v67, v238, v235
	v_add_f32_e32 v239, v84, v244
	v_add_f32_e32 v240, v85, v245
	v_max3_f32 v66, v66, s74, v67
	v_max_f32_e32 v67, v236, v239
	v_max_f32_e32 v68, v237, v240
	v_max3_f32 v241, v66, v67, v68
	v_add_u32_e32 v66, 0x201a0, v224
	v_add_u32_e32 v68, 0x20220, v224
	ds_read2_b32 v[66:67], v66 offset1:1
	ds_read2_b32 v[68:69], v68 offset1:1
	v_add_u32_e32 v82, 0x201a8, v224
	v_add_u32_e32 v84, 0x20228, v224
	ds_read2_b32 v[82:83], v82 offset1:1
	ds_read2_b32 v[84:85], v84 offset1:1
	s_waitcnt lgkmcnt(0)
	v_add_f32_e32 v242, v70, v66
	v_add_f32_e32 v86, v86, v68
	v_add_f32_e32 v243, v71, v67
	v_add_f32_e32 v87, v87, v69
	v_max_f32_e32 v66, v242, v86
	v_max_f32_e32 v67, v243, v87
	v_add_f32_e32 v82, v72, v82
	v_add_f32_e32 v84, v88, v84
	v_add_f32_e32 v83, v73, v83
	v_add_f32_e32 v85, v89, v85
	v_max3_f32 v66, v241, v66, v67
	v_max_f32_e32 v67, v82, v84
	v_max_f32_e32 v68, v83, v85
	v_max3_f32 v88, v66, v67, v68
	v_add_u32_e32 v66, 0x201c0, v224
	v_add_u32_e32 v68, 0x20240, v224
	ds_read2_b32 v[66:67], v66 offset1:1
	ds_read2_b32 v[68:69], v68 offset1:1
	v_add_u32_e32 v70, 0x201c8, v224
	v_add_u32_e32 v72, 0x20248, v224
	ds_read2_b32 v[70:71], v70 offset1:1
	ds_read2_b32 v[72:73], v72 offset1:1
	s_waitcnt lgkmcnt(0)
	v_add_f32_e32 v74, v74, v66
	v_add_f32_e32 v89, v90, v68
	v_add_f32_e32 v75, v75, v67
	v_add_f32_e32 v90, v91, v69
	v_max_f32_e32 v66, v74, v89
	v_max_f32_e32 v67, v75, v90
	v_max3_f32 v66, v88, v66, v67
	v_add_f32_e32 v76, v76, v70
	v_add_f32_e32 v88, v92, v72
	v_add_f32_e32 v77, v77, v71
	v_add_f32_e32 v91, v93, v73
	v_max_f32_e32 v67, v76, v88
	v_max_f32_e32 v68, v77, v91
	v_max3_f32 v92, v66, v67, v68
	v_add_u32_e32 v66, 0x201e0, v224
	v_add_u32_e32 v68, 0x20260, v224
	ds_read2_b32 v[66:67], v66 offset1:1
	ds_read2_b32 v[68:69], v68 offset1:1
	v_add_u32_e32 v70, 0x201e8, v224
	v_add_u32_e32 v72, 0x20268, v224
	ds_read2_b32 v[70:71], v70 offset1:1
	ds_read2_b32 v[72:73], v72 offset1:1
	s_waitcnt lgkmcnt(0)
	v_add_f32_e32 v66, v78, v66
	v_add_f32_e32 v68, v94, v68
	v_add_f32_e32 v67, v79, v67
	v_add_f32_e32 v69, v95, v69
	v_max_f32_e32 v78, v66, v68
	v_max_f32_e32 v79, v67, v69
	v_add_f32_e32 v70, v80, v70
	v_add_f32_e32 v72, v96, v72
	v_add_f32_e32 v71, v81, v71
	v_add_f32_e32 v73, v97, v73
	v_max3_f32 v78, v92, v78, v79
	v_max_f32_e32 v79, v70, v72
	v_max_f32_e32 v80, v71, v73
	v_max3_f32 v78, v78, v79, v80
	v_and_b32_e32 v80, 64, v217
	v_xor_b32_e32 v79, 32, v217
	v_add_u32_e32 v80, 64, v80
	v_cmp_lt_i32_e32 vcc, v79, v80
	s_nop 1
	v_cndmask_b32_e32 v79, v217, v79, vcc
	v_lshlrev_b32_e32 v79, 2, v79
	ds_bpermute_b32 v80, v79, v78
	s_waitcnt lgkmcnt(0)
; DI void phase_attn(const Params& P, int l, LAS unsigned char* lds) {
;     ...
;                     pmax = fmaxf(pmax, __shfl_xor(pmax, 32));
;                     float mn = m_run, alpha = 1.f;
;                     if (!__all(pmax - m_run <= 8.f)) { mn = fmaxf(m_run, pmax); alpha = __builtin_amdgcn_exp2f(m_run - mn); m_run = mn; }
;                     float ps = 0.f;
; #pragma unroll
;                     for (int r = 0; r < 16; ++r) { p0[r] = __builtin_amdgcn_exp2f(p0[r] - mn); p1[r] = __builtin_amdgcn_exp2f(p1[r] - mn); ps += p0[r] + p1[r]; }
;                     ps += __shfl_xor(ps, 32);
;                     l_run = l_run * alpha + ps;
;                     bf16x8 pa0, pa1, pa2, pa3;
;     ...
;                     PK4(p0, 0, pa0); PK4(p0, 8, pa1); PK4(p1, 0, pa2); PK4(p1, 8, pa3);
;     ...
;                     if (__any(alpha < 1.f)) {
; #pragma unroll
;                         for (int d = 0; d < 4; ++d)
; #pragma unroll
;                             for (int r = 0; r < 16; ++r) o[d][r] *= alpha; }
	v_max_f32_e32 v80, v80, v80
	v_max_f32_e32 v78, v78, v80
	v_sub_f32_e32 v80, v78, v220
	v_cmp_ge_f32_e32 vcc, s75, v80
	s_cmp_eq_u64 vcc, exec
	v_max_f32_e32 v80, v220, v220
	v_max_f32_e32 v78, v80, v78
	s_cselect_b64 vcc, -1, 0
	v_sub_f32_e32 v80, v220, v78
	v_cndmask_b32_e32 v220, v78, v220, vcc
	v_sub_f32_e32 v78, v233, v220
	v_sub_f32_e32 v81, v234, v220
	v_exp_f32_e32 v78, v78
	v_exp_f32_e32 v81, v81
	v_sub_f32_e32 v92, v238, v220
	v_sub_f32_e32 v93, v235, v220
	v_exp_f32_e32 v92, v92
	v_exp_f32_e32 v93, v93
	v_sub_f32_e32 v96, v236, v220
	v_sub_f32_e32 v97, v239, v220
	v_exp_f32_e32 v96, v96
	v_exp_f32_e32 v97, v97
	v_sub_f32_e32 v233, v237, v220
	v_sub_f32_e32 v234, v240, v220
	v_exp_f32_e32 v233, v233
	v_exp_f32_e32 v234, v234
	v_sub_f32_e32 v235, v242, v220
	v_sub_f32_e32 v86, v86, v220
	v_sub_f32_e32 v82, v82, v220
	v_add_f32_e32 v94, v78, v81
	v_exp_f32_e32 v235, v235
	v_exp_f32_e32 v86, v86
	v_sub_f32_e32 v236, v243, v220
	v_sub_f32_e32 v87, v87, v220
	v_exp_f32_e32 v237, v82
	v_sub_f32_e32 v82, v84, v220
	v_add_f32_e32 v94, 0, v94
	v_add_f32_e32 v95, v92, v93
	v_exp_f32_e32 v236, v236
	v_exp_f32_e32 v87, v87
	v_exp_f32_e32 v238, v82
	v_sub_f32_e32 v82, v83, v220
	v_add_f32_e32 v94, v95, v94
	v_add_f32_e32 v95, v96, v97
	v_exp_f32_e32 v239, v82
	v_sub_f32_e32 v82, v85, v220
	v_add_f32_e32 v94, v95, v94
	v_add_f32_e32 v95, v233, v234
	v_exp_f32_e32 v85, v82
	v_sub_f32_e32 v74, v74, v220
	v_sub_f32_e32 v84, v89, v220
	v_add_f32_e32 v94, v95, v94
	v_add_f32_e32 v95, v235, v86
	v_exp_f32_e32 v74, v74
	v_exp_f32_e32 v89, v84
	v_sub_f32_e32 v75, v75, v220
	v_sub_f32_e32 v84, v90, v220
	v_add_f32_e32 v94, v95, v94
	v_add_f32_e32 v95, v236, v87
	v_exp_f32_e32 v75, v75
	v_exp_f32_e32 v90, v84
	v_sub_f32_e32 v76, v76, v220
	v_sub_f32_e32 v84, v88, v220
	v_sub_f32_e32 v66, v66, v220
	v_add_f32_e32 v82, v95, v94
	v_add_f32_e32 v83, v237, v238
	v_exp_f32_e32 v76, v76
	v_exp_f32_e32 v88, v84
	v_sub_f32_e32 v77, v77, v220
	v_sub_f32_e32 v84, v91, v220
	v_exp_f32_e32 v94, v66
	v_sub_f32_e32 v66, v68, v220
	v_add_f32_e32 v82, v83, v82
	v_add_f32_e32 v83, v239, v85
	v_exp_f32_e32 v77, v77
	v_exp_f32_e32 v91, v84
	v_exp_f32_e32 v95, v66
	v_sub_f32_e32 v66, v67, v220
	v_sub_f32_e32 v68, v70, v220
	v_add_f32_e32 v82, v83, v82
	v_add_f32_e32 v83, v74, v89
	v_exp_f32_e32 v240, v66
	v_sub_f32_e32 v66, v69, v220
	v_exp_f32_e32 v242, v68
	v_sub_f32_e32 v68, v72, v220
	v_add_f32_e32 v82, v83, v82
	v_add_f32_e32 v83, v75, v90
	v_exp_f32_e32 v241, v66
	v_exp_f32_e32 v243, v68
	v_sub_f32_e32 v68, v71, v220
	v_add_f32_e32 v82, v83, v82
	v_add_f32_e32 v83, v76, v88
	v_exp_f32_e32 v244, v68
	v_sub_f32_e32 v68, v73, v220
	v_add_f32_e32 v82, v83, v82
	v_add_f32_e32 v83, v77, v91
	v_exp_f32_e32 v245, v68
	v_add_f32_e32 v66, v83, v82
	v_add_f32_e32 v67, v94, v95
	v_add_f32_e32 v66, v67, v66
	v_add_f32_e32 v67, v240, v241
	v_add_f32_e32 v66, v67, v66
	v_add_f32_e32 v67, v242, v243
	v_add_f32_e32 v66, v67, v66
	v_add_f32_e32 v67, v244, v245
	v_exp_f32_e32 v80, v80
	v_add_f32_e32 v83, v67, v66
	ds_bpermute_b32 v84, v79, v83
	v_cvt_pk_bf16_f32 v66, v78, v92
	v_cndmask_b32_e64 v82, v80, 1.0, vcc
	v_cvt_pk_bf16_f32 v67, v96, v233
	v_cvt_pk_bf16_f32 v68, v235, v236
	v_cvt_pk_bf16_f32 v69, v237, v239
	v_cvt_pk_bf16_f32 v70, v74, v75
	v_cvt_pk_bf16_f32 v71, v76, v77
	v_cvt_pk_bf16_f32 v72, v94, v240
	v_cvt_pk_bf16_f32 v73, v242, v244
	v_cvt_pk_bf16_f32 v74, v81, v93
	v_cvt_pk_bf16_f32 v75, v97, v234
	v_cvt_pk_bf16_f32 v76, v86, v87
	v_cvt_pk_bf16_f32 v77, v238, v85
	v_cvt_pk_bf16_f32 v78, v89, v90
	v_cvt_pk_bf16_f32 v79, v88, v91
	v_cvt_pk_bf16_f32 v80, v95, v241
	v_cvt_pk_bf16_f32 v81, v243, v245
	s_nop 0
	v_permlane32_swap_b32_e32 v66, v68
	v_permlane32_swap_b32_e32 v67, v69
	v_permlane32_swap_b32_e32 v70, v72
	v_permlane32_swap_b32_e32 v71, v73
	v_permlane32_swap_b32_e32 v74, v76
	v_permlane32_swap_b32_e32 v75, v77
	v_permlane32_swap_b32_e32 v78, v80
	v_permlane32_swap_b32_e32 v79, v81
	v_cmp_gt_f32_e32 vcc, 1.0, v82
	s_cbranch_vccz .LBB0_489
	v_pk_mul_f32 v[64:65], v[64:65], v[82:83] op_sel_hi:[1,0]
	v_pk_mul_f32 v[62:63], v[62:63], v[82:83] op_sel_hi:[1,0]
	v_pk_mul_f32 v[60:61], v[60:61], v[82:83] op_sel_hi:[1,0]
	v_pk_mul_f32 v[58:59], v[58:59], v[82:83] op_sel_hi:[1,0]
	v_pk_mul_f32 v[56:57], v[56:57], v[82:83] op_sel_hi:[1,0]
	v_pk_mul_f32 v[54:55], v[54:55], v[82:83] op_sel_hi:[1,0]
	v_pk_mul_f32 v[52:53], v[52:53], v[82:83] op_sel_hi:[1,0]
	v_pk_mul_f32 v[50:51], v[50:51], v[82:83] op_sel_hi:[1,0]
	v_pk_mul_f32 v[48:49], v[48:49], v[82:83] op_sel_hi:[1,0]
	v_pk_mul_f32 v[46:47], v[46:47], v[82:83] op_sel_hi:[1,0]
	v_pk_mul_f32 v[44:45], v[44:45], v[82:83] op_sel_hi:[1,0]
	v_pk_mul_f32 v[42:43], v[42:43], v[82:83] op_sel_hi:[1,0]
	v_pk_mul_f32 v[40:41], v[40:41], v[82:83] op_sel_hi:[1,0]
	v_pk_mul_f32 v[38:39], v[38:39], v[82:83] op_sel_hi:[1,0]
	v_pk_mul_f32 v[36:37], v[36:37], v[82:83] op_sel_hi:[1,0]
	v_pk_mul_f32 v[34:35], v[34:35], v[82:83] op_sel_hi:[1,0]
	v_pk_mul_f32 v[32:33], v[32:33], v[82:83] op_sel_hi:[1,0]
	v_pk_mul_f32 v[30:31], v[30:31], v[82:83] op_sel_hi:[1,0]
	v_pk_mul_f32 v[28:29], v[28:29], v[82:83] op_sel_hi:[1,0]
	v_pk_mul_f32 v[26:27], v[26:27], v[82:83] op_sel_hi:[1,0]
	v_pk_mul_f32 v[24:25], v[24:25], v[82:83] op_sel_hi:[1,0]
	v_pk_mul_f32 v[22:23], v[22:23], v[82:83] op_sel_hi:[1,0]
	v_pk_mul_f32 v[20:21], v[20:21], v[82:83] op_sel_hi:[1,0]
	v_pk_mul_f32 v[18:19], v[18:19], v[82:83] op_sel_hi:[1,0]
	v_pk_mul_f32 v[16:17], v[16:17], v[82:83] op_sel_hi:[1,0]
	v_pk_mul_f32 v[14:15], v[14:15], v[82:83] op_sel_hi:[1,0]
	v_pk_mul_f32 v[12:13], v[12:13], v[82:83] op_sel_hi:[1,0]
	v_pk_mul_f32 v[10:11], v[10:11], v[82:83] op_sel_hi:[1,0]
	v_pk_mul_f32 v[8:9], v[8:9], v[82:83] op_sel_hi:[1,0]
	v_pk_mul_f32 v[6:7], v[6:7], v[82:83] op_sel_hi:[1,0]
	v_pk_mul_f32 v[4:5], v[4:5], v[82:83] op_sel_hi:[1,0]
	v_pk_mul_f32 v[2:3], v[2:3], v[82:83] op_sel_hi:[1,0]

; #define LAS __attribute__((address_space(3)))
; DI int crow(int r, int hi) { return (r & 3) + 8 * (r >> 2) + 4 * hi; }
; DI void qkt(f32x16& p0, f32x16& p1, const LAS char* Ks, const bf16x8* qr, int r32, int hi) {
;     for (int i = 0; i < 16; ++i) { p0[i] = 0.f; p1[i] = 0.f; }
; #pragma unroll
;     for (int d0 = 0; d0 < 8; ++d0) { const int cb = (d0 * 16 + hi * 8) * 2;
;         const bf16x8 b0 = *(const LAS bf16x8*)(Ks + KSWZ(r32, cb));
;         const bf16x8 b1 = *(const LAS bf16x8*)(Ks + KSWZ(32 + r32, cb));
;         p0 = __builtin_amdgcn_mfma_f32_32x32x16_bf16(b0, qr[d0], p0, 0, 0, 0);
;         p1 = __builtin_amdgcn_mfma_f32_32x32x16_bf16(b1, qr[d0], p1, 0, 0, 0); }
; }
; DI void phase_attn(const Params& P, int l, LAS unsigned char* lds) {
;     ...
;             for (int h2 = 0; h2 < 2; ++h2) {
;                 const int kp0 = (n - 1 + t) * 128 + h2 * 64;
;                 if (kp0 + 63 >= rq - 128 && kp0 <= rq + 159) {
;                     f32x16 p0, p1;
;                     qkt(p0, p1, Bf + h2 * 16384, qr, r32, hi);
;                     const LAS float* tq = tg + (kp0 - rq);
;                     float pmax = -1e30f;
; #pragma unroll
;                     for (int r = 0; r < 16; ++r) { p0[r] += tq[crow(r, hi)]; p1[r] += tq[32 + crow(r, hi)]; pmax = fmaxf(pmax, fmaxf(p0[r], p1[r])); }
;                     pmax = fmaxf(pmax, __shfl_xor(pmax, 32));
.LBB0_490:
	s_add_i32 s26, s24, 64
	s_addk_i32 s24, 0x7f
	s_cmp_lt_i32 s24, s89
	s_cselect_b64 s[24:25], -1, 0
	s_cmp_gt_i32 s26, s90
	s_cselect_b64 s[26:27], -1, 0
	s_or_b64 s[24:25], s[24:25], s[26:27]
	s_and_b64 vcc, exec, s[24:25]
	s_cbranch_vccnz .LBB0_474
	ds_read_b128 v[66:69], v232 offset:16384
	ds_read_b128 v[82:85], v232 offset:24576
	ds_read_b128 v[232:235], v231 offset:16384
	ds_read_b128 v[236:239], v231 offset:24576
	ds_read_b128 v[246:249], v230 offset:16384
	ds_read_b128 v[250:253], v230 offset:24576
	s_waitcnt lgkmcnt(4)
	v_mfma_f32_32x32x16_bf16 v[66:81], v[66:69], v[126:129], 0
	v_mfma_f32_32x32x16_bf16 v[82:97], v[82:85], v[126:129], 0
	s_waitcnt lgkmcnt(2)
	v_mfma_f32_32x32x16_bf16 v[66:81], v[232:235], v[122:125], v[66:81]
	v_mfma_f32_32x32x16_bf16 v[82:97], v[236:239], v[122:125], v[82:97]
	ds_read_b128 v[230:233], v229 offset:16384
	ds_read_b128 v[234:237], v229 offset:24576
	s_waitcnt lgkmcnt(2)
	v_mfma_f32_32x32x16_bf16 v[66:81], v[246:249], v[118:121], v[66:81]
	v_mfma_f32_32x32x16_bf16 v[82:97], v[250:253], v[118:121], v[82:97]
	ds_read_b128 v[246:249], v228 offset:16384
	ds_read_b128 v[250:253], v228 offset:24576
	s_waitcnt lgkmcnt(2)
	v_mfma_f32_32x32x16_bf16 v[66:81], v[230:233], v[114:117], v[66:81]
	v_mfma_f32_32x32x16_bf16 v[82:97], v[234:237], v[114:117], v[82:97]
	ds_read_b128 v[228:231], v227 offset:16384
	ds_read_b128 v[232:235], v227 offset:24576
	s_waitcnt lgkmcnt(2)
	v_mfma_f32_32x32x16_bf16 v[66:81], v[246:249], v[110:113], v[66:81]
	v_mfma_f32_32x32x16_bf16 v[82:97], v[250:253], v[110:113], v[82:97]
	ds_read_b128 v[246:249], v226 offset:16384
	ds_read_b128 v[250:253], v226 offset:24576
	v_add_u32_e32 v236, 0x20308, v224
	s_waitcnt lgkmcnt(2)
	v_mfma_f32_32x32x16_bf16 v[66:81], v[228:231], v[106:109], v[66:81]
	v_mfma_f32_32x32x16_bf16 v[82:97], v[232:235], v[106:109], v[82:97]
	ds_read_b128 v[226:229], v225 offset:16384
	ds_read_b128 v[230:233], v225 offset:24576
	s_waitcnt lgkmcnt(2)
	v_mfma_f32_32x32x16_bf16 v[66:81], v[246:249], v[102:105], v[66:81]
	v_mfma_f32_32x32x16_bf16 v[82:97], v[250:253], v[102:105], v[82:97]
	v_add_u32_e32 v225, 0x20280, v224
	ds_read2_b32 v[234:235], v225 offset1:1
	v_add_u32_e32 v225, 0x20300, v224
	s_waitcnt lgkmcnt(0)
	v_mfma_f32_32x32x16_bf16 v[66:81], v[226:229], v[98:101], v[66:81]
	v_add_u32_e32 v228, 0x20288, v224
	ds_read2_b32 v[226:227], v225 offset1:1
	ds_read2_b32 v[228:229], v228 offset1:1
	ds_read2_b32 v[236:237], v236 offset1:1
	v_mfma_f32_32x32x16_bf16 v[82:97], v[230:233], v[98:101], v[82:97]
	s_nop 6
	v_add_f32_e32 v225, v66, v234
	v_add_f32_e32 v230, v67, v235
	s_waitcnt lgkmcnt(0)
	v_add_f32_e32 v228, v68, v228
	v_add_f32_e32 v229, v69, v229
	v_add_f32_e32 v226, v82, v226
	v_add_f32_e32 v227, v83, v227
	v_max_f32_e32 v66, v225, v226
	v_max_f32_e32 v67, v230, v227
	v_add_f32_e32 v231, v84, v236
	v_add_f32_e32 v232, v85, v237
	v_max3_f32 v66, v66, s74, v67
	v_max_f32_e32 v67, v228, v231
	v_max_f32_e32 v68, v229, v232
	v_max3_f32 v233, v66, v67, v68
	v_add_u32_e32 v66, 0x202a0, v224
	v_add_u32_e32 v68, 0x20320, v224
	ds_read2_b32 v[66:67], v66 offset1:1
	ds_read2_b32 v[68:69], v68 offset1:1
	v_add_u32_e32 v82, 0x202a8, v224
	v_add_u32_e32 v84, 0x20328, v224
	ds_read2_b32 v[82:83], v82 offset1:1
	ds_read2_b32 v[84:85], v84 offset1:1
	s_waitcnt lgkmcnt(0)
	v_add_f32_e32 v234, v70, v66
	v_add_f32_e32 v86, v86, v68
	v_add_f32_e32 v235, v71, v67
	v_add_f32_e32 v87, v87, v69
	v_max_f32_e32 v66, v234, v86
	v_max_f32_e32 v67, v235, v87
	v_add_f32_e32 v82, v72, v82
	v_add_f32_e32 v84, v88, v84
	v_add_f32_e32 v83, v73, v83
	v_add_f32_e32 v85, v89, v85
	v_max3_f32 v66, v233, v66, v67
	v_max_f32_e32 v67, v82, v84
	v_max_f32_e32 v68, v83, v85
	v_max3_f32 v88, v66, v67, v68
	v_add_u32_e32 v66, 0x202c0, v224
	v_add_u32_e32 v68, 0x20340, v224
	ds_read2_b32 v[66:67], v66 offset1:1
	ds_read2_b32 v[68:69], v68 offset1:1
	v_add_u32_e32 v70, 0x202c8, v224
	v_add_u32_e32 v72, 0x20348, v224
	ds_read2_b32 v[70:71], v70 offset1:1
	ds_read2_b32 v[72:73], v72 offset1:1
	s_waitcnt lgkmcnt(0)
	v_add_f32_e32 v74, v74, v66
	v_add_f32_e32 v89, v90, v68
	v_add_f32_e32 v75, v75, v67
	v_add_f32_e32 v90, v91, v69
	v_max_f32_e32 v66, v74, v89
	v_max_f32_e32 v67, v75, v90
	v_max3_f32 v66, v88, v66, v67
	v_add_f32_e32 v76, v76, v70
	v_add_f32_e32 v88, v92, v72
	v_add_f32_e32 v77, v77, v71
	v_add_f32_e32 v91, v93, v73
	v_max_f32_e32 v67, v76, v88
	v_max_f32_e32 v68, v77, v91
	v_max3_f32 v92, v66, v67, v68
	v_add_u32_e32 v66, 0x202e0, v224
	v_add_u32_e32 v68, 0x20360, v224
	ds_read2_b32 v[66:67], v66 offset1:1
	ds_read2_b32 v[68:69], v68 offset1:1
	v_add_u32_e32 v70, 0x202e8, v224
	v_add_u32_e32 v72, 0x20368, v224
	ds_read2_b32 v[70:71], v70 offset1:1
	ds_read2_b32 v[72:73], v72 offset1:1
	s_waitcnt lgkmcnt(0)
	v_add_f32_e32 v66, v78, v66
	v_add_f32_e32 v68, v94, v68
	v_add_f32_e32 v67, v79, v67
	v_add_f32_e32 v69, v95, v69
	v_max_f32_e32 v78, v66, v68
	v_max_f32_e32 v79, v67, v69
	v_add_f32_e32 v70, v80, v70
	v_add_f32_e32 v72, v96, v72
	v_add_f32_e32 v71, v81, v71
	v_add_f32_e32 v73, v97, v73
	v_max3_f32 v78, v92, v78, v79
	v_max_f32_e32 v79, v70, v72
	v_max_f32_e32 v80, v71, v73
	v_max3_f32 v78, v78, v79, v80
	v_and_b32_e32 v80, 64, v217
	v_xor_b32_e32 v79, 32, v217
	v_add_u32_e32 v80, 64, v80
	v_cmp_lt_i32_e32 vcc, v79, v80
	s_nop 1
	v_cndmask_b32_e32 v79, v217, v79, vcc
	v_lshlrev_b32_e32 v79, 2, v79
	ds_bpermute_b32 v80, v79, v78
	s_waitcnt lgkmcnt(0)
; DI void phase_attn(const Params& P, int l, LAS unsigned char* lds) {
;     ...
;                     pmax = fmaxf(pmax, __shfl_xor(pmax, 32));
;                     float mn = m_run, alpha = 1.f;
;                     if (!__all(pmax - m_run <= 8.f)) { mn = fmaxf(m_run, pmax); alpha = __builtin_amdgcn_exp2f(m_run - mn); m_run = mn; }
;                     float ps = 0.f;
; #pragma unroll
;                     for (int r = 0; r < 16; ++r) { p0[r] = __builtin_amdgcn_exp2f(p0[r] - mn); p1[r] = __builtin_amdgcn_exp2f(p1[r] - mn); ps += p0[r] + p1[r]; }
;                     ps += __shfl_xor(ps, 32);
;                     l_run = l_run * alpha + ps;
;                     bf16x8 pa0, pa1, pa2, pa3;
;     ...
;                     PK4(p0, 0, pa0); PK4(p0, 8, pa1); PK4(p1, 0, pa2); PK4(p1, 8, pa3);
;     ...
;                     if (__any(alpha < 1.f)) {
; #pragma unroll
;                         for (int d = 0; d < 4; ++d)
; #pragma unroll
;                             for (int r = 0; r < 16; ++r) o[d][r] *= alpha; }
	v_max_f32_e32 v80, v80, v80
	v_max_f32_e32 v78, v78, v80
	v_sub_f32_e32 v80, v78, v220
	v_cmp_ge_f32_e32 vcc, s75, v80
	s_cmp_eq_u64 vcc, exec
	v_max_f32_e32 v80, v220, v220
	v_max_f32_e32 v78, v80, v78
	s_cselect_b64 vcc, -1, 0
	v_sub_f32_e32 v80, v220, v78
	v_cndmask_b32_e32 v220, v78, v220, vcc
	v_sub_f32_e32 v78, v225, v220
	v_sub_f32_e32 v81, v226, v220
	v_exp_f32_e32 v78, v78
	v_exp_f32_e32 v81, v81
	v_sub_f32_e32 v92, v230, v220
	v_sub_f32_e32 v93, v227, v220
	v_exp_f32_e32 v92, v92
	v_exp_f32_e32 v93, v93
	v_sub_f32_e32 v96, v228, v220
	v_sub_f32_e32 v97, v231, v220
	v_exp_f32_e32 v96, v96
	v_exp_f32_e32 v97, v97
	v_sub_f32_e32 v224, v229, v220
	v_sub_f32_e32 v225, v232, v220
	v_exp_f32_e32 v224, v224
	v_exp_f32_e32 v225, v225
	v_sub_f32_e32 v226, v234, v220
	v_sub_f32_e32 v86, v86, v220
	v_sub_f32_e32 v82, v82, v220
	v_add_f32_e32 v94, v78, v81
	v_exp_f32_e32 v226, v226
	v_exp_f32_e32 v86, v86
	v_sub_f32_e32 v227, v235, v220
	v_sub_f32_e32 v87, v87, v220
	v_exp_f32_e32 v228, v82
	v_sub_f32_e32 v82, v84, v220
	v_add_f32_e32 v94, 0, v94
	v_add_f32_e32 v95, v92, v93
	v_exp_f32_e32 v227, v227
	v_exp_f32_e32 v87, v87
	v_exp_f32_e32 v229, v82
	v_sub_f32_e32 v82, v83, v220
	v_add_f32_e32 v94, v95, v94
	v_add_f32_e32 v95, v96, v97
	v_exp_f32_e32 v230, v82
	v_sub_f32_e32 v82, v85, v220
	v_add_f32_e32 v94, v95, v94
	v_add_f32_e32 v95, v224, v225
	v_exp_f32_e32 v85, v82
	v_sub_f32_e32 v74, v74, v220
	v_sub_f32_e32 v84, v89, v220
	v_add_f32_e32 v94, v95, v94
	v_add_f32_e32 v95, v226, v86
	v_exp_f32_e32 v74, v74
	v_exp_f32_e32 v89, v84
	v_sub_f32_e32 v75, v75, v220
	v_sub_f32_e32 v84, v90, v220
	v_add_f32_e32 v94, v95, v94
	v_add_f32_e32 v95, v227, v87
	v_exp_f32_e32 v75, v75
	v_exp_f32_e32 v90, v84
	v_sub_f32_e32 v76, v76, v220
	v_sub_f32_e32 v84, v88, v220
	v_sub_f32_e32 v66, v66, v220
	v_add_f32_e32 v82, v95, v94
	v_add_f32_e32 v83, v228, v229
	v_exp_f32_e32 v76, v76
	v_exp_f32_e32 v88, v84
	v_sub_f32_e32 v77, v77, v220
	v_sub_f32_e32 v84, v91, v220
	v_exp_f32_e32 v94, v66
	v_sub_f32_e32 v66, v68, v220
	v_add_f32_e32 v82, v83, v82
	v_add_f32_e32 v83, v230, v85
	v_exp_f32_e32 v77, v77
	v_exp_f32_e32 v91, v84
	v_exp_f32_e32 v95, v66
	v_sub_f32_e32 v66, v67, v220
	v_sub_f32_e32 v68, v70, v220
	v_add_f32_e32 v82, v83, v82
	v_add_f32_e32 v83, v74, v89
	v_exp_f32_e32 v231, v66
	v_sub_f32_e32 v66, v69, v220
	v_exp_f32_e32 v233, v68
	v_sub_f32_e32 v68, v72, v220
	v_add_f32_e32 v82, v83, v82
	v_add_f32_e32 v83, v75, v90
	v_exp_f32_e32 v232, v66
	v_exp_f32_e32 v234, v68
	v_sub_f32_e32 v68, v71, v220
	v_add_f32_e32 v82, v83, v82
	v_add_f32_e32 v83, v76, v88
	v_exp_f32_e32 v235, v68
	v_sub_f32_e32 v68, v73, v220
	v_add_f32_e32 v82, v83, v82
	v_add_f32_e32 v83, v77, v91
	v_exp_f32_e32 v236, v68
	v_add_f32_e32 v66, v83, v82
	v_add_f32_e32 v67, v94, v95
	v_add_f32_e32 v66, v67, v66
	v_add_f32_e32 v67, v231, v232
	v_add_f32_e32 v66, v67, v66
	v_add_f32_e32 v67, v233, v234
	v_add_f32_e32 v66, v67, v66
	v_add_f32_e32 v67, v235, v236
	v_exp_f32_e32 v80, v80
	v_add_f32_e32 v83, v67, v66
	ds_bpermute_b32 v84, v79, v83
	v_cvt_pk_bf16_f32 v66, v78, v92
	v_cndmask_b32_e64 v82, v80, 1.0, vcc
	v_cvt_pk_bf16_f32 v67, v96, v224
	v_cvt_pk_bf16_f32 v68, v226, v227
	v_cvt_pk_bf16_f32 v69, v228, v230
	v_cvt_pk_bf16_f32 v70, v74, v75
	v_cvt_pk_bf16_f32 v71, v76, v77
	v_cvt_pk_bf16_f32 v72, v94, v231
	v_cvt_pk_bf16_f32 v73, v233, v235
	v_cvt_pk_bf16_f32 v74, v81, v93
	v_cvt_pk_bf16_f32 v75, v97, v225
	v_cvt_pk_bf16_f32 v76, v86, v87
	v_cvt_pk_bf16_f32 v77, v229, v85
	v_cvt_pk_bf16_f32 v78, v89, v90
	v_cvt_pk_bf16_f32 v79, v88, v91
	v_cvt_pk_bf16_f32 v80, v95, v232
	v_cvt_pk_bf16_f32 v81, v234, v236
	s_nop 0
	v_permlane32_swap_b32_e32 v66, v68
	v_permlane32_swap_b32_e32 v67, v69
	v_permlane32_swap_b32_e32 v70, v72
	v_permlane32_swap_b32_e32 v71, v73
	v_permlane32_swap_b32_e32 v74, v76
	v_permlane32_swap_b32_e32 v75, v77
	v_permlane32_swap_b32_e32 v78, v80
	v_permlane32_swap_b32_e32 v79, v81
	v_cmp_gt_f32_e32 vcc, 1.0, v82
	s_cbranch_vccz .LBB0_473
	v_pk_mul_f32 v[64:65], v[64:65], v[82:83] op_sel_hi:[1,0]
	v_pk_mul_f32 v[62:63], v[62:63], v[82:83] op_sel_hi:[1,0]
	v_pk_mul_f32 v[60:61], v[60:61], v[82:83] op_sel_hi:[1,0]
	v_pk_mul_f32 v[58:59], v[58:59], v[82:83] op_sel_hi:[1,0]
	v_pk_mul_f32 v[56:57], v[56:57], v[82:83] op_sel_hi:[1,0]
	v_pk_mul_f32 v[54:55], v[54:55], v[82:83] op_sel_hi:[1,0]
	v_pk_mul_f32 v[52:53], v[52:53], v[82:83] op_sel_hi:[1,0]
	v_pk_mul_f32 v[50:51], v[50:51], v[82:83] op_sel_hi:[1,0]
	v_pk_mul_f32 v[48:49], v[48:49], v[82:83] op_sel_hi:[1,0]
	v_pk_mul_f32 v[46:47], v[46:47], v[82:83] op_sel_hi:[1,0]
	v_pk_mul_f32 v[44:45], v[44:45], v[82:83] op_sel_hi:[1,0]
	v_pk_mul_f32 v[42:43], v[42:43], v[82:83] op_sel_hi:[1,0]
	v_pk_mul_f32 v[40:41], v[40:41], v[82:83] op_sel_hi:[1,0]
	v_pk_mul_f32 v[38:39], v[38:39], v[82:83] op_sel_hi:[1,0]
	v_pk_mul_f32 v[36:37], v[36:37], v[82:83] op_sel_hi:[1,0]
	v_pk_mul_f32 v[34:35], v[34:35], v[82:83] op_sel_hi:[1,0]
	v_pk_mul_f32 v[32:33], v[32:33], v[82:83] op_sel_hi:[1,0]
	v_pk_mul_f32 v[30:31], v[30:31], v[82:83] op_sel_hi:[1,0]
	v_pk_mul_f32 v[28:29], v[28:29], v[82:83] op_sel_hi:[1,0]
	v_pk_mul_f32 v[26:27], v[26:27], v[82:83] op_sel_hi:[1,0]
	v_pk_mul_f32 v[24:25], v[24:25], v[82:83] op_sel_hi:[1,0]
	v_pk_mul_f32 v[22:23], v[22:23], v[82:83] op_sel_hi:[1,0]
	v_pk_mul_f32 v[20:21], v[20:21], v[82:83] op_sel_hi:[1,0]
	v_pk_mul_f32 v[18:19], v[18:19], v[82:83] op_sel_hi:[1,0]
	v_pk_mul_f32 v[16:17], v[16:17], v[82:83] op_sel_hi:[1,0]
	v_pk_mul_f32 v[14:15], v[14:15], v[82:83] op_sel_hi:[1,0]
	v_pk_mul_f32 v[12:13], v[12:13], v[82:83] op_sel_hi:[1,0]
	v_pk_mul_f32 v[10:11], v[10:11], v[82:83] op_sel_hi:[1,0]
	v_pk_mul_f32 v[8:9], v[8:9], v[82:83] op_sel_hi:[1,0]
	v_pk_mul_f32 v[6:7], v[6:7], v[82:83] op_sel_hi:[1,0]
	v_pk_mul_f32 v[4:5], v[4:5], v[82:83] op_sel_hi:[1,0]
	v_pk_mul_f32 v[2:3], v[2:3], v[82:83] op_sel_hi:[1,0]
	s_branch .LBB0_473

; #define PG8_STAGE(bufoff, gbase, voff) do { _Pragma("unroll") for (int _i = 0; _i < 2; ++_i) \
;         __builtin_amdgcn_global_load_lds((const unsigned*)((const char*)(gbase) + (voff)[_i]), (PG8_LAS unsigned*)(lds + (bufoff) + ldsw + _i * 8192), 16, 0, 0); } while (0)
; #define PG8_WAIT_V(n) asm volatile("s_waitcnt vmcnt(" #n ")" ::: "memory")
; #define PG8_BAR __builtin_amdgcn_s_barrier()
; template <class Epi, class Sched, bool ALIGN_EPI = false, bool SP2 = false>
; __device__ __forceinline__ void gemm_phase(PG8_LAS unsigned char* lds, const Gemm g, const Sched& S, const Epi& E) {
;     ...
;     const char* cA = (const char*)g.A + (size_t)cur.pm * tstep; const char* cB = (const char*)g.Bt + (size_t)cur.pn * tstep;
;     S.a_ready(cur);
;     if constexpr (SP2) {
;         PG8_STAGE(PG8_SB(0, 0), cB, voffB); PG8_STAGE(PG8_SB(0, 1), cB + hstep, voffB); PG8_STAGE(PG8_SA(0, 0), cA, voffA); PG8_STAGE(PG8_SA(0, 1), cA + hstep, voffA);
;         if (wr == 1) PG8_BAR;
;         PG8_WAIT_V(2); PG8_BAR;
;         PG8_STAGE(PG8_SB(1, 0), cB + kstep, voffB); PG8_STAGE(PG8_SA(1, 0), cA + kstep, voffA); PG8_STAGE(PG8_SB(1, 1), cB + hstep + kstep, voffB);
;         PG8_WAIT_V(6); PG8_BAR;
;     } else {
;         PG8_STAGE(PG8_SB(0, 0), cB, voffB); PG8_STAGE(PG8_SA(0, 0), cA, voffA); PG8_STAGE(PG8_SB(0, 1), cB + hstep, voffB); PG8_STAGE(PG8_SA(0, 1), cA + hstep, voffA);
;         if (wr == 1) PG8_BAR;
;         PG8_WAIT_V(4); PG8_BAR;
;         PG8_STAGE(PG8_SB(1, 0), cB + kstep, voffB); PG8_STAGE(PG8_SA(1, 0), cA + kstep, voffA); PG8_STAGE(PG8_SB(1, 1), cB + hstep + kstep, voffB);
;         PG8_WAIT_V(6); PG8_BAR;
;     }
;     for (;;) {
;         const bool has_next = S.next(ui + 1, nxt);
;         const char* nA = has_next ? (const char*)g.A + (size_t)nxt.pm * tstep : cA; const char* nB = has_next ? (const char*)g.Bt + (size_t)nxt.pn * tstep : cB;
.LBB0_609:
	s_add_u32 s8, s50, 0x3e0f0000
	s_mov_b64 s[10:11], 0x80
	s_addc_u32 s9, s51, 0
	s_and_b32 s42, s1, 3
	s_add_i32 m0, s37, 0x18000
	v_lshl_add_u64 v[8:9], v[8:9], 0, s[10:11]
	s_waitcnt lgkmcnt(0)
	s_ashr_i32 s41, s94, 31
	s_lshl_b32 s14, s3, 13
	s_lshl_b32 s15, s42, 12
	s_waitcnt vmcnt(2)
	s_barrier
	global_load_lds_dwordx4 v[8:9], off
	v_lshl_add_u64 v[6:7], v[6:7], 0, s[10:11]
	s_add_i32 m0, s37, 0x1a000
	s_add_i32 s43, s37, 0x8000
	s_add_i32 s44, s37, 0xa000
	global_load_lds_dwordx4 v[6:7], off
	v_lshl_add_u64 v[2:3], v[2:3], 0, s[10:11]
	s_mov_b32 m0, s43
	s_add_u32 s12, s24, 0x80080
	global_load_lds_dwordx4 v[2:3], off
	v_lshl_add_u64 v[2:3], v[4:5], 0, s[10:11]
	s_mov_b32 m0, s44
	s_addc_u32 s13, s25, 0
	global_load_lds_dwordx4 v[2:3], off
	s_add_i32 m0, s37, 0x1c000
	v_lshl_add_u64 v[2:3], s[12:13], 0, v[132:133]
	global_load_lds_dwordx4 v[2:3], off
	v_lshl_add_u64 v[2:3], s[12:13], 0, v[136:137]
	s_add_i32 m0, s37, 0x1e000
	v_lshlrev_b32_e32 v6, 6, v147
	global_load_lds_dwordx4 v[2:3], off
	v_bfe_u32 v3, v147, 4, 2
	v_lshlrev_b32_e32 v5, 4, v3
	s_movk_i32 s1, 0x3c0
	v_lshlrev_b32_e32 v4, 3, v3
	v_and_or_b32 v6, v6, s1, v5
	s_sext_i32_i8 s74, s0
	v_cmp_eq_u32_e64 s[0:1], 0, v3
	v_lshlrev_b32_e32 v3, 9, v147
	v_lshl_or_b32 v154, s42, 5, v4
	v_and_b32_e32 v3, 0x70000, v3
	v_lshlrev_b32_e32 v4, 12, v12
	v_and_b32_e32 v2, 15, v147
	v_lshlrev_b32_e32 v7, 2, v147
	v_or3_b32 v3, v10, v3, v4
	v_and_b32_e32 v7, 32, v7
	v_lshl_or_b32 v152, s3, 6, v2
	v_lshl_or_b32 v2, v2, 6, v5
	v_add_u32_e32 v138, v3, v11
	v_lshlrev_b32_e32 v3, 5, v13
	v_bitop3_b32 v2, v2, s14, v7 bitop3:0xde
	s_waitcnt vmcnt(0)
	s_cmpk_lt_u32 s2, 0x100
	v_and_b32_e32 v3, 0xf0000, v3
	v_bitop3_b32 v153, s15, v6, v7 bitop3:0xf6
	s_cselect_b64 s[12:13], -1, 0
	v_or3_b32 v3, v10, v3, v4
	s_add_i32 s45, 0, 0x10000
	s_add_i32 s70, 0, 0x14000
	v_add_u32_e32 v157, 0, v2
	v_mbcnt_lo_u32_b32 v2, -1, 0
	v_mov_b32_e32 v139, v133
	v_add_u32_e32 v140, v3, v11
	v_mov_b32_e32 v141, v133
	v_mov_b64_e32 v[142:143], 0x500
	v_mov_b64_e32 v[144:145], 0x4ff
	v_add_u32_e32 v155, s45, v153
	v_add_u32_e32 v156, s70, v153
	v_mbcnt_hi_u32_b32 v158, -1, v2
	s_mov_b32 s71, 0
	s_barrier
	s_branch .LBB0_612

; template <class Epi, class Sched, bool ALIGN_EPI = false, bool SP2 = false>
; __device__ __forceinline__ void gemm_phase(PG8_LAS unsigned char* lds, const Gemm g, const Sched& S, const Epi& E) {
;     ...
;         const bool has_next = S.next(ui + 1, nxt);
;         const char* nA = has_next ? (const char*)g.A + (size_t)nxt.pm * tstep : cA; const char* nB = has_next ? (const char*)g.Bt + (size_t)nxt.pn * tstep : cB;
;         for (int t = 0; t < nt; t += 2) {
;             const bool last = (t == nt - 2);
;             const char* a1 = cA + (size_t)(t + 1) * kstep;
;             const char* a2 = last ? nA : cA + (size_t)(t + 2) * kstep; const char* b2 = last ? nB : cB + (size_t)(t + 2) * kstep;
;             const char* a3 = a2 + kstep; const char* b3 = b2 + kstep;
;     ...
; #pragma unroll
;         for (int a = 0; a < 2; ++a)
; #pragma unroll
;             for (int b = 0; b < 2; ++b)
; #pragma unroll
;                 for (int m = 0; m < 4; ++m)
; #pragma unroll
;                     for (int n = 0; n < 2; ++n) acc[a][b][m][n] = (f32x4){0.f, 0.f, 0.f, 0.f};
;         cur = nxt; cA = nA; cB = nB; ++ui;
.LBB0_614:
	s_ashr_i32 s17, s16, 31
	s_lshl_b64 s[18:19], s[16:17], 20
	s_add_u32 s18, s30, s18
	s_addc_u32 s19, s31, s19
	s_and_b64 s[20:21], s[2:3], exec
	s_cselect_b32 s17, s19, s23
	s_cselect_b32 s75, s18, s22
	s_ashr_i32 s15, s14, 31
	s_lshl_b64 s[20:21], s[14:15], 20
	s_add_u32 s20, s28, s20
	s_addc_u32 s21, s29, s21
	s_and_b64 s[26:27], s[2:3], exec
	s_cselect_b32 s15, s21, s25
	s_cselect_b32 s76, s20, s24
	s_add_u32 s22, s22, 0x80080
	s_addc_u32 s23, s23, 0
	s_add_u32 s77, s24, 0x100
	v_mov_b32_e32 v2, 0
	s_addc_u32 s78, s25, 0
	s_mov_b32 s79, -2
	v_mov_b32_e32 v3, v2
	v_mov_b32_e32 v4, v2
	v_mov_b32_e32 v5, v2
	v_mov_b32_e32 v6, v2
	s_waitcnt lgkmcnt(0)
	v_mov_b32_e32 v7, v2
	v_mov_b32_e32 v8, v2
	v_mov_b32_e32 v9, v2
	v_mov_b32_e32 v18, v2
	v_mov_b32_e32 v19, v2
	v_mov_b32_e32 v20, v2
	v_mov_b32_e32 v21, v2
	v_mov_b32_e32 v22, v2
	v_mov_b32_e32 v23, v2
	v_mov_b32_e32 v24, v2
	v_mov_b32_e32 v25, v2
	v_mov_b32_e32 v34, v2
	v_mov_b32_e32 v35, v2
	v_mov_b32_e32 v36, v2
	v_mov_b32_e32 v37, v2
	v_mov_b32_e32 v38, v2
	v_mov_b32_e32 v39, v2
	v_mov_b32_e32 v40, v2
	v_mov_b32_e32 v41, v2
	v_mov_b32_e32 v50, v2
	v_mov_b32_e32 v51, v2
	v_mov_b32_e32 v52, v2
	v_mov_b32_e32 v53, v2
	v_mov_b32_e32 v54, v2
	v_mov_b32_e32 v55, v2
	v_mov_b32_e32 v56, v2
	v_mov_b32_e32 v57, v2
	v_mov_b32_e32 v10, v2
	v_mov_b32_e32 v11, v2
	v_mov_b32_e32 v12, v2
	v_mov_b32_e32 v13, v2
	v_mov_b32_e32 v14, v2
	v_mov_b32_e32 v15, v2
	v_mov_b32_e32 v16, v2
	v_mov_b32_e32 v17, v2
	v_mov_b32_e32 v26, v2
	v_mov_b32_e32 v27, v2
	v_mov_b32_e32 v28, v2
	v_mov_b32_e32 v29, v2
	v_mov_b32_e32 v30, v2
	v_mov_b32_e32 v31, v2
	v_mov_b32_e32 v32, v2
	v_mov_b32_e32 v33, v2
	v_mov_b32_e32 v42, v2
	v_mov_b32_e32 v43, v2
	v_mov_b32_e32 v44, v2
	v_mov_b32_e32 v45, v2
	v_mov_b32_e32 v46, v2
	v_mov_b32_e32 v47, v2
	v_mov_b32_e32 v48, v2
	v_mov_b32_e32 v49, v2
	v_mov_b32_e32 v58, v2
	v_mov_b32_e32 v59, v2
	v_mov_b32_e32 v60, v2
	v_mov_b32_e32 v61, v2
	v_mov_b32_e32 v62, v2
	v_mov_b32_e32 v63, v2
	v_mov_b32_e32 v64, v2
	v_mov_b32_e32 v65, v2
	v_mov_b32_e32 v66, v2
	v_mov_b32_e32 v67, v2
	v_mov_b32_e32 v68, v2
	v_mov_b32_e32 v69, v2
	v_mov_b32_e32 v70, v2
	v_mov_b32_e32 v71, v2
	v_mov_b32_e32 v72, v2
	v_mov_b32_e32 v73, v2
	v_mov_b32_e32 v82, v2
	v_mov_b32_e32 v83, v2
	v_mov_b32_e32 v84, v2
	v_mov_b32_e32 v85, v2
	v_mov_b32_e32 v86, v2
	v_mov_b32_e32 v87, v2
	v_mov_b32_e32 v88, v2
	v_mov_b32_e32 v89, v2
	v_mov_b32_e32 v98, v2
	v_mov_b32_e32 v99, v2
	v_mov_b32_e32 v100, v2
	v_mov_b32_e32 v101, v2
	v_mov_b32_e32 v102, v2
	v_mov_b32_e32 v103, v2
	v_mov_b32_e32 v104, v2
	v_mov_b32_e32 v105, v2
	v_mov_b32_e32 v114, v2
	v_mov_b32_e32 v115, v2
	v_mov_b32_e32 v116, v2
	v_mov_b32_e32 v117, v2
	v_mov_b32_e32 v118, v2
	v_mov_b32_e32 v119, v2
	v_mov_b32_e32 v120, v2
	v_mov_b32_e32 v121, v2
	v_mov_b32_e32 v74, v2
	v_mov_b32_e32 v75, v2
	v_mov_b32_e32 v76, v2
	v_mov_b32_e32 v77, v2
	v_mov_b32_e32 v78, v2
	v_mov_b32_e32 v79, v2
	v_mov_b32_e32 v80, v2
	v_mov_b32_e32 v81, v2
	v_mov_b32_e32 v90, v2
	v_mov_b32_e32 v91, v2
	v_mov_b32_e32 v92, v2
	v_mov_b32_e32 v93, v2
	v_mov_b32_e32 v94, v2
	v_mov_b32_e32 v95, v2
	v_mov_b32_e32 v96, v2
	v_mov_b32_e32 v97, v2
	v_mov_b32_e32 v106, v2
	v_mov_b32_e32 v107, v2
	v_mov_b32_e32 v108, v2
	v_mov_b32_e32 v109, v2
	v_mov_b32_e32 v110, v2
	v_mov_b32_e32 v111, v2
	v_mov_b32_e32 v112, v2
	v_mov_b32_e32 v113, v2
	v_mov_b32_e32 v122, v2
	v_mov_b32_e32 v123, v2
	v_mov_b32_e32 v124, v2
	v_mov_b32_e32 v125, v2
	v_mov_b32_e32 v126, v2
	v_mov_b32_e32 v127, v2
	v_mov_b32_e32 v128, v2
	v_mov_b32_e32 v129, v2
	v_and_b32_e32 v241, 0x3ff, v0
	v_and_b32_e32 v240, 63, v241
	v_readfirstlane_b32 s90, v241
	v_lshrrev_b32_e32 v205, 2, v240
	v_and_b32_e32 v201, 3, v240
	v_lshlrev_b32_e32 v201, 4, v201
	v_lshrrev_b32_e32 v162, 5, v240
	v_lshlrev_b32_e32 v162, 5, v162
	v_xor_b32_e32 v201, v201, v162
	v_lshl_or_b32 v160, v205, 12, v201
	v_add_u32_e32 v162, 64, v160
	v_lshrrev_b32_e32 v240, 2, v205
	v_and_b32_e32 v241, 3, v205
	v_lshl_or_b32 v240, v240, 3, v241
	v_lshl_or_b32 v201, v240, 12, v201
	v_add_u32_e32 v205, 64, v201
	v_add_u32_e32 v240, 0x4000, v201
	v_add_u32_e32 v241, 0x4040, v201
	s_lshr_b32 s90, s90, 6
	s_lshr_b32 s91, s90, 2
	s_and_b32 s90, s90, 3
	s_lshl_b32 s32, s91, 2
	s_add_i32 s32, s32, s90
	s_lshl_b32 s32, s32, 11
	s_xor_b32 s84, s91, 1
	s_mul_i32 s85, s84, 0xc000
	s_add_i32 s85, s85, 0x10000
	s_lshl_b32 s86, s84, 14
	s_sub_i32 s86, 0x18000, s86
	s_lshl_b32 s89, s90, 12
	s_add_i32 s85, s85, s89
	s_add_i32 s86, s86, s89
	s_lshl_b32 s84, s84, 19
	s_lshl_b32 s89, s90, 17
	s_add_i32 s84, s84, s89
	s_mul_i32 s87, s91, 0x45
	s_add_i32 s87, s87, 30
	s_mul_i32 s88, s91, 0x47
	s_sub_i32 s88, 0x63, s88
	s_lshl_b32 s89, s32, 5
	s_add_u32 s68, s22, s89
	s_addc_u32 s69, s23, 0
	s_sub_u32 s66, s68, 0x80000
	s_subb_u32 s67, s69, 0
	s_sub_i32 s89, s91, 1
	s_lshl_b32 s89, s89, 7
	s_add_i32 s89, s89, s84
	s_add_u32 s82, s77, s89
	s_addc_u32 s83, s78, 0
	s_mov_b32 s89, 0
; #define PG8_STAGE(bufoff, gbase, voff) do { _Pragma("unroll") for (int _i = 0; _i < 2; ++_i) \
;         __builtin_amdgcn_global_load_lds((const unsigned*)((const char*)(gbase) + (voff)[_i]), (PG8_LAS unsigned*)(lds + (bufoff) + ldsw + _i * 8192), 16, 0, 0); } while (0)
; #define PG8_LDA(dst, b, h) do { _Pragma("unroll") for (int m = 0; m < 4; ++m) _Pragma("unroll") for (int k = 0; k < 2; ++k) dst[m][k] = *(const PG8_LAS bf16x8*)(lds + PG8_SA(b, h) + aoff + m * 2048 + k * 1024); } while (0)
; #define PG8_LDB(dst, b, h) do { _Pragma("unroll") for (int n = 0; n < 2; ++n) _Pragma("unroll") for (int k = 0; k < 2; ++k) dst[n][k] = *(const PG8_LAS bf16x8*)(lds + PG8_SB(b, h) + boff + n * 2048 + k * 1024); } while (0)
; #define PG8_MMA(ai, bj, At, Bt) do { __builtin_amdgcn_s_setprio(1); _Pragma("unroll") for (int m = 0; m < 4; ++m) _Pragma("unroll") for (int n = 0; n < 2; ++n) _Pragma("unroll") for (int k = 0; k < 2; ++k) \
;         acc[ai][bj][m][n] = __builtin_amdgcn_mfma_f32_16x16x32_bf16(Bt[n][k], At[m][k], acc[ai][bj][m][n], 0, 0, 0); __builtin_amdgcn_s_setprio(0); } while (0)
; #define PG8_BAR __builtin_amdgcn_s_barrier()
; template <class Epi, class Sched, bool ALIGN_EPI = false, bool SP2 = false>
; __device__ __forceinline__ void gemm_phase(PG8_LAS unsigned char* lds, const Gemm g, const Sched& S, const Epi& E) {
;     ...
;             if constexpr (SP2) {
;             PG8_LDB(B0, 0, 0); PG8_LDB(B1, 0, 1); PG8_SCHED; PG8_LDA(At, 0, 0); PG8_STAGE(PG8_SA(1, 1), a1 + hstep, voffA);
;             PG8_WAIT_V(8); PG8_WAIT_L(0); PG8_BAR; PG8_MMA(0, 0, At, B0); PG8_MMA(0, 1, At, B1); PG8_BAR; PG8_SCHED;
;             PG8_LDA(At, 0, 1); PG8_STAGE(PG8_SB(0, 0), b2, voffB); PG8_STAGE(PG8_SB(0, 1), b2 + hstep, voffB); PG8_STAGE(PG8_SA(0, 0), a2, voffA);
;             PG8_WAIT_V(8); PG8_WAIT_L(0); PG8_BAR; PG8_MMA(1, 0, At, B0); PG8_MMA(1, 1, At, B1); PG8_BAR; PG8_SCHED;
;             PG8_LDB(B0, 1, 0); PG8_LDB(B1, 1, 1); PG8_SCHED; PG8_LDA(At, 1, 0); PG8_STAGE(PG8_SA(0, 1), a2 + hstep, voffA);
;             PG8_WAIT_V(8); PG8_WAIT_L(0); PG8_BAR; PG8_MMA(0, 0, At, B0); PG8_MMA(0, 1, At, B1); PG8_BAR; PG8_SCHED;
;             PG8_LDA(At, 1, 1); PG8_STAGE(PG8_SB(1, 0), b3, voffB); PG8_STAGE(PG8_SB(1, 1), b3 + hstep, voffB); PG8_STAGE(PG8_SA(1, 0), a3, voffA);
;             PG8_WAIT_V(8); PG8_WAIT_L(0); PG8_BAR; PG8_MMA(1, 0, At, B0); PG8_MMA(1, 1, At, B1); PG8_BAR; PG8_SCHED;
.Lsp4_loop_1:
	s_add_i32 m0, s32, 0x8000
	s_nop 0
	global_load_lds_dwordx4 v160, s[66:67]
	s_add_i32 m0, s32, 0x8400
	s_nop 0
	global_load_lds_dwordx4 v162, s[66:67]
	s_add_i32 m0, s32, 0xc000
	s_nop 0
	global_load_lds_dwordx4 v160, s[68:69]
	s_add_i32 m0, s32, 0xc400
	s_nop 0
	global_load_lds_dwordx4 v162, s[68:69]
	ds_read_b128 v[148:151], v155
	ds_read_b128 v[164:167], v155 offset:1024
	ds_read_b128 v[168:171], v155 offset:2048
	ds_read_b128 v[172:175], v155 offset:3072
	ds_read_b128 v[176:179], v155 offset:16384
	ds_read_b128 v[180:183], v155 offset:17408
	ds_read_b128 v[184:187], v155 offset:18432
	ds_read_b128 v[188:191], v155 offset:19456
	ds_read_b128 v[192:195], v157
	ds_read_b128 v[196:199], v157 offset:1024
	ds_read_b128 v[206:209], v157 offset:2048
	ds_read_b128 v[210:213], v157 offset:3072
	ds_read_b128 v[214:217], v157 offset:4096
	ds_read_b128 v[218:221], v157 offset:5120
	ds_read_b128 v[222:225], v157 offset:6144
	ds_read_b128 v[226:229], v157 offset:7168
	s_waitcnt lgkmcnt(8)
	s_add_i32 m0, s85, 0x0
	s_nop 0
	global_load_lds_dwordx4 v201, s[82:83]
	s_add_i32 m0, s85, 0x400
	s_nop 0
	global_load_lds_dwordx4 v205, s[82:83]
	s_add_i32 m0, s85, 0x800
	s_nop 0
	global_load_lds_dwordx4 v240, s[82:83]
	s_add_i32 m0, s85, 0xc00
	s_nop 0
	global_load_lds_dwordx4 v241, s[82:83]
	s_add_u32 s66, s66, 0x80
	s_addc_u32 s67, s67, 0
	s_add_u32 s68, s68, 0x80
	s_addc_u32 s69, s69, 0
	s_add_u32 s82, s82, 0x80
	s_addc_u32 s83, s83, 0
	s_cmp_lg_u32 s89, 30
	s_cbranch_scc1 .Lsp4_noA_1
	s_lshl_b32 s90, s32, 5
	s_add_u32 s66, s75, s90
	s_addc_u32 s67, s17, 0
	s_add_u32 s68, s66, 0x80000
	s_addc_u32 s69, s67, 0
.Lsp4_noA_1:
	s_cmp_lg_u32 s89, s87
	s_cbranch_scc1 .Lsp4_noB0_1
	s_add_u32 s82, s76, s84
	s_addc_u32 s83, s15, 0
.Lsp4_noB0_1:
	s_waitcnt lgkmcnt(0)
	s_barrier
	s_setprio 1
	v_mfma_f32_16x16x32_bf16 v[126:129], v[148:151], v[192:195], v[126:129]
	v_mfma_f32_16x16x32_bf16 v[122:125], v[168:171], v[192:195], v[122:125]
	v_mfma_f32_16x16x32_bf16 v[118:121], v[176:179], v[192:195], v[118:121]
	v_mfma_f32_16x16x32_bf16 v[114:117], v[184:187], v[192:195], v[114:117]
	ds_read_b128 v[192:195], v157 offset:16384
	v_mfma_f32_16x16x32_bf16 v[110:113], v[148:151], v[206:209], v[110:113]
	v_mfma_f32_16x16x32_bf16 v[106:109], v[168:171], v[206:209], v[106:109]
	v_mfma_f32_16x16x32_bf16 v[102:105], v[176:179], v[206:209], v[102:105]
	v_mfma_f32_16x16x32_bf16 v[98:101], v[184:187], v[206:209], v[98:101]
	ds_read_b128 v[206:209], v157 offset:18432
	v_mfma_f32_16x16x32_bf16 v[94:97], v[148:151], v[214:217], v[94:97]
	v_mfma_f32_16x16x32_bf16 v[90:93], v[168:171], v[214:217], v[90:93]
	v_mfma_f32_16x16x32_bf16 v[86:89], v[176:179], v[214:217], v[86:89]
	v_mfma_f32_16x16x32_bf16 v[82:85], v[184:187], v[214:217], v[82:85]
	ds_read_b128 v[214:217], v157 offset:20480
	v_mfma_f32_16x16x32_bf16 v[78:81], v[148:151], v[222:225], v[78:81]
	v_mfma_f32_16x16x32_bf16 v[74:77], v[168:171], v[222:225], v[74:77]
	v_mfma_f32_16x16x32_bf16 v[70:73], v[176:179], v[222:225], v[70:73]
	v_mfma_f32_16x16x32_bf16 v[66:69], v[184:187], v[222:225], v[66:69]
	ds_read_b128 v[222:225], v157 offset:22528
	v_mfma_f32_16x16x32_bf16 v[126:129], v[164:167], v[196:199], v[126:129]
	v_mfma_f32_16x16x32_bf16 v[122:125], v[172:175], v[196:199], v[122:125]
	v_mfma_f32_16x16x32_bf16 v[118:121], v[180:183], v[196:199], v[118:121]
	v_mfma_f32_16x16x32_bf16 v[114:117], v[188:191], v[196:199], v[114:117]
	ds_read_b128 v[196:199], v157 offset:17408
	v_mfma_f32_16x16x32_bf16 v[110:113], v[164:167], v[210:213], v[110:113]
	v_mfma_f32_16x16x32_bf16 v[106:109], v[172:175], v[210:213], v[106:109]
	v_mfma_f32_16x16x32_bf16 v[102:105], v[180:183], v[210:213], v[102:105]
	v_mfma_f32_16x16x32_bf16 v[98:101], v[188:191], v[210:213], v[98:101]
	ds_read_b128 v[210:213], v157 offset:19456
	v_mfma_f32_16x16x32_bf16 v[94:97], v[164:167], v[218:221], v[94:97]
	v_mfma_f32_16x16x32_bf16 v[90:93], v[172:175], v[218:221], v[90:93]
	v_mfma_f32_16x16x32_bf16 v[86:89], v[180:183], v[218:221], v[86:89]
	v_mfma_f32_16x16x32_bf16 v[82:85], v[188:191], v[218:221], v[82:85]
	ds_read_b128 v[218:221], v157 offset:21504
	v_mfma_f32_16x16x32_bf16 v[78:81], v[164:167], v[226:229], v[78:81]
	v_mfma_f32_16x16x32_bf16 v[74:77], v[172:175], v[226:229], v[74:77]
	v_mfma_f32_16x16x32_bf16 v[70:73], v[180:183], v[226:229], v[70:73]
	v_mfma_f32_16x16x32_bf16 v[66:69], v[188:191], v[226:229], v[66:69]
	ds_read_b128 v[226:229], v157 offset:23552
	s_waitcnt lgkmcnt(4)
	v_mfma_f32_16x16x32_bf16 v[62:65], v[148:151], v[192:195], v[62:65]
	v_mfma_f32_16x16x32_bf16 v[58:61], v[168:171], v[192:195], v[58:61]
	v_mfma_f32_16x16x32_bf16 v[54:57], v[176:179], v[192:195], v[54:57]
	v_mfma_f32_16x16x32_bf16 v[50:53], v[184:187], v[192:195], v[50:53]
	v_mfma_f32_16x16x32_bf16 v[46:49], v[148:151], v[206:209], v[46:49]
	v_mfma_f32_16x16x32_bf16 v[42:45], v[168:171], v[206:209], v[42:45]
	v_mfma_f32_16x16x32_bf16 v[38:41], v[176:179], v[206:209], v[38:41]
	v_mfma_f32_16x16x32_bf16 v[34:37], v[184:187], v[206:209], v[34:37]
	v_mfma_f32_16x16x32_bf16 v[30:33], v[148:151], v[214:217], v[30:33]
	v_mfma_f32_16x16x32_bf16 v[26:29], v[168:171], v[214:217], v[26:29]
	v_mfma_f32_16x16x32_bf16 v[22:25], v[176:179], v[214:217], v[22:25]
	v_mfma_f32_16x16x32_bf16 v[18:21], v[184:187], v[214:217], v[18:21]
	v_mfma_f32_16x16x32_bf16 v[14:17], v[148:151], v[222:225], v[14:17]
	v_mfma_f32_16x16x32_bf16 v[10:13], v[168:171], v[222:225], v[10:13]
	v_mfma_f32_16x16x32_bf16 v[6:9], v[176:179], v[222:225], v[6:9]
	v_mfma_f32_16x16x32_bf16 v[2:5], v[184:187], v[222:225], v[2:5]
	s_waitcnt lgkmcnt(0)
	v_mfma_f32_16x16x32_bf16 v[62:65], v[164:167], v[196:199], v[62:65]
	v_mfma_f32_16x16x32_bf16 v[58:61], v[172:175], v[196:199], v[58:61]
	v_mfma_f32_16x16x32_bf16 v[54:57], v[180:183], v[196:199], v[54:57]
	v_mfma_f32_16x16x32_bf16 v[50:53], v[188:191], v[196:199], v[50:53]
	v_mfma_f32_16x16x32_bf16 v[46:49], v[164:167], v[210:213], v[46:49]
	v_mfma_f32_16x16x32_bf16 v[42:45], v[172:175], v[210:213], v[42:45]
	v_mfma_f32_16x16x32_bf16 v[38:41], v[180:183], v[210:213], v[38:41]
	v_mfma_f32_16x16x32_bf16 v[34:37], v[188:191], v[210:213], v[34:37]
	v_mfma_f32_16x16x32_bf16 v[30:33], v[164:167], v[218:221], v[30:33]
	v_mfma_f32_16x16x32_bf16 v[26:29], v[172:175], v[218:221], v[26:29]
	v_mfma_f32_16x16x32_bf16 v[22:25], v[180:183], v[218:221], v[22:25]
	v_mfma_f32_16x16x32_bf16 v[18:21], v[188:191], v[218:221], v[18:21]
	v_mfma_f32_16x16x32_bf16 v[14:17], v[164:167], v[226:229], v[14:17]
	v_mfma_f32_16x16x32_bf16 v[10:13], v[172:175], v[226:229], v[10:13]
	v_mfma_f32_16x16x32_bf16 v[6:9], v[180:183], v[226:229], v[6:9]
	v_mfma_f32_16x16x32_bf16 v[2:5], v[188:191], v[226:229], v[2:5]
	s_setprio 0
	s_waitcnt vmcnt(0)
	s_barrier
; #define PG8_STAGE(bufoff, gbase, voff) do { _Pragma("unroll") for (int _i = 0; _i < 2; ++_i) \
;         __builtin_amdgcn_global_load_lds((const unsigned*)((const char*)(gbase) + (voff)[_i]), (PG8_LAS unsigned*)(lds + (bufoff) + ldsw + _i * 8192), 16, 0, 0); } while (0)
; #define PG8_LDA(dst, b, h) do { _Pragma("unroll") for (int m = 0; m < 4; ++m) _Pragma("unroll") for (int k = 0; k < 2; ++k) dst[m][k] = *(const PG8_LAS bf16x8*)(lds + PG8_SA(b, h) + aoff + m * 2048 + k * 1024); } while (0)
; #define PG8_LDB(dst, b, h) do { _Pragma("unroll") for (int n = 0; n < 2; ++n) _Pragma("unroll") for (int k = 0; k < 2; ++k) dst[n][k] = *(const PG8_LAS bf16x8*)(lds + PG8_SB(b, h) + boff + n * 2048 + k * 1024); } while (0)
; template <class Epi, class Sched, bool ALIGN_EPI = false, bool SP2 = false>
; __device__ __forceinline__ void gemm_phase(PG8_LAS unsigned char* lds, const Gemm g, const Sched& S, const Epi& E) {
;     ...
;         for (int t = 0; t < nt; t += 2) {
;             const bool last = (t == nt - 2);
;             const char* a1 = cA + (size_t)(t + 1) * kstep;
;             const char* a2 = last ? nA : cA + (size_t)(t + 2) * kstep; const char* b2 = last ? nB : cB + (size_t)(t + 2) * kstep;
;             const char* a3 = a2 + kstep; const char* b3 = b2 + kstep;
;             if (last && has_next) S.a_ready(nxt);
;             if constexpr (SP2) {
;             PG8_LDB(B0, 0, 0); PG8_LDB(B1, 0, 1); PG8_SCHED; PG8_LDA(At, 0, 0); PG8_STAGE(PG8_SA(1, 1), a1 + hstep, voffA);
;             PG8_WAIT_V(8); PG8_WAIT_L(0); PG8_BAR; PG8_MMA(0, 0, At, B0); PG8_MMA(0, 1, At, B1); PG8_BAR; PG8_SCHED;
;             PG8_LDA(At, 0, 1); PG8_STAGE(PG8_SB(0, 0), b2, voffB); PG8_STAGE(PG8_SB(0, 1), b2 + hstep, voffB); PG8_STAGE(PG8_SA(0, 0), a2, voffA);
;             PG8_WAIT_V(8); PG8_WAIT_L(0); PG8_BAR; PG8_MMA(1, 0, At, B0); PG8_MMA(1, 1, At, B1); PG8_BAR; PG8_SCHED;
;             PG8_LDB(B0, 1, 0); PG8_LDB(B1, 1, 1); PG8_SCHED; PG8_LDA(At, 1, 0); PG8_STAGE(PG8_SA(0, 1), a2 + hstep, voffA);
;             PG8_WAIT_V(8); PG8_WAIT_L(0); PG8_BAR; PG8_MMA(0, 0, At, B0); PG8_MMA(0, 1, At, B1); PG8_BAR; PG8_SCHED;
;             PG8_LDA(At, 1, 1); PG8_STAGE(PG8_SB(1, 0), b3, voffB); PG8_STAGE(PG8_SB(1, 1), b3 + hstep, voffB); PG8_STAGE(PG8_SA(1, 0), a3, voffA);
;             PG8_WAIT_V(8); PG8_WAIT_L(0); PG8_BAR; PG8_MMA(1, 0, At, B0); PG8_MMA(1, 1, At, B1); PG8_BAR; PG8_SCHED;
	s_add_i32 m0, s32, 0x0
	s_nop 0
	global_load_lds_dwordx4 v160, s[66:67]
	s_add_i32 m0, s32, 0x400
	s_nop 0
	global_load_lds_dwordx4 v162, s[66:67]
	s_add_i32 m0, s32, 0x4000
	s_nop 0
	global_load_lds_dwordx4 v160, s[68:69]
	s_add_i32 m0, s32, 0x4400
	s_nop 0
	global_load_lds_dwordx4 v162, s[68:69]
	ds_read_b128 v[148:151], v155 offset:32768
	ds_read_b128 v[164:167], v155 offset:33792
	ds_read_b128 v[168:171], v155 offset:34816
	ds_read_b128 v[172:175], v155 offset:35840
	ds_read_b128 v[176:179], v155 offset:49152
	ds_read_b128 v[180:183], v155 offset:50176
	ds_read_b128 v[184:187], v155 offset:51200
	ds_read_b128 v[188:191], v155 offset:52224
	ds_read_b128 v[192:195], v157 offset:32768
	ds_read_b128 v[196:199], v157 offset:33792
	ds_read_b128 v[206:209], v157 offset:34816
	ds_read_b128 v[210:213], v157 offset:35840
	ds_read_b128 v[214:217], v157 offset:36864
	ds_read_b128 v[218:221], v157 offset:37888
	ds_read_b128 v[222:225], v157 offset:38912
	ds_read_b128 v[226:229], v157 offset:39936
	s_waitcnt lgkmcnt(8)
	s_add_i32 m0, s86, 0x0
	s_nop 0
	global_load_lds_dwordx4 v201, s[82:83]
	s_add_i32 m0, s86, 0x400
	s_nop 0
	global_load_lds_dwordx4 v205, s[82:83]
	s_add_i32 m0, s86, 0x800
	s_nop 0
	global_load_lds_dwordx4 v240, s[82:83]
	s_add_i32 m0, s86, 0xc00
	s_nop 0
	global_load_lds_dwordx4 v241, s[82:83]
	s_add_u32 s66, s66, 0x80
	s_addc_u32 s67, s67, 0
	s_add_u32 s68, s68, 0x80
	s_addc_u32 s69, s69, 0
	s_add_u32 s82, s82, 0x80
	s_addc_u32 s83, s83, 0
	s_cmp_lg_u32 s89, s88
	s_cbranch_scc1 .Lsp4_noB1_1
	s_add_u32 s82, s76, s84
	s_addc_u32 s83, s15, 0
.Lsp4_noB1_1:
	s_waitcnt lgkmcnt(0)
	s_barrier
	s_setprio 1
	v_mfma_f32_16x16x32_bf16 v[126:129], v[148:151], v[192:195], v[126:129]
	v_mfma_f32_16x16x32_bf16 v[122:125], v[168:171], v[192:195], v[122:125]
	v_mfma_f32_16x16x32_bf16 v[118:121], v[176:179], v[192:195], v[118:121]
	v_mfma_f32_16x16x32_bf16 v[114:117], v[184:187], v[192:195], v[114:117]
	ds_read_b128 v[192:195], v157 offset:49152
	v_mfma_f32_16x16x32_bf16 v[110:113], v[148:151], v[206:209], v[110:113]
	v_mfma_f32_16x16x32_bf16 v[106:109], v[168:171], v[206:209], v[106:109]
	v_mfma_f32_16x16x32_bf16 v[102:105], v[176:179], v[206:209], v[102:105]
	v_mfma_f32_16x16x32_bf16 v[98:101], v[184:187], v[206:209], v[98:101]
	ds_read_b128 v[206:209], v157 offset:51200
	v_mfma_f32_16x16x32_bf16 v[94:97], v[148:151], v[214:217], v[94:97]
	v_mfma_f32_16x16x32_bf16 v[90:93], v[168:171], v[214:217], v[90:93]
	v_mfma_f32_16x16x32_bf16 v[86:89], v[176:179], v[214:217], v[86:89]
	v_mfma_f32_16x16x32_bf16 v[82:85], v[184:187], v[214:217], v[82:85]
	ds_read_b128 v[214:217], v157 offset:53248
	v_mfma_f32_16x16x32_bf16 v[78:81], v[148:151], v[222:225], v[78:81]
	v_mfma_f32_16x16x32_bf16 v[74:77], v[168:171], v[222:225], v[74:77]
	v_mfma_f32_16x16x32_bf16 v[70:73], v[176:179], v[222:225], v[70:73]
	v_mfma_f32_16x16x32_bf16 v[66:69], v[184:187], v[222:225], v[66:69]
	ds_read_b128 v[222:225], v157 offset:55296
	v_mfma_f32_16x16x32_bf16 v[126:129], v[164:167], v[196:199], v[126:129]
	v_mfma_f32_16x16x32_bf16 v[122:125], v[172:175], v[196:199], v[122:125]
	v_mfma_f32_16x16x32_bf16 v[118:121], v[180:183], v[196:199], v[118:121]
	v_mfma_f32_16x16x32_bf16 v[114:117], v[188:191], v[196:199], v[114:117]
	ds_read_b128 v[196:199], v157 offset:50176
	v_mfma_f32_16x16x32_bf16 v[110:113], v[164:167], v[210:213], v[110:113]
	v_mfma_f32_16x16x32_bf16 v[106:109], v[172:175], v[210:213], v[106:109]
	v_mfma_f32_16x16x32_bf16 v[102:105], v[180:183], v[210:213], v[102:105]
	v_mfma_f32_16x16x32_bf16 v[98:101], v[188:191], v[210:213], v[98:101]
	ds_read_b128 v[210:213], v157 offset:52224
	v_mfma_f32_16x16x32_bf16 v[94:97], v[164:167], v[218:221], v[94:97]
	v_mfma_f32_16x16x32_bf16 v[90:93], v[172:175], v[218:221], v[90:93]
	v_mfma_f32_16x16x32_bf16 v[86:89], v[180:183], v[218:221], v[86:89]
	v_mfma_f32_16x16x32_bf16 v[82:85], v[188:191], v[218:221], v[82:85]
	ds_read_b128 v[218:221], v157 offset:54272
	v_mfma_f32_16x16x32_bf16 v[78:81], v[164:167], v[226:229], v[78:81]
	v_mfma_f32_16x16x32_bf16 v[74:77], v[172:175], v[226:229], v[74:77]
	v_mfma_f32_16x16x32_bf16 v[70:73], v[180:183], v[226:229], v[70:73]
	v_mfma_f32_16x16x32_bf16 v[66:69], v[188:191], v[226:229], v[66:69]
	ds_read_b128 v[226:229], v157 offset:56320
	s_waitcnt lgkmcnt(4)
	v_mfma_f32_16x16x32_bf16 v[62:65], v[148:151], v[192:195], v[62:65]
	v_mfma_f32_16x16x32_bf16 v[58:61], v[168:171], v[192:195], v[58:61]
	v_mfma_f32_16x16x32_bf16 v[54:57], v[176:179], v[192:195], v[54:57]
	v_mfma_f32_16x16x32_bf16 v[50:53], v[184:187], v[192:195], v[50:53]
	v_mfma_f32_16x16x32_bf16 v[46:49], v[148:151], v[206:209], v[46:49]
	v_mfma_f32_16x16x32_bf16 v[42:45], v[168:171], v[206:209], v[42:45]
	v_mfma_f32_16x16x32_bf16 v[38:41], v[176:179], v[206:209], v[38:41]
	v_mfma_f32_16x16x32_bf16 v[34:37], v[184:187], v[206:209], v[34:37]
	v_mfma_f32_16x16x32_bf16 v[30:33], v[148:151], v[214:217], v[30:33]
	v_mfma_f32_16x16x32_bf16 v[26:29], v[168:171], v[214:217], v[26:29]
	v_mfma_f32_16x16x32_bf16 v[22:25], v[176:179], v[214:217], v[22:25]
	v_mfma_f32_16x16x32_bf16 v[18:21], v[184:187], v[214:217], v[18:21]
	v_mfma_f32_16x16x32_bf16 v[14:17], v[148:151], v[222:225], v[14:17]
	v_mfma_f32_16x16x32_bf16 v[10:13], v[168:171], v[222:225], v[10:13]
	v_mfma_f32_16x16x32_bf16 v[6:9], v[176:179], v[222:225], v[6:9]
	v_mfma_f32_16x16x32_bf16 v[2:5], v[184:187], v[222:225], v[2:5]
	s_waitcnt lgkmcnt(0)
	v_mfma_f32_16x16x32_bf16 v[62:65], v[164:167], v[196:199], v[62:65]
	v_mfma_f32_16x16x32_bf16 v[58:61], v[172:175], v[196:199], v[58:61]
	v_mfma_f32_16x16x32_bf16 v[54:57], v[180:183], v[196:199], v[54:57]
	v_mfma_f32_16x16x32_bf16 v[50:53], v[188:191], v[196:199], v[50:53]
	v_mfma_f32_16x16x32_bf16 v[46:49], v[164:167], v[210:213], v[46:49]
	v_mfma_f32_16x16x32_bf16 v[42:45], v[172:175], v[210:213], v[42:45]
	v_mfma_f32_16x16x32_bf16 v[38:41], v[180:183], v[210:213], v[38:41]
	v_mfma_f32_16x16x32_bf16 v[34:37], v[188:191], v[210:213], v[34:37]
	v_mfma_f32_16x16x32_bf16 v[30:33], v[164:167], v[218:221], v[30:33]
	v_mfma_f32_16x16x32_bf16 v[26:29], v[172:175], v[218:221], v[26:29]
	v_mfma_f32_16x16x32_bf16 v[22:25], v[180:183], v[218:221], v[22:25]
	v_mfma_f32_16x16x32_bf16 v[18:21], v[188:191], v[218:221], v[18:21]
	v_mfma_f32_16x16x32_bf16 v[14:17], v[164:167], v[226:229], v[14:17]
	v_mfma_f32_16x16x32_bf16 v[10:13], v[172:175], v[226:229], v[10:13]
	v_mfma_f32_16x16x32_bf16 v[6:9], v[180:183], v[226:229], v[6:9]
	v_mfma_f32_16x16x32_bf16 v[2:5], v[188:191], v[226:229], v[2:5]
	s_setprio 0
	s_waitcnt vmcnt(0)
	s_barrier
	s_add_i32 s89, s89, 2
	s_cmp_lt_u32 s89, 32
	s_cbranch_scc1 .Lsp4_loop_1
	s_and_b64 vcc, exec, s[12:13]
	s_cbranch_vccz .LBB0_618
	s_barrier

; #define PG8_STAGE(bufoff, gbase, voff) do { _Pragma("unroll") for (int _i = 0; _i < 2; ++_i) \
;         __builtin_amdgcn_global_load_lds((const unsigned*)((const char*)(gbase) + (voff)[_i]), (PG8_LAS unsigned*)(lds + (bufoff) + ldsw + _i * 8192), 16, 0, 0); } while (0)
; #define PG8_WAIT_V(n) asm volatile("s_waitcnt vmcnt(" #n ")" ::: "memory")
; #define PG8_BAR __builtin_amdgcn_s_barrier()
; template <class Epi, class Sched, bool ALIGN_EPI = false, bool SP2 = false>
; __device__ __forceinline__ void gemm_phase(PG8_LAS unsigned char* lds, const Gemm g, const Sched& S, const Epi& E) {
;     ...
;     const char* cA = (const char*)g.A + (size_t)cur.pm * tstep; const char* cB = (const char*)g.Bt + (size_t)cur.pn * tstep;
;     S.a_ready(cur);
;     if constexpr (SP2) {
;         PG8_STAGE(PG8_SB(0, 0), cB, voffB); PG8_STAGE(PG8_SB(0, 1), cB + hstep, voffB); PG8_STAGE(PG8_SA(0, 0), cA, voffA); PG8_STAGE(PG8_SA(0, 1), cA + hstep, voffA);
;         if (wr == 1) PG8_BAR;
;         PG8_WAIT_V(2); PG8_BAR;
;         PG8_STAGE(PG8_SB(1, 0), cB + kstep, voffB); PG8_STAGE(PG8_SA(1, 0), cA + kstep, voffA); PG8_STAGE(PG8_SB(1, 1), cB + hstep + kstep, voffB);
;         PG8_WAIT_V(6); PG8_BAR;
.LBB0_759:
	s_lshl_b32 s10, s10, 5
	s_and_b32 s45, s10, 0x60
	s_lshl_b32 s3, s6, 13
	s_lshl_b32 s20, s45, 7
	s_add_u32 s10, s50, 0x3c40000
	s_addc_u32 s11, s51, 0
	s_add_u32 s12, s50, 0x1a440000
	s_addc_u32 s13, s51, 0
	s_add_u32 s74, s50, 0x3ccf0000
	s_addc_u32 s75, s51, 0
	s_add_u32 s14, s50, 0x10440000
	s_addc_u32 s15, s51, 0
	s_add_u32 s76, s50, 0x3b8f0000
	s_mov_b64 s[16:17], 0x80
	s_addc_u32 s77, s51, 0
	s_add_i32 m0, s41, 0x18000
	v_lshl_add_u64 v[8:9], v[8:9], 0, s[16:17]
	s_ashr_i32 s78, s94, 31
	s_waitcnt vmcnt(2)
	s_barrier
	global_load_lds_dwordx4 v[8:9], off
	v_lshl_add_u64 v[6:7], v[6:7], 0, s[16:17]
	s_add_i32 m0, s41, 0x1a000
	s_add_i32 s79, s41, 0x8000
	s_add_i32 s80, s41, 0xa000
	global_load_lds_dwordx4 v[6:7], off
	v_lshl_add_u64 v[2:3], v[2:3], 0, s[16:17]
	s_mov_b32 m0, s79
	s_add_u32 s18, s30, 0x80080
	global_load_lds_dwordx4 v[2:3], off
	v_lshl_add_u64 v[2:3], v[4:5], 0, s[16:17]
	s_mov_b32 m0, s80
	s_addc_u32 s19, s31, 0
	global_load_lds_dwordx4 v[2:3], off
	s_add_i32 m0, s41, 0x1c000
	v_lshl_add_u64 v[2:3], s[18:19], 0, v[134:135]
	global_load_lds_dwordx4 v[2:3], off
	v_lshl_add_u64 v[2:3], s[18:19], 0, v[138:139]
	s_add_i32 m0, s41, 0x1e000
	v_lshlrev_b32_e32 v4, 6, v131
	global_load_lds_dwordx4 v[2:3], off
	v_and_b32_e32 v2, 15, v131
	v_lshlrev_b32_e32 v3, 1, v130
	s_movk_i32 s18, 0x3c0
	v_lshlrev_b32_e32 v5, 2, v131
	v_and_or_b32 v4, v4, s18, v3
	v_and_b32_e32 v5, 32, v5
	v_lshl_or_b32 v147, s6, 6, v2
	v_lshl_or_b32 v2, v2, 6, v3
	v_lshlrev_b32_e32 v3, 9, v131
	v_bitop3_b32 v160, s20, v4, v5 bitop3:0xf6
	v_and_b32_e32 v3, 0x70000, v3
	v_lshlrev_b32_e32 v4, 12, v12
	v_or3_b32 v3, v10, v3, v4
	v_add_u32_e32 v142, v3, v11
	v_lshlrev_b32_e32 v3, 5, v13
	s_waitcnt vmcnt(0)
	s_cmpk_lt_u32 s1, 0x100
	v_and_b32_e32 v3, 0xf0000, v3
	v_bitop3_b32 v2, v2, s3, v5 bitop3:0xde
	s_cselect_b64 s[18:19], -1, 0
	v_or3_b32 v3, v10, v3, v4
	s_add_i32 s81, 0, 0x10000
	s_add_i32 s82, 0, 0x14000
	s_sext_i32_i8 s3, s0
	v_or_b32_e32 v162, s45, v130
	v_mov_b32_e32 v143, v141
	v_add_u32_e32 v144, v3, v11
	v_mov_b32_e32 v145, v141
	v_mov_b64_e32 v[148:149], 0xdc0
	v_mov_b64_e32 v[150:151], 0xdbf
	v_add_u32_e32 v164, s81, v160
	v_add_u32_e32 v165, s82, v160
	v_add_u32_e32 v166, 0, v2
	v_mov_b32_e32 v167, 0x3db504f3
	v_mov_b32_e32 v168, 0x3e0293ee
	s_mov_b32 s83, 0
	s_barrier
	s_branch .LBB0_762

; template <class Epi, class Sched, bool ALIGN_EPI = false, bool SP2 = false>
; __device__ __forceinline__ void gemm_phase(PG8_LAS unsigned char* lds, const Gemm g, const Sched& S, const Epi& E) {
;     const int tid = threadIdx.x, wid = __builtin_amdgcn_readfirstlane(tid >> 6), lane = tid & 63, wr = wid >> 2, wc = wid & 3, fr = lane & 15, fq = lane >> 4;
;     const int K = g.K, nt = K / BK;
;     unsigned voffA[2], voffB[2];
; #pragma unroll
;     for (int i = 0; i < 2; ++i) { int R, C; stage_rc(tid * 16 + i * 8192, R, C); const int Rb = Epi::PERM ? ((R & ~31) + perm32(R & 31)) : R;
;         voffA[i] = (unsigned)(R * K + C) * 2u; voffB[i] = (unsigned)(Rb * K + C) * 2u; }
;     const size_t kstep = (size_t)(BK * 2);
;     const size_t hstep = (size_t)HALF * K * 2;
;     const size_t tstep = 2 * hstep;
;     const unsigned ldsw = (unsigned)wid * 1024u;
;     const int aoff = lds_byte(wr * 64 + fr, fq * 8), boff = lds_byte(wc * 32 + fr, fq * 8);
;     ...
; #pragma unroll
;         for (int a = 0; a < 2; ++a)
; #pragma unroll
;             for (int b = 0; b < 2; ++b)
; #pragma unroll
;                 for (int m = 0; m < 4; ++m)
; #pragma unroll
;                     for (int n = 0; n < 2; ++n) acc[a][b][m][n] = (f32x4){0.f, 0.f, 0.f, 0.f};
;         cur = nxt; cA = nA; cB = nB; ++ui;
.LBB0_764:
	s_ashr_i32 s23, s22, 31
	s_lshl_b64 s[24:25], s[22:23], 20
	s_add_u32 s24, s4, s24
	s_addc_u32 s25, s5, s25
	s_and_b64 s[26:27], s[0:1], exec
	s_cselect_b32 s6, s25, s29
	s_cselect_b32 s23, s24, s28
	s_ashr_i32 s21, s20, 31
	s_lshl_b64 s[26:27], s[20:21], 20
	s_add_u32 s26, s39, s26
	s_addc_u32 s27, s40, s27
	s_and_b64 s[34:35], s[0:1], exec
	s_cselect_b32 s21, s27, s31
	s_cselect_b32 s70, s26, s30
	s_add_u32 s28, s28, 0x80080
	s_addc_u32 s29, s29, 0
	s_add_u32 s71, s30, 0x100
	v_mov_b32_e32 v2, 0
	s_addc_u32 s84, s31, 0
	s_mov_b32 s85, -2
	v_mov_b32_e32 v3, v2
	v_mov_b32_e32 v4, v2
	v_mov_b32_e32 v5, v2
	v_mov_b32_e32 v6, v2
	v_mov_b32_e32 v7, v2
	v_mov_b32_e32 v8, v2
	v_mov_b32_e32 v9, v2
	v_mov_b32_e32 v18, v2
	v_mov_b32_e32 v19, v2
	v_mov_b32_e32 v20, v2
	v_mov_b32_e32 v21, v2
	v_mov_b32_e32 v22, v2
	v_mov_b32_e32 v23, v2
	v_mov_b32_e32 v24, v2
	v_mov_b32_e32 v25, v2
	v_mov_b32_e32 v34, v2
	v_mov_b32_e32 v35, v2
	v_mov_b32_e32 v36, v2
	v_mov_b32_e32 v37, v2
	v_mov_b32_e32 v38, v2
	v_mov_b32_e32 v39, v2
	v_mov_b32_e32 v40, v2
	v_mov_b32_e32 v41, v2
	v_mov_b32_e32 v50, v2
	v_mov_b32_e32 v51, v2
	v_mov_b32_e32 v52, v2
	v_mov_b32_e32 v53, v2
	v_mov_b32_e32 v54, v2
	v_mov_b32_e32 v55, v2
	v_mov_b32_e32 v56, v2
	v_mov_b32_e32 v57, v2
	v_mov_b32_e32 v10, v2
	v_mov_b32_e32 v11, v2
	v_mov_b32_e32 v12, v2
	v_mov_b32_e32 v13, v2
	v_mov_b32_e32 v14, v2
	v_mov_b32_e32 v15, v2
	v_mov_b32_e32 v16, v2
	v_mov_b32_e32 v17, v2
	v_mov_b32_e32 v26, v2
	v_mov_b32_e32 v27, v2
	v_mov_b32_e32 v28, v2
	v_mov_b32_e32 v29, v2
	v_mov_b32_e32 v30, v2
	v_mov_b32_e32 v31, v2
	v_mov_b32_e32 v32, v2
	v_mov_b32_e32 v33, v2
	v_mov_b32_e32 v42, v2
	v_mov_b32_e32 v43, v2
	v_mov_b32_e32 v44, v2
	v_mov_b32_e32 v45, v2
	v_mov_b32_e32 v46, v2
	v_mov_b32_e32 v47, v2
	v_mov_b32_e32 v48, v2
	v_mov_b32_e32 v49, v2
	v_mov_b32_e32 v58, v2
	v_mov_b32_e32 v59, v2
	v_mov_b32_e32 v60, v2
	v_mov_b32_e32 v61, v2
	v_mov_b32_e32 v62, v2
	v_mov_b32_e32 v63, v2
	v_mov_b32_e32 v64, v2
	v_mov_b32_e32 v65, v2
	v_mov_b32_e32 v66, v2
	v_mov_b32_e32 v67, v2
	v_mov_b32_e32 v68, v2
	v_mov_b32_e32 v69, v2
	v_mov_b32_e32 v70, v2
	v_mov_b32_e32 v71, v2
	v_mov_b32_e32 v72, v2
	v_mov_b32_e32 v73, v2
	v_mov_b32_e32 v82, v2
	v_mov_b32_e32 v83, v2
	v_mov_b32_e32 v84, v2
	v_mov_b32_e32 v85, v2
	v_mov_b32_e32 v86, v2
	v_mov_b32_e32 v87, v2
	v_mov_b32_e32 v88, v2
	v_mov_b32_e32 v89, v2
	v_mov_b32_e32 v98, v2
	v_mov_b32_e32 v99, v2
	v_mov_b32_e32 v100, v2
	v_mov_b32_e32 v101, v2
	v_mov_b32_e32 v102, v2
	v_mov_b32_e32 v103, v2
	v_mov_b32_e32 v104, v2
	v_mov_b32_e32 v105, v2
	v_mov_b32_e32 v114, v2
	v_mov_b32_e32 v115, v2
	v_mov_b32_e32 v116, v2
	v_mov_b32_e32 v117, v2
	v_mov_b32_e32 v118, v2
	v_mov_b32_e32 v119, v2
	v_mov_b32_e32 v120, v2
	v_mov_b32_e32 v121, v2
	v_mov_b32_e32 v74, v2
	v_mov_b32_e32 v75, v2
	v_mov_b32_e32 v76, v2
	v_mov_b32_e32 v77, v2
	v_mov_b32_e32 v78, v2
	v_mov_b32_e32 v79, v2
	v_mov_b32_e32 v80, v2
	v_mov_b32_e32 v81, v2
	v_mov_b32_e32 v90, v2
	v_mov_b32_e32 v91, v2
	v_mov_b32_e32 v92, v2
	v_mov_b32_e32 v93, v2
	v_mov_b32_e32 v94, v2
	v_mov_b32_e32 v95, v2
	v_mov_b32_e32 v96, v2
	v_mov_b32_e32 v97, v2
	v_mov_b32_e32 v106, v2
	v_mov_b32_e32 v107, v2
	v_mov_b32_e32 v108, v2
	v_mov_b32_e32 v109, v2
	v_mov_b32_e32 v110, v2
	v_mov_b32_e32 v111, v2
	v_mov_b32_e32 v112, v2
	v_mov_b32_e32 v113, v2
	v_mov_b32_e32 v122, v2
	v_mov_b32_e32 v123, v2
	v_mov_b32_e32 v124, v2
	v_mov_b32_e32 v125, v2
	v_mov_b32_e32 v126, v2
	v_mov_b32_e32 v127, v2
	v_mov_b32_e32 v128, v2
	v_mov_b32_e32 v129, v2
	v_and_b32_e32 v242, 0x3ff, v0
	v_and_b32_e32 v241, 63, v242
	v_readfirstlane_b32 s97, v242
	v_lshrrev_b32_e32 v240, 2, v241
	v_and_b32_e32 v203, 3, v241
	v_lshlrev_b32_e32 v203, 4, v203
	v_lshrrev_b32_e32 v201, 5, v241
	v_lshlrev_b32_e32 v201, 5, v201
	v_xor_b32_e32 v203, v203, v201
	v_lshl_or_b32 v169, v240, 12, v203
	v_add_u32_e32 v201, 64, v169
	v_lshrrev_b32_e32 v241, 2, v240
	v_and_b32_e32 v242, 3, v240
	v_lshl_or_b32 v241, v241, 3, v242
	v_lshl_or_b32 v203, v241, 12, v203
	v_add_u32_e32 v240, 64, v203
	v_add_u32_e32 v241, 0x4000, v203
	v_add_u32_e32 v242, 0x4040, v203
	s_lshr_b32 s97, s97, 6
	s_lshr_b32 s98, s97, 2
	s_and_b32 s97, s97, 3
	s_lshl_b32 s32, s98, 2
	s_add_i32 s32, s32, s97
	s_lshl_b32 s32, s32, 11
	s_xor_b32 s90, s98, 1
	s_mul_i32 s91, s90, 0xc000
	s_add_i32 s91, s91, 0x10000
	s_lshl_b32 s92, s90, 14
	s_sub_i32 s92, 0x18000, s92
	s_lshl_b32 s96, s97, 12
	s_add_i32 s91, s91, s96
	s_add_i32 s92, s92, s96
	s_lshl_b32 s90, s90, 19
	s_lshl_b32 s96, s97, 17
	s_add_i32 s90, s90, s96
	s_mul_i32 s93, s98, 0x45
	s_add_i32 s93, s93, 30
	s_mul_i32 s95, s98, 0x47
	s_sub_i32 s95, 0x63, s95
	s_lshl_b32 s96, s32, 5
	s_add_u32 s68, s28, s96
	s_addc_u32 s69, s29, 0
	s_sub_u32 s66, s68, 0x80000
	s_subb_u32 s67, s69, 0
	s_sub_i32 s96, s98, 1
	s_lshl_b32 s96, s96, 7
	s_add_i32 s96, s96, s90
	s_add_u32 s88, s71, s96
	s_addc_u32 s89, s84, 0
	s_mov_b32 s96, 0
; #define PG8_STAGE(bufoff, gbase, voff) do { _Pragma("unroll") for (int _i = 0; _i < 2; ++_i) \
;         __builtin_amdgcn_global_load_lds((const unsigned*)((const char*)(gbase) + (voff)[_i]), (PG8_LAS unsigned*)(lds + (bufoff) + ldsw + _i * 8192), 16, 0, 0); } while (0)
; #define PG8_LDA(dst, b, h) do { _Pragma("unroll") for (int m = 0; m < 4; ++m) _Pragma("unroll") for (int k = 0; k < 2; ++k) dst[m][k] = *(const PG8_LAS bf16x8*)(lds + PG8_SA(b, h) + aoff + m * 2048 + k * 1024); } while (0)
; #define PG8_LDB(dst, b, h) do { _Pragma("unroll") for (int n = 0; n < 2; ++n) _Pragma("unroll") for (int k = 0; k < 2; ++k) dst[n][k] = *(const PG8_LAS bf16x8*)(lds + PG8_SB(b, h) + boff + n * 2048 + k * 1024); } while (0)
; #define PG8_MMA(ai, bj, At, Bt) do { __builtin_amdgcn_s_setprio(1); _Pragma("unroll") for (int m = 0; m < 4; ++m) _Pragma("unroll") for (int n = 0; n < 2; ++n) _Pragma("unroll") for (int k = 0; k < 2; ++k) \
;         acc[ai][bj][m][n] = __builtin_amdgcn_mfma_f32_16x16x32_bf16(Bt[n][k], At[m][k], acc[ai][bj][m][n], 0, 0, 0); __builtin_amdgcn_s_setprio(0); } while (0)
; #define PG8_WAIT_V(n) asm volatile("s_waitcnt vmcnt(" #n ")" ::: "memory")
; #define PG8_BAR __builtin_amdgcn_s_barrier()
; template <class Epi, class Sched, bool ALIGN_EPI = false, bool SP2 = false>
; __device__ __forceinline__ void gemm_phase(PG8_LAS unsigned char* lds, const Gemm g, const Sched& S, const Epi& E) {
;     ...
;         for (int t = 0; t < nt; t += 2) {
;             const bool last = (t == nt - 2);
;             const char* a1 = cA + (size_t)(t + 1) * kstep;
;             const char* a2 = last ? nA : cA + (size_t)(t + 2) * kstep; const char* b2 = last ? nB : cB + (size_t)(t + 2) * kstep;
;             const char* a3 = a2 + kstep; const char* b3 = b2 + kstep;
;             if (last && has_next) S.a_ready(nxt);
;             if constexpr (SP2) {
;             PG8_LDB(B0, 0, 0); PG8_LDB(B1, 0, 1); PG8_SCHED; PG8_LDA(At, 0, 0); PG8_STAGE(PG8_SA(1, 1), a1 + hstep, voffA);
;             PG8_WAIT_V(8); PG8_WAIT_L(0); PG8_BAR; PG8_MMA(0, 0, At, B0); PG8_MMA(0, 1, At, B1); PG8_BAR; PG8_SCHED;
;             PG8_LDA(At, 0, 1); PG8_STAGE(PG8_SB(0, 0), b2, voffB); PG8_STAGE(PG8_SB(0, 1), b2 + hstep, voffB); PG8_STAGE(PG8_SA(0, 0), a2, voffA);
;             PG8_WAIT_V(8); PG8_WAIT_L(0); PG8_BAR; PG8_MMA(1, 0, At, B0); PG8_MMA(1, 1, At, B1); PG8_BAR; PG8_SCHED;
.Lsp4_loop_2:
	s_add_i32 m0, s32, 0x8000
	s_nop 0
	global_load_lds_dwordx4 v169, s[66:67]
	s_add_i32 m0, s32, 0x8400
	s_nop 0
	global_load_lds_dwordx4 v201, s[66:67]
	s_add_i32 m0, s32, 0xc000
	s_nop 0
	global_load_lds_dwordx4 v169, s[68:69]
	s_add_i32 m0, s32, 0xc400
	s_nop 0
	global_load_lds_dwordx4 v201, s[68:69]
	ds_read_b128 v[152:155], v164
	ds_read_b128 v[156:159], v164 offset:1024
	ds_read_b128 v[170:173], v164 offset:2048
	ds_read_b128 v[174:177], v164 offset:3072
	ds_read_b128 v[178:181], v164 offset:16384
	ds_read_b128 v[182:185], v164 offset:17408
	ds_read_b128 v[186:189], v164 offset:18432
	ds_read_b128 v[190:193], v164 offset:19456
	ds_read_b128 v[194:197], v166
	ds_read_b128 v[204:207], v166 offset:1024
	ds_read_b128 v[208:211], v166 offset:2048
	ds_read_b128 v[212:215], v166 offset:3072
	ds_read_b128 v[216:219], v166 offset:4096
	ds_read_b128 v[220:223], v166 offset:5120
	ds_read_b128 v[224:227], v166 offset:6144
	ds_read_b128 v[228:231], v166 offset:7168
	s_waitcnt lgkmcnt(8)
	s_add_i32 m0, s91, 0x0
	s_nop 0
	global_load_lds_dwordx4 v203, s[88:89]
	s_add_i32 m0, s91, 0x400
	s_nop 0
	global_load_lds_dwordx4 v240, s[88:89]
	s_add_i32 m0, s91, 0x800
	s_nop 0
	global_load_lds_dwordx4 v241, s[88:89]
	s_add_i32 m0, s91, 0xc00
	s_nop 0
	global_load_lds_dwordx4 v242, s[88:89]
	s_add_u32 s66, s66, 0x80
	s_addc_u32 s67, s67, 0
	s_add_u32 s68, s68, 0x80
	s_addc_u32 s69, s69, 0
	s_add_u32 s88, s88, 0x80
	s_addc_u32 s89, s89, 0
	s_cmp_lg_u32 s96, 30
	s_cbranch_scc1 .Lsp4_noA_2
	s_lshl_b32 s97, s32, 5
	s_add_u32 s66, s23, s97
	s_addc_u32 s67, s6, 0
	s_add_u32 s68, s66, 0x80000
	s_addc_u32 s69, s67, 0
.Lsp4_noA_2:
	s_cmp_lg_u32 s96, s93
	s_cbranch_scc1 .Lsp4_noB0_2
	s_add_u32 s88, s70, s90
	s_addc_u32 s89, s21, 0
.Lsp4_noB0_2:
	s_waitcnt lgkmcnt(0)
	s_barrier
	s_setprio 1
	v_mfma_f32_16x16x32_bf16 v[126:129], v[152:155], v[194:197], v[126:129]
	v_mfma_f32_16x16x32_bf16 v[122:125], v[170:173], v[194:197], v[122:125]
	v_mfma_f32_16x16x32_bf16 v[118:121], v[178:181], v[194:197], v[118:121]
	v_mfma_f32_16x16x32_bf16 v[114:117], v[186:189], v[194:197], v[114:117]
	ds_read_b128 v[194:197], v166 offset:16384
	v_mfma_f32_16x16x32_bf16 v[110:113], v[152:155], v[208:211], v[110:113]
	v_mfma_f32_16x16x32_bf16 v[106:109], v[170:173], v[208:211], v[106:109]
	v_mfma_f32_16x16x32_bf16 v[102:105], v[178:181], v[208:211], v[102:105]
	v_mfma_f32_16x16x32_bf16 v[98:101], v[186:189], v[208:211], v[98:101]
	ds_read_b128 v[208:211], v166 offset:18432
	v_mfma_f32_16x16x32_bf16 v[94:97], v[152:155], v[216:219], v[94:97]
	v_mfma_f32_16x16x32_bf16 v[90:93], v[170:173], v[216:219], v[90:93]
	v_mfma_f32_16x16x32_bf16 v[86:89], v[178:181], v[216:219], v[86:89]
	v_mfma_f32_16x16x32_bf16 v[82:85], v[186:189], v[216:219], v[82:85]
	ds_read_b128 v[216:219], v166 offset:20480
	v_mfma_f32_16x16x32_bf16 v[78:81], v[152:155], v[224:227], v[78:81]
	v_mfma_f32_16x16x32_bf16 v[74:77], v[170:173], v[224:227], v[74:77]
	v_mfma_f32_16x16x32_bf16 v[70:73], v[178:181], v[224:227], v[70:73]
	v_mfma_f32_16x16x32_bf16 v[66:69], v[186:189], v[224:227], v[66:69]
	ds_read_b128 v[224:227], v166 offset:22528
	v_mfma_f32_16x16x32_bf16 v[126:129], v[156:159], v[204:207], v[126:129]
	v_mfma_f32_16x16x32_bf16 v[122:125], v[174:177], v[204:207], v[122:125]
	v_mfma_f32_16x16x32_bf16 v[118:121], v[182:185], v[204:207], v[118:121]
	v_mfma_f32_16x16x32_bf16 v[114:117], v[190:193], v[204:207], v[114:117]
	ds_read_b128 v[204:207], v166 offset:17408
	v_mfma_f32_16x16x32_bf16 v[110:113], v[156:159], v[212:215], v[110:113]
	v_mfma_f32_16x16x32_bf16 v[106:109], v[174:177], v[212:215], v[106:109]
	v_mfma_f32_16x16x32_bf16 v[102:105], v[182:185], v[212:215], v[102:105]
	v_mfma_f32_16x16x32_bf16 v[98:101], v[190:193], v[212:215], v[98:101]
	ds_read_b128 v[212:215], v166 offset:19456
	v_mfma_f32_16x16x32_bf16 v[94:97], v[156:159], v[220:223], v[94:97]
	v_mfma_f32_16x16x32_bf16 v[90:93], v[174:177], v[220:223], v[90:93]
	v_mfma_f32_16x16x32_bf16 v[86:89], v[182:185], v[220:223], v[86:89]
	v_mfma_f32_16x16x32_bf16 v[82:85], v[190:193], v[220:223], v[82:85]
	ds_read_b128 v[220:223], v166 offset:21504
	v_mfma_f32_16x16x32_bf16 v[78:81], v[156:159], v[228:231], v[78:81]
	v_mfma_f32_16x16x32_bf16 v[74:77], v[174:177], v[228:231], v[74:77]
	v_mfma_f32_16x16x32_bf16 v[70:73], v[182:185], v[228:231], v[70:73]
	v_mfma_f32_16x16x32_bf16 v[66:69], v[190:193], v[228:231], v[66:69]
	ds_read_b128 v[228:231], v166 offset:23552
	s_waitcnt lgkmcnt(4)
	v_mfma_f32_16x16x32_bf16 v[62:65], v[152:155], v[194:197], v[62:65]
	v_mfma_f32_16x16x32_bf16 v[58:61], v[170:173], v[194:197], v[58:61]
	v_mfma_f32_16x16x32_bf16 v[54:57], v[178:181], v[194:197], v[54:57]
	v_mfma_f32_16x16x32_bf16 v[50:53], v[186:189], v[194:197], v[50:53]
	v_mfma_f32_16x16x32_bf16 v[46:49], v[152:155], v[208:211], v[46:49]
	v_mfma_f32_16x16x32_bf16 v[42:45], v[170:173], v[208:211], v[42:45]
	v_mfma_f32_16x16x32_bf16 v[38:41], v[178:181], v[208:211], v[38:41]
	v_mfma_f32_16x16x32_bf16 v[34:37], v[186:189], v[208:211], v[34:37]
	v_mfma_f32_16x16x32_bf16 v[30:33], v[152:155], v[216:219], v[30:33]
	v_mfma_f32_16x16x32_bf16 v[26:29], v[170:173], v[216:219], v[26:29]
	v_mfma_f32_16x16x32_bf16 v[22:25], v[178:181], v[216:219], v[22:25]
	v_mfma_f32_16x16x32_bf16 v[18:21], v[186:189], v[216:219], v[18:21]
	v_mfma_f32_16x16x32_bf16 v[14:17], v[152:155], v[224:227], v[14:17]
	v_mfma_f32_16x16x32_bf16 v[10:13], v[170:173], v[224:227], v[10:13]
	v_mfma_f32_16x16x32_bf16 v[6:9], v[178:181], v[224:227], v[6:9]
	v_mfma_f32_16x16x32_bf16 v[2:5], v[186:189], v[224:227], v[2:5]
	s_waitcnt lgkmcnt(0)
	v_mfma_f32_16x16x32_bf16 v[62:65], v[156:159], v[204:207], v[62:65]
	v_mfma_f32_16x16x32_bf16 v[58:61], v[174:177], v[204:207], v[58:61]
	v_mfma_f32_16x16x32_bf16 v[54:57], v[182:185], v[204:207], v[54:57]
	v_mfma_f32_16x16x32_bf16 v[50:53], v[190:193], v[204:207], v[50:53]
	v_mfma_f32_16x16x32_bf16 v[46:49], v[156:159], v[212:215], v[46:49]
	v_mfma_f32_16x16x32_bf16 v[42:45], v[174:177], v[212:215], v[42:45]
	v_mfma_f32_16x16x32_bf16 v[38:41], v[182:185], v[212:215], v[38:41]
	v_mfma_f32_16x16x32_bf16 v[34:37], v[190:193], v[212:215], v[34:37]
	v_mfma_f32_16x16x32_bf16 v[30:33], v[156:159], v[220:223], v[30:33]
	v_mfma_f32_16x16x32_bf16 v[26:29], v[174:177], v[220:223], v[26:29]
	v_mfma_f32_16x16x32_bf16 v[22:25], v[182:185], v[220:223], v[22:25]
	v_mfma_f32_16x16x32_bf16 v[18:21], v[190:193], v[220:223], v[18:21]
	v_mfma_f32_16x16x32_bf16 v[14:17], v[156:159], v[228:231], v[14:17]
	v_mfma_f32_16x16x32_bf16 v[10:13], v[174:177], v[228:231], v[10:13]
	v_mfma_f32_16x16x32_bf16 v[6:9], v[182:185], v[228:231], v[6:9]
	v_mfma_f32_16x16x32_bf16 v[2:5], v[190:193], v[228:231], v[2:5]
	s_setprio 0
	s_waitcnt vmcnt(0)
	s_barrier
; #define PG8_STAGE(bufoff, gbase, voff) do { _Pragma("unroll") for (int _i = 0; _i < 2; ++_i) \
;         __builtin_amdgcn_global_load_lds((const unsigned*)((const char*)(gbase) + (voff)[_i]), (PG8_LAS unsigned*)(lds + (bufoff) + ldsw + _i * 8192), 16, 0, 0); } while (0)
; #define PG8_LDA(dst, b, h) do { _Pragma("unroll") for (int m = 0; m < 4; ++m) _Pragma("unroll") for (int k = 0; k < 2; ++k) dst[m][k] = *(const PG8_LAS bf16x8*)(lds + PG8_SA(b, h) + aoff + m * 2048 + k * 1024); } while (0)
; #define PG8_LDB(dst, b, h) do { _Pragma("unroll") for (int n = 0; n < 2; ++n) _Pragma("unroll") for (int k = 0; k < 2; ++k) dst[n][k] = *(const PG8_LAS bf16x8*)(lds + PG8_SB(b, h) + boff + n * 2048 + k * 1024); } while (0)
; template <class Epi, class Sched, bool ALIGN_EPI = false, bool SP2 = false>
; __device__ __forceinline__ void gemm_phase(PG8_LAS unsigned char* lds, const Gemm g, const Sched& S, const Epi& E) {
;     ...
;         for (int t = 0; t < nt; t += 2) {
;             const bool last = (t == nt - 2);
;             const char* a1 = cA + (size_t)(t + 1) * kstep;
;             const char* a2 = last ? nA : cA + (size_t)(t + 2) * kstep; const char* b2 = last ? nB : cB + (size_t)(t + 2) * kstep;
;             const char* a3 = a2 + kstep; const char* b3 = b2 + kstep;
;             if (last && has_next) S.a_ready(nxt);
;             if constexpr (SP2) {
;             PG8_LDB(B0, 0, 0); PG8_LDB(B1, 0, 1); PG8_SCHED; PG8_LDA(At, 0, 0); PG8_STAGE(PG8_SA(1, 1), a1 + hstep, voffA);
;             PG8_WAIT_V(8); PG8_WAIT_L(0); PG8_BAR; PG8_MMA(0, 0, At, B0); PG8_MMA(0, 1, At, B1); PG8_BAR; PG8_SCHED;
;             PG8_LDA(At, 0, 1); PG8_STAGE(PG8_SB(0, 0), b2, voffB); PG8_STAGE(PG8_SB(0, 1), b2 + hstep, voffB); PG8_STAGE(PG8_SA(0, 0), a2, voffA);
;             PG8_WAIT_V(8); PG8_WAIT_L(0); PG8_BAR; PG8_MMA(1, 0, At, B0); PG8_MMA(1, 1, At, B1); PG8_BAR; PG8_SCHED;
;             PG8_LDB(B0, 1, 0); PG8_LDB(B1, 1, 1); PG8_SCHED; PG8_LDA(At, 1, 0); PG8_STAGE(PG8_SA(0, 1), a2 + hstep, voffA);
;             PG8_WAIT_V(8); PG8_WAIT_L(0); PG8_BAR; PG8_MMA(0, 0, At, B0); PG8_MMA(0, 1, At, B1); PG8_BAR; PG8_SCHED;
;             PG8_LDA(At, 1, 1); PG8_STAGE(PG8_SB(1, 0), b3, voffB); PG8_STAGE(PG8_SB(1, 1), b3 + hstep, voffB); PG8_STAGE(PG8_SA(1, 0), a3, voffA);
;             PG8_WAIT_V(8); PG8_WAIT_L(0); PG8_BAR; PG8_MMA(1, 0, At, B0); PG8_MMA(1, 1, At, B1); PG8_BAR; PG8_SCHED;
	s_add_i32 m0, s32, 0x0
	s_nop 0
	global_load_lds_dwordx4 v169, s[66:67]
	s_add_i32 m0, s32, 0x400
	s_nop 0
	global_load_lds_dwordx4 v201, s[66:67]
	s_add_i32 m0, s32, 0x4000
	s_nop 0
	global_load_lds_dwordx4 v169, s[68:69]
	s_add_i32 m0, s32, 0x4400
	s_nop 0
	global_load_lds_dwordx4 v201, s[68:69]
	ds_read_b128 v[152:155], v164 offset:32768
	ds_read_b128 v[156:159], v164 offset:33792
	ds_read_b128 v[170:173], v164 offset:34816
	ds_read_b128 v[174:177], v164 offset:35840
	ds_read_b128 v[178:181], v164 offset:49152
	ds_read_b128 v[182:185], v164 offset:50176
	ds_read_b128 v[186:189], v164 offset:51200
	ds_read_b128 v[190:193], v164 offset:52224
	ds_read_b128 v[194:197], v166 offset:32768
	ds_read_b128 v[204:207], v166 offset:33792
	ds_read_b128 v[208:211], v166 offset:34816
	ds_read_b128 v[212:215], v166 offset:35840
	ds_read_b128 v[216:219], v166 offset:36864
	ds_read_b128 v[220:223], v166 offset:37888
	ds_read_b128 v[224:227], v166 offset:38912
	ds_read_b128 v[228:231], v166 offset:39936
	s_waitcnt lgkmcnt(8)
	s_add_i32 m0, s92, 0x0
	s_nop 0
	global_load_lds_dwordx4 v203, s[88:89]
	s_add_i32 m0, s92, 0x400
	s_nop 0
	global_load_lds_dwordx4 v240, s[88:89]
	s_add_i32 m0, s92, 0x800
	s_nop 0
	global_load_lds_dwordx4 v241, s[88:89]
	s_add_i32 m0, s92, 0xc00
	s_nop 0
	global_load_lds_dwordx4 v242, s[88:89]
	s_add_u32 s66, s66, 0x80
	s_addc_u32 s67, s67, 0
	s_add_u32 s68, s68, 0x80
	s_addc_u32 s69, s69, 0
	s_add_u32 s88, s88, 0x80
	s_addc_u32 s89, s89, 0
	s_cmp_lg_u32 s96, s95
	s_cbranch_scc1 .Lsp4_noB1_2
	s_add_u32 s88, s70, s90
	s_addc_u32 s89, s21, 0
.Lsp4_noB1_2:
	s_waitcnt lgkmcnt(0)
	s_barrier
	s_setprio 1
	v_mfma_f32_16x16x32_bf16 v[126:129], v[152:155], v[194:197], v[126:129]
	v_mfma_f32_16x16x32_bf16 v[122:125], v[170:173], v[194:197], v[122:125]
	v_mfma_f32_16x16x32_bf16 v[118:121], v[178:181], v[194:197], v[118:121]
	v_mfma_f32_16x16x32_bf16 v[114:117], v[186:189], v[194:197], v[114:117]
	ds_read_b128 v[194:197], v166 offset:49152
	v_mfma_f32_16x16x32_bf16 v[110:113], v[152:155], v[208:211], v[110:113]
	v_mfma_f32_16x16x32_bf16 v[106:109], v[170:173], v[208:211], v[106:109]
	v_mfma_f32_16x16x32_bf16 v[102:105], v[178:181], v[208:211], v[102:105]
	v_mfma_f32_16x16x32_bf16 v[98:101], v[186:189], v[208:211], v[98:101]
	ds_read_b128 v[208:211], v166 offset:51200
	v_mfma_f32_16x16x32_bf16 v[94:97], v[152:155], v[216:219], v[94:97]
	v_mfma_f32_16x16x32_bf16 v[90:93], v[170:173], v[216:219], v[90:93]
	v_mfma_f32_16x16x32_bf16 v[86:89], v[178:181], v[216:219], v[86:89]
	v_mfma_f32_16x16x32_bf16 v[82:85], v[186:189], v[216:219], v[82:85]
	ds_read_b128 v[216:219], v166 offset:53248
	v_mfma_f32_16x16x32_bf16 v[78:81], v[152:155], v[224:227], v[78:81]
	v_mfma_f32_16x16x32_bf16 v[74:77], v[170:173], v[224:227], v[74:77]
	v_mfma_f32_16x16x32_bf16 v[70:73], v[178:181], v[224:227], v[70:73]
	v_mfma_f32_16x16x32_bf16 v[66:69], v[186:189], v[224:227], v[66:69]
	ds_read_b128 v[224:227], v166 offset:55296
	v_mfma_f32_16x16x32_bf16 v[126:129], v[156:159], v[204:207], v[126:129]
	v_mfma_f32_16x16x32_bf16 v[122:125], v[174:177], v[204:207], v[122:125]
	v_mfma_f32_16x16x32_bf16 v[118:121], v[182:185], v[204:207], v[118:121]
	v_mfma_f32_16x16x32_bf16 v[114:117], v[190:193], v[204:207], v[114:117]
	ds_read_b128 v[204:207], v166 offset:50176
	v_mfma_f32_16x16x32_bf16 v[110:113], v[156:159], v[212:215], v[110:113]
	v_mfma_f32_16x16x32_bf16 v[106:109], v[174:177], v[212:215], v[106:109]
	v_mfma_f32_16x16x32_bf16 v[102:105], v[182:185], v[212:215], v[102:105]
	v_mfma_f32_16x16x32_bf16 v[98:101], v[190:193], v[212:215], v[98:101]
	ds_read_b128 v[212:215], v166 offset:52224
	v_mfma_f32_16x16x32_bf16 v[94:97], v[156:159], v[220:223], v[94:97]
	v_mfma_f32_16x16x32_bf16 v[90:93], v[174:177], v[220:223], v[90:93]
	v_mfma_f32_16x16x32_bf16 v[86:89], v[182:185], v[220:223], v[86:89]
	v_mfma_f32_16x16x32_bf16 v[82:85], v[190:193], v[220:223], v[82:85]
	ds_read_b128 v[220:223], v166 offset:54272
	v_mfma_f32_16x16x32_bf16 v[78:81], v[156:159], v[228:231], v[78:81]
	v_mfma_f32_16x16x32_bf16 v[74:77], v[174:177], v[228:231], v[74:77]
	v_mfma_f32_16x16x32_bf16 v[70:73], v[182:185], v[228:231], v[70:73]
	v_mfma_f32_16x16x32_bf16 v[66:69], v[190:193], v[228:231], v[66:69]
	ds_read_b128 v[228:231], v166 offset:56320
	s_waitcnt lgkmcnt(4)
	v_mfma_f32_16x16x32_bf16 v[62:65], v[152:155], v[194:197], v[62:65]
	v_mfma_f32_16x16x32_bf16 v[58:61], v[170:173], v[194:197], v[58:61]
	v_mfma_f32_16x16x32_bf16 v[54:57], v[178:181], v[194:197], v[54:57]
	v_mfma_f32_16x16x32_bf16 v[50:53], v[186:189], v[194:197], v[50:53]
	v_mfma_f32_16x16x32_bf16 v[46:49], v[152:155], v[208:211], v[46:49]
	v_mfma_f32_16x16x32_bf16 v[42:45], v[170:173], v[208:211], v[42:45]
	v_mfma_f32_16x16x32_bf16 v[38:41], v[178:181], v[208:211], v[38:41]
	v_mfma_f32_16x16x32_bf16 v[34:37], v[186:189], v[208:211], v[34:37]
	v_mfma_f32_16x16x32_bf16 v[30:33], v[152:155], v[216:219], v[30:33]
	v_mfma_f32_16x16x32_bf16 v[26:29], v[170:173], v[216:219], v[26:29]
	v_mfma_f32_16x16x32_bf16 v[22:25], v[178:181], v[216:219], v[22:25]
	v_mfma_f32_16x16x32_bf16 v[18:21], v[186:189], v[216:219], v[18:21]
	v_mfma_f32_16x16x32_bf16 v[14:17], v[152:155], v[224:227], v[14:17]
	v_mfma_f32_16x16x32_bf16 v[10:13], v[170:173], v[224:227], v[10:13]
	v_mfma_f32_16x16x32_bf16 v[6:9], v[178:181], v[224:227], v[6:9]
	v_mfma_f32_16x16x32_bf16 v[2:5], v[186:189], v[224:227], v[2:5]
	s_waitcnt lgkmcnt(0)
	v_mfma_f32_16x16x32_bf16 v[62:65], v[156:159], v[204:207], v[62:65]
	v_mfma_f32_16x16x32_bf16 v[58:61], v[174:177], v[204:207], v[58:61]
	v_mfma_f32_16x16x32_bf16 v[54:57], v[182:185], v[204:207], v[54:57]
	v_mfma_f32_16x16x32_bf16 v[50:53], v[190:193], v[204:207], v[50:53]
	v_mfma_f32_16x16x32_bf16 v[46:49], v[156:159], v[212:215], v[46:49]
	v_mfma_f32_16x16x32_bf16 v[42:45], v[174:177], v[212:215], v[42:45]
	v_mfma_f32_16x16x32_bf16 v[38:41], v[182:185], v[212:215], v[38:41]
	v_mfma_f32_16x16x32_bf16 v[34:37], v[190:193], v[212:215], v[34:37]
	v_mfma_f32_16x16x32_bf16 v[30:33], v[156:159], v[220:223], v[30:33]
	v_mfma_f32_16x16x32_bf16 v[26:29], v[174:177], v[220:223], v[26:29]
	v_mfma_f32_16x16x32_bf16 v[22:25], v[182:185], v[220:223], v[22:25]
	v_mfma_f32_16x16x32_bf16 v[18:21], v[190:193], v[220:223], v[18:21]
	v_mfma_f32_16x16x32_bf16 v[14:17], v[156:159], v[228:231], v[14:17]
	v_mfma_f32_16x16x32_bf16 v[10:13], v[174:177], v[228:231], v[10:13]
	v_mfma_f32_16x16x32_bf16 v[6:9], v[182:185], v[228:231], v[6:9]
	v_mfma_f32_16x16x32_bf16 v[2:5], v[190:193], v[228:231], v[2:5]
	s_setprio 0
	s_waitcnt vmcnt(0)
	s_barrier
	s_add_i32 s96, s96, 2
	s_cmp_lt_u32 s96, 32
	s_cbranch_scc1 .Lsp4_loop_2
	s_and_b64 vcc, exec, s[18:19]
	s_cbranch_vccz .LBB0_768
	s_barrier

; DI void phase_attn(const Params& P, int l, LAS unsigned char* lds) {
;     ...
;             if (t == t_lo + 1 && tid == 0) slot[2] = pend;
;             asm volatile("s_waitcnt lgkmcnt(0)" ::: "memory");
;             __builtin_amdgcn_s_barrier();
;             asm volatile("" ::: "memory");
;             if (t == t_lo && tid == 0) pend = (int)__hip_atomic_fetch_add(qctr, 1u, __ATOMIC_RELAXED, __HIP_MEMORY_SCOPE_AGENT);
.LBB0_1037:
	s_add_i32 s28, s89, s85
	s_waitcnt vmcnt(0)
	s_cmp_eq_u32 s28, 0
	s_cselect_b64 s[28:29], -1, 0
	s_and_b64 s[30:31], s[0:1], s[28:29]
	s_and_saveexec_b64 s[28:29], s[30:31]
	v_mov_b32_e32 v66, s55
	v_mov_b32_e32 v215, v255
	ds_write_b32 v66, v215
	s_or_b64 exec, exec, s[28:29]
	s_waitcnt lgkmcnt(0)
	s_barrier
	s_cmp_eq_u32 s70, 0
	s_cselect_b64 s[28:29], -1, 0
	s_and_b64 s[30:31], s[0:1], s[28:29]
	s_and_saveexec_b64 s[28:29], s[30:31]
	s_cbranch_execz .LBB0_1043
	s_mov_b64 s[34:35], exec
	v_mbcnt_lo_u32_b32 v66, s34, 0
	v_mbcnt_hi_u32_b32 v66, s35, v66
	v_cmp_eq_u32_e32 vcc, 0, v66
	s_and_saveexec_b64 s[30:31], vcc
	s_cbranch_execz .LBB0_1042
	s_bcnt1_i32_b64 s34, s[34:35]
	v_mov_b32_e32 v67, s34
	global_atomic_add v255, v159, v67, s[2:3] sc0
.LBB0_1042:
	s_or_b64 exec, exec, s[30:31]
.LBB0_1043:
	s_or_b64 exec, exec, s[28:29]
	s_add_i32 s28, s4, s85
	s_add_i32 s28, s28, 1
	s_cmp_ge_u32 s28, s84
	s_cbranch_scc0 .LBB0_1055
	s_mov_b64 s[28:29], 0
	s_and_b64 vcc, exec, s[24:25]
	s_mov_b64 s[30:31], 0
	s_cbranch_vccnz .LBB0_1056
	s_and_b64 vcc, exec, s[28:29]
	v_mov_b64_e32 v[66:67], v[188:189]
	s_cbranch_vccnz .LBB0_1057

; #define LAS __attribute__((address_space(3)))
; DI int crow(int r, int hi) { return (r & 3) + 8 * (r >> 2) + 4 * hi; }
; DI void qkt(f32x16& p0, f32x16& p1, const LAS char* Ks, const bf16x8* qr, int r32, int hi) {
;     for (int i = 0; i < 16; ++i) { p0[i] = 0.f; p1[i] = 0.f; }
; #pragma unroll
;     for (int d0 = 0; d0 < 8; ++d0) { const int cb = (d0 * 16 + hi * 8) * 2;
;         const bf16x8 b0 = *(const LAS bf16x8*)(Ks + KSWZ(r32, cb));
;         const bf16x8 b1 = *(const LAS bf16x8*)(Ks + KSWZ(32 + r32, cb));
;         p0 = __builtin_amdgcn_mfma_f32_32x32x16_bf16(b0, qr[d0], p0, 0, 0, 0);
;         p1 = __builtin_amdgcn_mfma_f32_32x32x16_bf16(b1, qr[d0], p1, 0, 0, 0); }
; }
; DI void phase_attn(const Params& P, int l, LAS unsigned char* lds) {
;     ...
;                 const int kp0 = (n - 1 + t) * 128 + h2 * 64;
;                 if (kp0 + 63 >= rq - 128 && kp0 <= rq + 159) {
;                     f32x16 p0, p1;
;                     qkt(p0, p1, Bf + h2 * 16384, qr, r32, hi);
;                     const LAS float* tq = tg + (kp0 - rq);
;                     float pmax = -1e30f;
; #pragma unroll
;                     for (int r = 0; r < 16; ++r) { p0[r] += tq[crow(r, hi)]; p1[r] += tq[32 + crow(r, hi)]; pmax = fmaxf(pmax, fmaxf(p0[r], p1[r])); }
;                     pmax = fmaxf(pmax, __shfl_xor(pmax, 32));
.LBB0_1048:
	s_and_b32 s29, s88, 0x10000
	s_add_i32 s28, s71, s90
	v_add_u32_e32 v66, s29, v203
	v_add_u32_e32 v220, s29, v212
	s_add_i32 s29, s28, 63
	s_cmp_lt_i32 s29, s86
	s_cselect_b64 s[30:31], -1, 0
	s_cmp_gt_i32 s28, s87
	s_cselect_b64 s[34:35], -1, 0
	s_or_b64 s[30:31], s[30:31], s[34:35]
	s_and_b64 vcc, exec, s[30:31]
	v_add_u32_e32 v229, v66, v202
	v_add_u32_e32 v228, v66, v205
	v_add_u32_e32 v227, v66, v206
	v_add_u32_e32 v226, v66, v207
	v_add_u32_e32 v225, v66, v208
	v_add_u32_e32 v224, v66, v209
	v_add_u32_e32 v223, v66, v210
	v_add_u32_e32 v222, v66, v211
	v_add_u32_e32 v221, s70, v216
	s_cbranch_vccnz .LBB0_1052
	ds_read_b128 v[66:69], v229
	ds_read_b128 v[82:85], v229 offset:8192
	ds_read_b128 v[230:233], v228
	ds_read_b128 v[234:237], v228 offset:8192
	v_add_u32_e32 v238, 0x20180, v221
	v_add_u32_e32 v240, 0x20208, v221
	ds_read_b128 v[246:249], v227
	ds_read_b128 v[250:253], v227 offset:8192
	s_waitcnt lgkmcnt(4)
	v_mfma_f32_32x32x16_bf16 v[66:81], v[66:69], v[126:129], 0
	v_mfma_f32_32x32x16_bf16 v[82:97], v[82:85], v[126:129], 0
	s_waitcnt lgkmcnt(2)
	v_mfma_f32_32x32x16_bf16 v[66:81], v[230:233], v[122:125], v[66:81]
	v_mfma_f32_32x32x16_bf16 v[82:97], v[234:237], v[122:125], v[82:97]
	ds_read_b128 v[230:233], v226
	ds_read_b128 v[234:237], v226 offset:8192
	s_waitcnt lgkmcnt(2)
	v_mfma_f32_32x32x16_bf16 v[66:81], v[246:249], v[118:121], v[66:81]
	v_mfma_f32_32x32x16_bf16 v[82:97], v[250:253], v[118:121], v[82:97]
	ds_read_b128 v[246:249], v225
	ds_read_b128 v[250:253], v225 offset:8192
	s_waitcnt lgkmcnt(2)
	v_mfma_f32_32x32x16_bf16 v[66:81], v[230:233], v[114:117], v[66:81]
	v_mfma_f32_32x32x16_bf16 v[82:97], v[234:237], v[114:117], v[82:97]
	ds_read_b128 v[230:233], v224
	ds_read_b128 v[234:237], v224 offset:8192
	s_waitcnt lgkmcnt(2)
	v_mfma_f32_32x32x16_bf16 v[66:81], v[246:249], v[110:113], v[66:81]
	v_mfma_f32_32x32x16_bf16 v[82:97], v[250:253], v[110:113], v[82:97]
	ds_read_b128 v[246:249], v223
	ds_read_b128 v[250:253], v223 offset:8192
	s_waitcnt lgkmcnt(2)
	v_mfma_f32_32x32x16_bf16 v[66:81], v[230:233], v[106:109], v[66:81]
	v_mfma_f32_32x32x16_bf16 v[82:97], v[234:237], v[106:109], v[82:97]
	ds_read_b128 v[230:233], v222
	ds_read_b128 v[234:237], v222 offset:8192
	s_waitcnt lgkmcnt(2)
	v_mfma_f32_32x32x16_bf16 v[66:81], v[246:249], v[102:105], v[66:81]
	v_mfma_f32_32x32x16_bf16 v[82:97], v[250:253], v[102:105], v[82:97]
	ds_read2_b32 v[238:239], v238 offset1:1
	s_waitcnt lgkmcnt(0)
	v_mfma_f32_32x32x16_bf16 v[66:81], v[230:233], v[98:101], v[66:81]
	v_add_u32_e32 v230, 0x20200, v221
	v_add_u32_e32 v232, 0x20188, v221
	ds_read2_b32 v[230:231], v230 offset1:1
	ds_read2_b32 v[232:233], v232 offset1:1
	ds_read2_b32 v[240:241], v240 offset1:1
	s_nop 6
	v_add_f32_e32 v238, v66, v238
	v_mfma_f32_32x32x16_bf16 v[82:97], v[234:237], v[98:101], v[82:97]
	v_add_f32_e32 v234, v67, v239
	s_waitcnt lgkmcnt(0)
	v_add_f32_e32 v232, v68, v232
	v_add_f32_e32 v233, v69, v233
	s_nop 7
	v_add_f32_e32 v230, v82, v230
	v_add_f32_e32 v231, v83, v231
	v_max_f32_e32 v66, v238, v230
	v_max_f32_e32 v67, v234, v231
	v_add_f32_e32 v235, v84, v240
	v_add_f32_e32 v236, v85, v241
	v_max3_f32 v66, v66, s57, v67
	v_max_f32_e32 v67, v232, v235
	v_max_f32_e32 v68, v233, v236
	v_max3_f32 v237, v66, v67, v68
	v_add_u32_e32 v66, 0x201a0, v221
	v_add_u32_e32 v68, 0x20220, v221
	ds_read2_b32 v[66:67], v66 offset1:1
	ds_read2_b32 v[68:69], v68 offset1:1
	v_add_u32_e32 v82, 0x201a8, v221
	v_add_u32_e32 v84, 0x20228, v221
	ds_read2_b32 v[82:83], v82 offset1:1
	ds_read2_b32 v[84:85], v84 offset1:1
	s_waitcnt lgkmcnt(0)
	v_add_f32_e32 v239, v70, v66
	v_add_f32_e32 v86, v86, v68
	v_add_f32_e32 v240, v71, v67
	v_add_f32_e32 v87, v87, v69
	v_max_f32_e32 v66, v239, v86
	v_max_f32_e32 v67, v240, v87
	v_add_f32_e32 v82, v72, v82
	v_add_f32_e32 v84, v88, v84
	v_add_f32_e32 v83, v73, v83
	v_add_f32_e32 v85, v89, v85
	v_max3_f32 v66, v237, v66, v67
	v_max_f32_e32 v67, v82, v84
	v_max_f32_e32 v68, v83, v85
	v_max3_f32 v88, v66, v67, v68
	v_add_u32_e32 v66, 0x201c0, v221
	v_add_u32_e32 v68, 0x20240, v221
	ds_read2_b32 v[66:67], v66 offset1:1
	ds_read2_b32 v[68:69], v68 offset1:1
	v_add_u32_e32 v70, 0x201c8, v221
	v_add_u32_e32 v72, 0x20248, v221
	ds_read2_b32 v[70:71], v70 offset1:1
	ds_read2_b32 v[72:73], v72 offset1:1
	s_waitcnt lgkmcnt(0)
	v_add_f32_e32 v74, v74, v66
	v_add_f32_e32 v89, v90, v68
	v_add_f32_e32 v75, v75, v67
	v_add_f32_e32 v90, v91, v69
	v_max_f32_e32 v66, v74, v89
	v_max_f32_e32 v67, v75, v90
	v_max3_f32 v66, v88, v66, v67
	v_add_f32_e32 v76, v76, v70
	v_add_f32_e32 v88, v92, v72
	v_add_f32_e32 v77, v77, v71
	v_add_f32_e32 v91, v93, v73
	v_max_f32_e32 v67, v76, v88
	v_max_f32_e32 v68, v77, v91
	v_max3_f32 v92, v66, v67, v68
	v_add_u32_e32 v66, 0x201e0, v221
	v_add_u32_e32 v68, 0x20260, v221
	ds_read2_b32 v[66:67], v66 offset1:1
	ds_read2_b32 v[68:69], v68 offset1:1
	v_add_u32_e32 v70, 0x201e8, v221
	v_add_u32_e32 v72, 0x20268, v221
	ds_read2_b32 v[70:71], v70 offset1:1
	ds_read2_b32 v[72:73], v72 offset1:1
	s_waitcnt lgkmcnt(0)
	v_add_f32_e32 v66, v78, v66
	v_add_f32_e32 v68, v94, v68
	v_add_f32_e32 v67, v79, v67
	v_add_f32_e32 v69, v95, v69
	v_max_f32_e32 v78, v66, v68
	v_max_f32_e32 v79, v67, v69
	v_add_f32_e32 v70, v80, v70
	v_add_f32_e32 v72, v96, v72
	v_add_f32_e32 v71, v81, v71
	v_add_f32_e32 v73, v97, v73
	v_max3_f32 v78, v92, v78, v79
	v_max_f32_e32 v79, v70, v72
	v_max_f32_e32 v80, v71, v73
	v_max3_f32 v78, v78, v79, v80
	v_and_b32_e32 v80, 64, v214
	v_xor_b32_e32 v79, 32, v214
	v_add_u32_e32 v80, 64, v80
	v_cmp_lt_i32_e32 vcc, v79, v80
	s_nop 1
	v_cndmask_b32_e32 v79, v214, v79, vcc
	v_lshlrev_b32_e32 v79, 2, v79
	ds_bpermute_b32 v80, v79, v78
	s_waitcnt lgkmcnt(0)
; DI void phase_attn(const Params& P, int l, LAS unsigned char* lds) {
;     ...
;                     pmax = fmaxf(pmax, __shfl_xor(pmax, 32));
;                     float mn = m_run, alpha = 1.f;
;                     if (!__all(pmax - m_run <= 8.f)) { mn = fmaxf(m_run, pmax); alpha = __builtin_amdgcn_exp2f(m_run - mn); m_run = mn; }
;                     float ps = 0.f;
; #pragma unroll
;                     for (int r = 0; r < 16; ++r) { p0[r] = __builtin_amdgcn_exp2f(p0[r] - mn); p1[r] = __builtin_amdgcn_exp2f(p1[r] - mn); ps += p0[r] + p1[r]; }
;                     ps += __shfl_xor(ps, 32);
;                     l_run = l_run * alpha + ps;
;                     bf16x8 pa0, pa1, pa2, pa3;
;     ...
;                     PK4(p0, 0, pa0); PK4(p0, 8, pa1); PK4(p1, 0, pa2); PK4(p1, 8, pa3);
;     ...
;                     if (__any(alpha < 1.f)) {
; #pragma unroll
;                         for (int d = 0; d < 4; ++d)
; #pragma unroll
;                             for (int r = 0; r < 16; ++r) o[d][r] *= alpha; }
	v_max_f32_e32 v80, v80, v80
	v_max_f32_e32 v78, v78, v80
	v_sub_f32_e32 v80, v78, v217
	v_cmp_ge_f32_e32 vcc, s58, v80
	s_cmp_eq_u64 vcc, exec
	v_max_f32_e32 v80, v217, v217
	v_max_f32_e32 v78, v80, v78
	s_cselect_b64 vcc, -1, 0
	v_sub_f32_e32 v80, v217, v78
	v_cndmask_b32_e32 v217, v78, v217, vcc
	v_sub_f32_e32 v78, v238, v217
	v_sub_f32_e32 v81, v230, v217
	v_exp_f32_e32 v78, v78
	v_exp_f32_e32 v81, v81
	v_sub_f32_e32 v92, v234, v217
	v_sub_f32_e32 v93, v231, v217
	v_exp_f32_e32 v92, v92
	v_exp_f32_e32 v93, v93
	v_sub_f32_e32 v96, v232, v217
	v_sub_f32_e32 v97, v235, v217
	v_exp_f32_e32 v96, v96
	v_exp_f32_e32 v97, v97
	v_sub_f32_e32 v230, v233, v217
	v_sub_f32_e32 v231, v236, v217
	v_exp_f32_e32 v230, v230
	v_exp_f32_e32 v231, v231
	v_sub_f32_e32 v232, v239, v217
	v_sub_f32_e32 v86, v86, v217
	v_sub_f32_e32 v82, v82, v217
	v_add_f32_e32 v94, v78, v81
	v_exp_f32_e32 v232, v232
	v_exp_f32_e32 v86, v86
	v_sub_f32_e32 v233, v240, v217
	v_sub_f32_e32 v87, v87, v217
	v_exp_f32_e32 v234, v82
	v_sub_f32_e32 v82, v84, v217
	v_add_f32_e32 v94, 0, v94
	v_add_f32_e32 v95, v92, v93
	v_exp_f32_e32 v233, v233
	v_exp_f32_e32 v87, v87
	v_exp_f32_e32 v235, v82
	v_sub_f32_e32 v82, v83, v217
	v_add_f32_e32 v94, v95, v94
	v_add_f32_e32 v95, v96, v97
	v_exp_f32_e32 v236, v82
	v_sub_f32_e32 v82, v85, v217
	v_add_f32_e32 v94, v95, v94
	v_add_f32_e32 v95, v230, v231
	v_exp_f32_e32 v85, v82
	v_sub_f32_e32 v74, v74, v217
	v_sub_f32_e32 v84, v89, v217
	v_add_f32_e32 v94, v95, v94
	v_add_f32_e32 v95, v232, v86
	v_exp_f32_e32 v74, v74
	v_exp_f32_e32 v89, v84
	v_sub_f32_e32 v75, v75, v217
	v_sub_f32_e32 v84, v90, v217
	v_add_f32_e32 v94, v95, v94
	v_add_f32_e32 v95, v233, v87
	v_exp_f32_e32 v75, v75
	v_exp_f32_e32 v90, v84
	v_sub_f32_e32 v76, v76, v217
	v_sub_f32_e32 v84, v88, v217
	v_sub_f32_e32 v66, v66, v217
	v_add_f32_e32 v82, v95, v94
	v_add_f32_e32 v83, v234, v235
	v_exp_f32_e32 v76, v76
	v_exp_f32_e32 v88, v84
	v_sub_f32_e32 v77, v77, v217
	v_sub_f32_e32 v84, v91, v217
	v_exp_f32_e32 v94, v66
	v_sub_f32_e32 v66, v68, v217
	v_add_f32_e32 v82, v83, v82
	v_add_f32_e32 v83, v236, v85
	v_exp_f32_e32 v77, v77
	v_exp_f32_e32 v91, v84
	v_exp_f32_e32 v95, v66
	v_sub_f32_e32 v66, v67, v217
	v_sub_f32_e32 v68, v70, v217
	v_add_f32_e32 v82, v83, v82
	v_add_f32_e32 v83, v74, v89
	v_exp_f32_e32 v237, v66
	v_sub_f32_e32 v66, v69, v217
	v_exp_f32_e32 v239, v68
	v_sub_f32_e32 v68, v72, v217
	v_add_f32_e32 v82, v83, v82
	v_add_f32_e32 v83, v75, v90
	v_exp_f32_e32 v238, v66
	v_exp_f32_e32 v240, v68
	v_sub_f32_e32 v68, v71, v217
	v_add_f32_e32 v82, v83, v82
	v_add_f32_e32 v83, v76, v88
	v_exp_f32_e32 v241, v68
	v_sub_f32_e32 v68, v73, v217
	v_add_f32_e32 v82, v83, v82
	v_add_f32_e32 v83, v77, v91
	v_exp_f32_e32 v242, v68
	v_add_f32_e32 v66, v83, v82
	v_add_f32_e32 v67, v94, v95
	v_add_f32_e32 v66, v67, v66
	v_add_f32_e32 v67, v237, v238
	v_add_f32_e32 v66, v67, v66
	v_add_f32_e32 v67, v239, v240
	v_add_f32_e32 v66, v67, v66
	v_add_f32_e32 v67, v241, v242
	v_exp_f32_e32 v80, v80
	v_add_f32_e32 v83, v67, v66
	ds_bpermute_b32 v84, v79, v83
	v_cvt_pk_bf16_f32 v66, v78, v92
	v_cndmask_b32_e64 v82, v80, 1.0, vcc
	v_cvt_pk_bf16_f32 v67, v96, v230
	v_cvt_pk_bf16_f32 v68, v232, v233
	v_cvt_pk_bf16_f32 v69, v234, v236
	v_cvt_pk_bf16_f32 v70, v74, v75
	v_cvt_pk_bf16_f32 v71, v76, v77
	v_cvt_pk_bf16_f32 v72, v94, v237
	v_cvt_pk_bf16_f32 v73, v239, v241
	v_cvt_pk_bf16_f32 v74, v81, v93
	v_cvt_pk_bf16_f32 v75, v97, v231
	v_cvt_pk_bf16_f32 v76, v86, v87
	v_cvt_pk_bf16_f32 v77, v235, v85
	v_cvt_pk_bf16_f32 v78, v89, v90
	v_cvt_pk_bf16_f32 v79, v88, v91
	v_cvt_pk_bf16_f32 v80, v95, v238
	v_cvt_pk_bf16_f32 v81, v240, v242
	s_nop 0
	v_permlane32_swap_b32_e32 v66, v68
	v_permlane32_swap_b32_e32 v67, v69
	v_permlane32_swap_b32_e32 v70, v72
	v_permlane32_swap_b32_e32 v71, v73
	v_permlane32_swap_b32_e32 v74, v76
	v_permlane32_swap_b32_e32 v75, v77
	v_permlane32_swap_b32_e32 v78, v80
	v_permlane32_swap_b32_e32 v79, v81
	v_cmp_gt_f32_e32 vcc, 1.0, v82
	s_cbranch_vccz .LBB0_1051
	v_pk_mul_f32 v[64:65], v[64:65], v[82:83] op_sel_hi:[1,0]
	v_pk_mul_f32 v[62:63], v[62:63], v[82:83] op_sel_hi:[1,0]
	v_pk_mul_f32 v[60:61], v[60:61], v[82:83] op_sel_hi:[1,0]
	v_pk_mul_f32 v[58:59], v[58:59], v[82:83] op_sel_hi:[1,0]
	v_pk_mul_f32 v[56:57], v[56:57], v[82:83] op_sel_hi:[1,0]
	v_pk_mul_f32 v[54:55], v[54:55], v[82:83] op_sel_hi:[1,0]
	v_pk_mul_f32 v[52:53], v[52:53], v[82:83] op_sel_hi:[1,0]
	v_pk_mul_f32 v[50:51], v[50:51], v[82:83] op_sel_hi:[1,0]
	v_pk_mul_f32 v[48:49], v[48:49], v[82:83] op_sel_hi:[1,0]
	v_pk_mul_f32 v[46:47], v[46:47], v[82:83] op_sel_hi:[1,0]
	v_pk_mul_f32 v[44:45], v[44:45], v[82:83] op_sel_hi:[1,0]
	v_pk_mul_f32 v[42:43], v[42:43], v[82:83] op_sel_hi:[1,0]
	v_pk_mul_f32 v[40:41], v[40:41], v[82:83] op_sel_hi:[1,0]
	v_pk_mul_f32 v[38:39], v[38:39], v[82:83] op_sel_hi:[1,0]
	v_pk_mul_f32 v[36:37], v[36:37], v[82:83] op_sel_hi:[1,0]
	v_pk_mul_f32 v[34:35], v[34:35], v[82:83] op_sel_hi:[1,0]
	v_pk_mul_f32 v[32:33], v[32:33], v[82:83] op_sel_hi:[1,0]
	v_pk_mul_f32 v[30:31], v[30:31], v[82:83] op_sel_hi:[1,0]
	v_pk_mul_f32 v[28:29], v[28:29], v[82:83] op_sel_hi:[1,0]
	v_pk_mul_f32 v[26:27], v[26:27], v[82:83] op_sel_hi:[1,0]
	v_pk_mul_f32 v[24:25], v[24:25], v[82:83] op_sel_hi:[1,0]
	v_pk_mul_f32 v[22:23], v[22:23], v[82:83] op_sel_hi:[1,0]
	v_pk_mul_f32 v[20:21], v[20:21], v[82:83] op_sel_hi:[1,0]
	v_pk_mul_f32 v[18:19], v[18:19], v[82:83] op_sel_hi:[1,0]
	v_pk_mul_f32 v[16:17], v[16:17], v[82:83] op_sel_hi:[1,0]
	v_pk_mul_f32 v[14:15], v[14:15], v[82:83] op_sel_hi:[1,0]
	v_pk_mul_f32 v[12:13], v[12:13], v[82:83] op_sel_hi:[1,0]
	v_pk_mul_f32 v[10:11], v[10:11], v[82:83] op_sel_hi:[1,0]
	v_pk_mul_f32 v[8:9], v[8:9], v[82:83] op_sel_hi:[1,0]
	v_pk_mul_f32 v[6:7], v[6:7], v[82:83] op_sel_hi:[1,0]
	v_pk_mul_f32 v[4:5], v[4:5], v[82:83] op_sel_hi:[1,0]
	v_pk_mul_f32 v[2:3], v[2:3], v[82:83] op_sel_hi:[1,0]

; #define LAS __attribute__((address_space(3)))
; DI int crow(int r, int hi) { return (r & 3) + 8 * (r >> 2) + 4 * hi; }
; DI void qkt(f32x16& p0, f32x16& p1, const LAS char* Ks, const bf16x8* qr, int r32, int hi) {
;     for (int i = 0; i < 16; ++i) { p0[i] = 0.f; p1[i] = 0.f; }
; #pragma unroll
;     for (int d0 = 0; d0 < 8; ++d0) { const int cb = (d0 * 16 + hi * 8) * 2;
;         const bf16x8 b0 = *(const LAS bf16x8*)(Ks + KSWZ(r32, cb));
;         const bf16x8 b1 = *(const LAS bf16x8*)(Ks + KSWZ(32 + r32, cb));
;         p0 = __builtin_amdgcn_mfma_f32_32x32x16_bf16(b0, qr[d0], p0, 0, 0, 0);
;         p1 = __builtin_amdgcn_mfma_f32_32x32x16_bf16(b1, qr[d0], p1, 0, 0, 0); }
; }
; DI void phase_attn(const Params& P, int l, LAS unsigned char* lds) {
;     ...
;                 const int kp0 = (n - 1 + t) * 128 + h2 * 64;
;                 if (kp0 + 63 >= rq - 128 && kp0 <= rq + 159) {
;                     f32x16 p0, p1;
;                     qkt(p0, p1, Bf + h2 * 16384, qr, r32, hi);
;                     const LAS float* tq = tg + (kp0 - rq);
;                     float pmax = -1e30f;
; #pragma unroll
;                     for (int r = 0; r < 16; ++r) { p0[r] += tq[crow(r, hi)]; p1[r] += tq[32 + crow(r, hi)]; pmax = fmaxf(pmax, fmaxf(p0[r], p1[r])); }
;                     pmax = fmaxf(pmax, __shfl_xor(pmax, 32));
.LBB0_1052:
	s_add_i32 s30, s28, 64
	s_addk_i32 s28, 0x7f
	s_cmp_lt_i32 s28, s86
	s_cselect_b64 s[28:29], -1, 0
	s_cmp_gt_i32 s30, s87
	s_cselect_b64 s[30:31], -1, 0
	s_or_b64 s[28:29], s[28:29], s[30:31]
	s_and_b64 vcc, exec, s[28:29]
	s_cbranch_vccnz .LBB0_1036
	ds_read_b128 v[66:69], v229 offset:16384
	ds_read_b128 v[82:85], v229 offset:24576
	ds_read_b128 v[230:233], v228 offset:16384
	ds_read_b128 v[234:237], v228 offset:24576
	ds_read_b128 v[246:249], v227 offset:16384
	ds_read_b128 v[250:253], v227 offset:24576
	s_waitcnt lgkmcnt(4)
	v_mfma_f32_32x32x16_bf16 v[66:81], v[66:69], v[126:129], 0
	v_mfma_f32_32x32x16_bf16 v[82:97], v[82:85], v[126:129], 0
	s_waitcnt lgkmcnt(2)
	v_mfma_f32_32x32x16_bf16 v[66:81], v[230:233], v[122:125], v[66:81]
	v_mfma_f32_32x32x16_bf16 v[82:97], v[234:237], v[122:125], v[82:97]
	ds_read_b128 v[228:231], v226 offset:16384
	ds_read_b128 v[232:235], v226 offset:24576
	s_waitcnt lgkmcnt(2)
	v_mfma_f32_32x32x16_bf16 v[66:81], v[246:249], v[118:121], v[66:81]
	v_mfma_f32_32x32x16_bf16 v[82:97], v[250:253], v[118:121], v[82:97]
	ds_read_b128 v[246:249], v225 offset:16384
	ds_read_b128 v[250:253], v225 offset:24576
	s_waitcnt lgkmcnt(2)
	v_mfma_f32_32x32x16_bf16 v[66:81], v[228:231], v[114:117], v[66:81]
	v_mfma_f32_32x32x16_bf16 v[82:97], v[232:235], v[114:117], v[82:97]
	ds_read_b128 v[226:229], v224 offset:16384
	ds_read_b128 v[230:233], v224 offset:24576
	s_waitcnt lgkmcnt(2)
	v_mfma_f32_32x32x16_bf16 v[66:81], v[246:249], v[110:113], v[66:81]
	v_mfma_f32_32x32x16_bf16 v[82:97], v[250:253], v[110:113], v[82:97]
	ds_read_b128 v[246:249], v223 offset:16384
	ds_read_b128 v[250:253], v223 offset:24576
	s_waitcnt lgkmcnt(2)
	v_mfma_f32_32x32x16_bf16 v[66:81], v[226:229], v[106:109], v[66:81]
	v_mfma_f32_32x32x16_bf16 v[82:97], v[230:233], v[106:109], v[82:97]
	ds_read_b128 v[224:227], v222 offset:16384
	ds_read_b128 v[228:231], v222 offset:24576
	v_add_u32_e32 v232, 0x20308, v221
	s_waitcnt lgkmcnt(2)
	v_mfma_f32_32x32x16_bf16 v[66:81], v[246:249], v[102:105], v[66:81]
	v_mfma_f32_32x32x16_bf16 v[82:97], v[250:253], v[102:105], v[82:97]
	v_add_u32_e32 v222, 0x20280, v221
	ds_read2_b32 v[222:223], v222 offset1:1
	s_waitcnt lgkmcnt(0)
	v_mfma_f32_32x32x16_bf16 v[66:81], v[224:227], v[98:101], v[66:81]
	v_add_u32_e32 v224, 0x20300, v221
	v_add_u32_e32 v226, 0x20288, v221
	ds_read2_b32 v[224:225], v224 offset1:1
	ds_read2_b32 v[226:227], v226 offset1:1
	ds_read2_b32 v[232:233], v232 offset1:1
	s_nop 6
	v_add_f32_e32 v222, v66, v222
	v_mfma_f32_32x32x16_bf16 v[82:97], v[228:231], v[98:101], v[82:97]
	v_add_f32_e32 v223, v67, v223
	s_waitcnt lgkmcnt(0)
	v_add_f32_e32 v226, v68, v226
	v_add_f32_e32 v227, v69, v227
	s_nop 7
	v_add_f32_e32 v224, v82, v224
	v_add_f32_e32 v225, v83, v225
	v_max_f32_e32 v66, v222, v224
	v_max_f32_e32 v67, v223, v225
	v_add_f32_e32 v228, v84, v232
	v_add_f32_e32 v229, v85, v233
	v_max3_f32 v66, v66, s57, v67
	v_max_f32_e32 v67, v226, v228
	v_max_f32_e32 v68, v227, v229
	v_max3_f32 v230, v66, v67, v68
	v_add_u32_e32 v66, 0x202a0, v221
	v_add_u32_e32 v68, 0x20320, v221
	ds_read2_b32 v[66:67], v66 offset1:1
	ds_read2_b32 v[68:69], v68 offset1:1
	v_add_u32_e32 v82, 0x202a8, v221
	v_add_u32_e32 v84, 0x20328, v221
	ds_read2_b32 v[82:83], v82 offset1:1
	ds_read2_b32 v[84:85], v84 offset1:1
	s_waitcnt lgkmcnt(0)
	v_add_f32_e32 v231, v70, v66
	v_add_f32_e32 v86, v86, v68
	v_add_f32_e32 v232, v71, v67
	v_add_f32_e32 v87, v87, v69
	v_max_f32_e32 v66, v231, v86
	v_max_f32_e32 v67, v232, v87
	v_add_f32_e32 v82, v72, v82
	v_add_f32_e32 v84, v88, v84
	v_add_f32_e32 v83, v73, v83
	v_add_f32_e32 v85, v89, v85
	v_max3_f32 v66, v230, v66, v67
	v_max_f32_e32 v67, v82, v84
	v_max_f32_e32 v68, v83, v85
	v_max3_f32 v88, v66, v67, v68
	v_add_u32_e32 v66, 0x202c0, v221
	v_add_u32_e32 v68, 0x20340, v221
	ds_read2_b32 v[66:67], v66 offset1:1
	ds_read2_b32 v[68:69], v68 offset1:1
	v_add_u32_e32 v70, 0x202c8, v221
	v_add_u32_e32 v72, 0x20348, v221
	ds_read2_b32 v[70:71], v70 offset1:1
	ds_read2_b32 v[72:73], v72 offset1:1
	s_waitcnt lgkmcnt(0)
	v_add_f32_e32 v74, v74, v66
	v_add_f32_e32 v89, v90, v68
	v_add_f32_e32 v75, v75, v67
	v_add_f32_e32 v90, v91, v69
	v_max_f32_e32 v66, v74, v89
	v_max_f32_e32 v67, v75, v90
	v_max3_f32 v66, v88, v66, v67
	v_add_f32_e32 v76, v76, v70
	v_add_f32_e32 v88, v92, v72
	v_add_f32_e32 v77, v77, v71
	v_add_f32_e32 v91, v93, v73
	v_max_f32_e32 v67, v76, v88
	v_max_f32_e32 v68, v77, v91
	v_max3_f32 v92, v66, v67, v68
	v_add_u32_e32 v66, 0x202e0, v221
	v_add_u32_e32 v68, 0x20360, v221
	ds_read2_b32 v[66:67], v66 offset1:1
	ds_read2_b32 v[68:69], v68 offset1:1
	v_add_u32_e32 v70, 0x202e8, v221
	v_add_u32_e32 v72, 0x20368, v221
	ds_read2_b32 v[70:71], v70 offset1:1
	ds_read2_b32 v[72:73], v72 offset1:1
	s_waitcnt lgkmcnt(0)
	v_add_f32_e32 v66, v78, v66
	v_add_f32_e32 v68, v94, v68
	v_add_f32_e32 v67, v79, v67
	v_add_f32_e32 v69, v95, v69
	v_max_f32_e32 v78, v66, v68
	v_max_f32_e32 v79, v67, v69
	v_add_f32_e32 v70, v80, v70
	v_add_f32_e32 v72, v96, v72
	v_add_f32_e32 v71, v81, v71
	v_add_f32_e32 v73, v97, v73
	v_max3_f32 v78, v92, v78, v79
	v_max_f32_e32 v79, v70, v72
	v_max_f32_e32 v80, v71, v73
	v_max3_f32 v78, v78, v79, v80
	v_and_b32_e32 v80, 64, v214
	v_xor_b32_e32 v79, 32, v214
	v_add_u32_e32 v80, 64, v80
	v_cmp_lt_i32_e32 vcc, v79, v80
	s_nop 1
	v_cndmask_b32_e32 v79, v214, v79, vcc
	v_lshlrev_b32_e32 v79, 2, v79
	ds_bpermute_b32 v80, v79, v78
	s_waitcnt lgkmcnt(0)
; DI void phase_attn(const Params& P, int l, LAS unsigned char* lds) {
;     ...
;                     pmax = fmaxf(pmax, __shfl_xor(pmax, 32));
;                     float mn = m_run, alpha = 1.f;
;                     if (!__all(pmax - m_run <= 8.f)) { mn = fmaxf(m_run, pmax); alpha = __builtin_amdgcn_exp2f(m_run - mn); m_run = mn; }
;                     float ps = 0.f;
; #pragma unroll
;                     for (int r = 0; r < 16; ++r) { p0[r] = __builtin_amdgcn_exp2f(p0[r] - mn); p1[r] = __builtin_amdgcn_exp2f(p1[r] - mn); ps += p0[r] + p1[r]; }
;                     ps += __shfl_xor(ps, 32);
;                     l_run = l_run * alpha + ps;
;                     bf16x8 pa0, pa1, pa2, pa3;
;     ...
;                     PK4(p0, 0, pa0); PK4(p0, 8, pa1); PK4(p1, 0, pa2); PK4(p1, 8, pa3);
;     ...
;                     if (__any(alpha < 1.f)) {
; #pragma unroll
;                         for (int d = 0; d < 4; ++d)
; #pragma unroll
;                             for (int r = 0; r < 16; ++r) o[d][r] *= alpha; }
	v_max_f32_e32 v80, v80, v80
	v_max_f32_e32 v78, v78, v80
	v_sub_f32_e32 v80, v78, v217
	v_cmp_ge_f32_e32 vcc, s58, v80
	s_cmp_eq_u64 vcc, exec
	v_max_f32_e32 v80, v217, v217
	v_max_f32_e32 v78, v80, v78
	s_cselect_b64 vcc, -1, 0
	v_sub_f32_e32 v80, v217, v78
	v_cndmask_b32_e32 v217, v78, v217, vcc
	v_sub_f32_e32 v78, v222, v217
	v_sub_f32_e32 v81, v224, v217
	v_exp_f32_e32 v78, v78
	v_exp_f32_e32 v81, v81
	v_sub_f32_e32 v92, v223, v217
	v_sub_f32_e32 v93, v225, v217
	v_exp_f32_e32 v92, v92
	v_exp_f32_e32 v93, v93
	v_sub_f32_e32 v96, v226, v217
	v_sub_f32_e32 v97, v228, v217
	v_exp_f32_e32 v96, v96
	v_exp_f32_e32 v97, v97
	v_sub_f32_e32 v221, v227, v217
	v_sub_f32_e32 v222, v229, v217
	v_exp_f32_e32 v221, v221
	v_exp_f32_e32 v222, v222
	v_sub_f32_e32 v223, v231, v217
	v_sub_f32_e32 v86, v86, v217
	v_sub_f32_e32 v82, v82, v217
	v_add_f32_e32 v94, v78, v81
	v_exp_f32_e32 v223, v223
	v_exp_f32_e32 v86, v86
	v_sub_f32_e32 v224, v232, v217
	v_sub_f32_e32 v87, v87, v217
	v_exp_f32_e32 v225, v82
	v_sub_f32_e32 v82, v84, v217
	v_add_f32_e32 v94, 0, v94
	v_add_f32_e32 v95, v92, v93
	v_exp_f32_e32 v224, v224
	v_exp_f32_e32 v87, v87
	v_exp_f32_e32 v226, v82
	v_sub_f32_e32 v82, v83, v217
	v_add_f32_e32 v94, v95, v94
	v_add_f32_e32 v95, v96, v97
	v_exp_f32_e32 v227, v82
	v_sub_f32_e32 v82, v85, v217
	v_add_f32_e32 v94, v95, v94
	v_add_f32_e32 v95, v221, v222
	v_exp_f32_e32 v85, v82
	v_sub_f32_e32 v74, v74, v217
	v_sub_f32_e32 v84, v89, v217
	v_add_f32_e32 v94, v95, v94
	v_add_f32_e32 v95, v223, v86
	v_exp_f32_e32 v74, v74
	v_exp_f32_e32 v89, v84
	v_sub_f32_e32 v75, v75, v217
	v_sub_f32_e32 v84, v90, v217
	v_add_f32_e32 v94, v95, v94
	v_add_f32_e32 v95, v224, v87
	v_exp_f32_e32 v75, v75
	v_exp_f32_e32 v90, v84
	v_sub_f32_e32 v76, v76, v217
	v_sub_f32_e32 v84, v88, v217
	v_sub_f32_e32 v66, v66, v217
	v_add_f32_e32 v82, v95, v94
	v_add_f32_e32 v83, v225, v226
	v_exp_f32_e32 v76, v76
	v_exp_f32_e32 v88, v84
	v_sub_f32_e32 v77, v77, v217
	v_sub_f32_e32 v84, v91, v217
	v_exp_f32_e32 v94, v66
	v_sub_f32_e32 v66, v68, v217
	v_add_f32_e32 v82, v83, v82
	v_add_f32_e32 v83, v227, v85
	v_exp_f32_e32 v77, v77
	v_exp_f32_e32 v91, v84
	v_exp_f32_e32 v95, v66
	v_sub_f32_e32 v66, v67, v217
	v_sub_f32_e32 v68, v70, v217
	v_add_f32_e32 v82, v83, v82
	v_add_f32_e32 v83, v74, v89
	v_exp_f32_e32 v228, v66
	v_sub_f32_e32 v66, v69, v217
	v_exp_f32_e32 v230, v68
	v_sub_f32_e32 v68, v72, v217
	v_add_f32_e32 v82, v83, v82
	v_add_f32_e32 v83, v75, v90
	v_exp_f32_e32 v229, v66
	v_exp_f32_e32 v231, v68
	v_sub_f32_e32 v68, v71, v217
	v_add_f32_e32 v82, v83, v82
	v_add_f32_e32 v83, v76, v88
	v_exp_f32_e32 v232, v68
	v_sub_f32_e32 v68, v73, v217
	v_add_f32_e32 v82, v83, v82
	v_add_f32_e32 v83, v77, v91
	v_exp_f32_e32 v233, v68
	v_add_f32_e32 v66, v83, v82
	v_add_f32_e32 v67, v94, v95
	v_add_f32_e32 v66, v67, v66
	v_add_f32_e32 v67, v228, v229
	v_add_f32_e32 v66, v67, v66
	v_add_f32_e32 v67, v230, v231
	v_add_f32_e32 v66, v67, v66
	v_add_f32_e32 v67, v232, v233
	v_exp_f32_e32 v80, v80
	v_add_f32_e32 v83, v67, v66
	ds_bpermute_b32 v84, v79, v83
	v_cvt_pk_bf16_f32 v66, v78, v92
	v_cndmask_b32_e64 v82, v80, 1.0, vcc
	v_cvt_pk_bf16_f32 v67, v96, v221
	v_cvt_pk_bf16_f32 v68, v223, v224
	v_cvt_pk_bf16_f32 v69, v225, v227
	v_cvt_pk_bf16_f32 v70, v74, v75
	v_cvt_pk_bf16_f32 v71, v76, v77
	v_cvt_pk_bf16_f32 v72, v94, v228
	v_cvt_pk_bf16_f32 v73, v230, v232
	v_cvt_pk_bf16_f32 v74, v81, v93
	v_cvt_pk_bf16_f32 v75, v97, v222
	v_cvt_pk_bf16_f32 v76, v86, v87
	v_cvt_pk_bf16_f32 v77, v226, v85
	v_cvt_pk_bf16_f32 v78, v89, v90
	v_cvt_pk_bf16_f32 v79, v88, v91
	v_cvt_pk_bf16_f32 v80, v95, v229
	v_cvt_pk_bf16_f32 v81, v231, v233
	s_nop 0
	v_permlane32_swap_b32_e32 v66, v68
	v_permlane32_swap_b32_e32 v67, v69
	v_permlane32_swap_b32_e32 v70, v72
	v_permlane32_swap_b32_e32 v71, v73
	v_permlane32_swap_b32_e32 v74, v76
	v_permlane32_swap_b32_e32 v75, v77
	v_permlane32_swap_b32_e32 v78, v80
	v_permlane32_swap_b32_e32 v79, v81
	v_cmp_gt_f32_e32 vcc, 1.0, v82
	s_cbranch_vccz .LBB0_1035
	v_pk_mul_f32 v[64:65], v[64:65], v[82:83] op_sel_hi:[1,0]
	v_pk_mul_f32 v[62:63], v[62:63], v[82:83] op_sel_hi:[1,0]
	v_pk_mul_f32 v[60:61], v[60:61], v[82:83] op_sel_hi:[1,0]
	v_pk_mul_f32 v[58:59], v[58:59], v[82:83] op_sel_hi:[1,0]
	v_pk_mul_f32 v[56:57], v[56:57], v[82:83] op_sel_hi:[1,0]
	v_pk_mul_f32 v[54:55], v[54:55], v[82:83] op_sel_hi:[1,0]
	v_pk_mul_f32 v[52:53], v[52:53], v[82:83] op_sel_hi:[1,0]
	v_pk_mul_f32 v[50:51], v[50:51], v[82:83] op_sel_hi:[1,0]
	v_pk_mul_f32 v[48:49], v[48:49], v[82:83] op_sel_hi:[1,0]
	v_pk_mul_f32 v[46:47], v[46:47], v[82:83] op_sel_hi:[1,0]
	v_pk_mul_f32 v[44:45], v[44:45], v[82:83] op_sel_hi:[1,0]
	v_pk_mul_f32 v[42:43], v[42:43], v[82:83] op_sel_hi:[1,0]
	v_pk_mul_f32 v[40:41], v[40:41], v[82:83] op_sel_hi:[1,0]
	v_pk_mul_f32 v[38:39], v[38:39], v[82:83] op_sel_hi:[1,0]
	v_pk_mul_f32 v[36:37], v[36:37], v[82:83] op_sel_hi:[1,0]
	v_pk_mul_f32 v[34:35], v[34:35], v[82:83] op_sel_hi:[1,0]
	v_pk_mul_f32 v[32:33], v[32:33], v[82:83] op_sel_hi:[1,0]
	v_pk_mul_f32 v[30:31], v[30:31], v[82:83] op_sel_hi:[1,0]
	v_pk_mul_f32 v[28:29], v[28:29], v[82:83] op_sel_hi:[1,0]
	v_pk_mul_f32 v[26:27], v[26:27], v[82:83] op_sel_hi:[1,0]
	v_pk_mul_f32 v[24:25], v[24:25], v[82:83] op_sel_hi:[1,0]
	v_pk_mul_f32 v[22:23], v[22:23], v[82:83] op_sel_hi:[1,0]
	v_pk_mul_f32 v[20:21], v[20:21], v[82:83] op_sel_hi:[1,0]
	v_pk_mul_f32 v[18:19], v[18:19], v[82:83] op_sel_hi:[1,0]
	v_pk_mul_f32 v[16:17], v[16:17], v[82:83] op_sel_hi:[1,0]
	v_pk_mul_f32 v[14:15], v[14:15], v[82:83] op_sel_hi:[1,0]
	v_pk_mul_f32 v[12:13], v[12:13], v[82:83] op_sel_hi:[1,0]
	v_pk_mul_f32 v[10:11], v[10:11], v[82:83] op_sel_hi:[1,0]
	v_pk_mul_f32 v[8:9], v[8:9], v[82:83] op_sel_hi:[1,0]
	v_pk_mul_f32 v[6:7], v[6:7], v[82:83] op_sel_hi:[1,0]
	v_pk_mul_f32 v[4:5], v[4:5], v[82:83] op_sel_hi:[1,0]
	v_pk_mul_f32 v[2:3], v[2:3], v[82:83] op_sel_hi:[1,0]
	s_branch .LBB0_1035

; #define PG8_STAGE(bufoff, gbase, voff) do { _Pragma("unroll") for (int _i = 0; _i < 2; ++_i) \
;         __builtin_amdgcn_global_load_lds((const unsigned*)((const char*)(gbase) + (voff)[_i]), (PG8_LAS unsigned*)(lds + (bufoff) + ldsw + _i * 8192), 16, 0, 0); } while (0)
; #define PG8_WAIT_V(n) asm volatile("s_waitcnt vmcnt(" #n ")" ::: "memory")
; #define PG8_BAR __builtin_amdgcn_s_barrier()
; template <class Epi, class Sched, bool ALIGN_EPI = false, bool SP2 = false>
; __device__ __forceinline__ void gemm_phase(PG8_LAS unsigned char* lds, const Gemm g, const Sched& S, const Epi& E) {
;     ...
;     const char* cA = (const char*)g.A + (size_t)cur.pm * tstep; const char* cB = (const char*)g.Bt + (size_t)cur.pn * tstep;
;     S.a_ready(cur);
;     if constexpr (SP2) {
;         PG8_STAGE(PG8_SB(0, 0), cB, voffB); PG8_STAGE(PG8_SB(0, 1), cB + hstep, voffB); PG8_STAGE(PG8_SA(0, 0), cA, voffA); PG8_STAGE(PG8_SA(0, 1), cA + hstep, voffA);
;         if (wr == 1) PG8_BAR;
;         PG8_WAIT_V(2); PG8_BAR;
;         PG8_STAGE(PG8_SB(1, 0), cB + kstep, voffB); PG8_STAGE(PG8_SA(1, 0), cA + kstep, voffA); PG8_STAGE(PG8_SB(1, 1), cB + hstep + kstep, voffB);
;         PG8_WAIT_V(6); PG8_BAR;
.LBB0_1171:
	s_add_u32 s8, s50, 0x10440000
	s_addc_u32 s9, s51, 0
	s_add_u32 s10, s50, 0x29940000
	s_mov_b64 s[12:13], 0x80
	s_addc_u32 s11, s51, 0
	s_and_b32 s44, s1, 3
	s_add_i32 m0, s39, 0x18000
	v_lshl_add_u64 v[8:9], v[8:9], 0, s[12:13]
	s_ashr_i32 s43, s94, 31
	s_lshl_b32 s16, s3, 13
	s_lshl_b32 s17, s44, 12
	s_waitcnt vmcnt(2)
	s_barrier
	global_load_lds_dwordx4 v[8:9], off
	v_lshl_add_u64 v[6:7], v[6:7], 0, s[12:13]
	s_add_i32 m0, s39, 0x1a000
	s_add_i32 s45, s39, 0x8000
	s_add_i32 s52, s39, 0xa000
	global_load_lds_dwordx4 v[6:7], off
	v_lshl_add_u64 v[2:3], v[2:3], 0, s[12:13]
	s_mov_b32 m0, s45
	s_add_u32 s14, s26, 0x80080
	global_load_lds_dwordx4 v[2:3], off
	v_lshl_add_u64 v[2:3], v[4:5], 0, s[12:13]
	s_mov_b32 m0, s52
	s_addc_u32 s15, s27, 0
	global_load_lds_dwordx4 v[2:3], off
	s_add_i32 m0, s39, 0x1c000
	v_lshl_add_u64 v[2:3], s[14:15], 0, v[132:133]
	global_load_lds_dwordx4 v[2:3], off
	v_lshl_add_u64 v[2:3], s[14:15], 0, v[136:137]
	s_add_i32 m0, s39, 0x1e000
	v_lshlrev_b32_e32 v6, 6, v1
	global_load_lds_dwordx4 v[2:3], off
	v_bfe_u32 v3, v1, 4, 2
	v_lshlrev_b32_e32 v5, 4, v3
	s_movk_i32 s1, 0x3c0
	v_lshlrev_b32_e32 v4, 3, v3
	v_and_or_b32 v6, v6, s1, v5
	s_sext_i32_i8 s56, s0
	v_cmp_eq_u32_e64 s[0:1], 0, v3
	v_lshlrev_b32_e32 v3, 9, v1
	v_lshl_or_b32 v152, s44, 5, v4
	v_and_b32_e32 v3, 0x70000, v3
	v_lshlrev_b32_e32 v4, 12, v12
	v_and_b32_e32 v2, 15, v1
	v_lshlrev_b32_e32 v7, 2, v1
	v_or3_b32 v3, v10, v3, v4
	v_and_b32_e32 v7, 32, v7
	v_lshl_or_b32 v150, s3, 6, v2
	v_lshl_or_b32 v2, v2, 6, v5
	v_add_u32_e32 v138, v3, v11
	v_lshlrev_b32_e32 v3, 5, v13
	v_bitop3_b32 v2, v2, s16, v7 bitop3:0xde
	s_waitcnt vmcnt(0)
	s_cmpk_lt_u32 s2, 0x100
	v_and_b32_e32 v3, 0xf0000, v3
	v_bitop3_b32 v151, s17, v6, v7 bitop3:0xf6
	s_cselect_b64 s[14:15], -1, 0
	v_or3_b32 v3, v10, v3, v4
	s_add_i32 s53, 0, 0x10000
	s_add_i32 s54, 0, 0x14000
	v_add_u32_e32 v155, 0, v2
	v_mbcnt_lo_u32_b32 v2, -1, 0
	v_mov_b32_e32 v139, v133
	v_add_u32_e32 v140, v3, v11
	v_mov_b32_e32 v141, v133
	v_mov_b64_e32 v[142:143], 0x500
	v_mov_b64_e32 v[144:145], 0x4ff
	v_add_u32_e32 v153, s53, v151
	v_add_u32_e32 v154, s54, v151
	v_mbcnt_hi_u32_b32 v156, -1, v2
	s_mov_b32 s55, 0
	s_barrier
	s_branch .LBB0_1174

; template <class Epi, class Sched, bool ALIGN_EPI = false, bool SP2 = false>
; __device__ __forceinline__ void gemm_phase(PG8_LAS unsigned char* lds, const Gemm g, const Sched& S, const Epi& E) {
;     const int tid = threadIdx.x, wid = __builtin_amdgcn_readfirstlane(tid >> 6), lane = tid & 63, wr = wid >> 2, wc = wid & 3, fr = lane & 15, fq = lane >> 4;
;     const int K = g.K, nt = K / BK;
;     unsigned voffA[2], voffB[2];
; #pragma unroll
;     for (int i = 0; i < 2; ++i) { int R, C; stage_rc(tid * 16 + i * 8192, R, C); const int Rb = Epi::PERM ? ((R & ~31) + perm32(R & 31)) : R;
;         voffA[i] = (unsigned)(R * K + C) * 2u; voffB[i] = (unsigned)(Rb * K + C) * 2u; }
;     const size_t kstep = (size_t)(BK * 2);
;     const size_t hstep = (size_t)HALF * K * 2;
;     const size_t tstep = 2 * hstep;
;     const unsigned ldsw = (unsigned)wid * 1024u;
;     const int aoff = lds_byte(wr * 64 + fr, fq * 8), boff = lds_byte(wc * 32 + fr, fq * 8);
;     ...
; #pragma unroll
;         for (int a = 0; a < 2; ++a)
; #pragma unroll
;             for (int b = 0; b < 2; ++b)
; #pragma unroll
;                 for (int m = 0; m < 4; ++m)
; #pragma unroll
;                     for (int n = 0; n < 2; ++n) acc[a][b][m][n] = (f32x4){0.f, 0.f, 0.f, 0.f};
;         cur = nxt; cA = nA; cB = nB; ++ui;
.LBB0_1176:
	s_ashr_i32 s19, s18, 31
	s_lshl_b64 s[20:21], s[18:19], 20
	s_add_u32 s20, s34, s20
	s_addc_u32 s21, s35, s21
	s_and_b64 s[22:23], s[2:3], exec
	s_cselect_b32 s19, s21, s25
	s_cselect_b32 s57, s20, s24
	s_ashr_i32 s17, s16, 31
	s_lshl_b64 s[22:23], s[16:17], 20
	s_add_u32 s22, s30, s22
	s_addc_u32 s23, s31, s23
	s_and_b64 s[28:29], s[2:3], exec
	s_cselect_b32 s17, s23, s27
	s_cselect_b32 s58, s22, s26
	s_add_u32 s24, s24, 0x80080
	s_addc_u32 s25, s25, 0
	s_add_u32 s59, s26, 0x100
	v_mov_b32_e32 v2, 0
	s_addc_u32 s64, s27, 0
	s_mov_b32 s65, -2
	v_mov_b32_e32 v3, v2
	v_mov_b32_e32 v4, v2
	v_mov_b32_e32 v5, v2
	v_mov_b32_e32 v6, v2
	s_waitcnt lgkmcnt(0)
	v_mov_b32_e32 v7, v2
	v_mov_b32_e32 v8, v2
	v_mov_b32_e32 v9, v2
	v_mov_b32_e32 v18, v2
	v_mov_b32_e32 v19, v2
	v_mov_b32_e32 v20, v2
	v_mov_b32_e32 v21, v2
	v_mov_b32_e32 v22, v2
	v_mov_b32_e32 v23, v2
	v_mov_b32_e32 v24, v2
	v_mov_b32_e32 v25, v2
	v_mov_b32_e32 v34, v2
	v_mov_b32_e32 v35, v2
	v_mov_b32_e32 v36, v2
	v_mov_b32_e32 v37, v2
	v_mov_b32_e32 v38, v2
	v_mov_b32_e32 v39, v2
	v_mov_b32_e32 v40, v2
	v_mov_b32_e32 v41, v2
	v_mov_b32_e32 v50, v2
	v_mov_b32_e32 v51, v2
	v_mov_b32_e32 v52, v2
	v_mov_b32_e32 v53, v2
	v_mov_b32_e32 v54, v2
	v_mov_b32_e32 v55, v2
	v_mov_b32_e32 v56, v2
	v_mov_b32_e32 v57, v2
	v_mov_b32_e32 v10, v2
	v_mov_b32_e32 v11, v2
	v_mov_b32_e32 v12, v2
	v_mov_b32_e32 v13, v2
	v_mov_b32_e32 v14, v2
	v_mov_b32_e32 v15, v2
	v_mov_b32_e32 v16, v2
	v_mov_b32_e32 v17, v2
	v_mov_b32_e32 v26, v2
	v_mov_b32_e32 v27, v2
	v_mov_b32_e32 v28, v2
	v_mov_b32_e32 v29, v2
	v_mov_b32_e32 v30, v2
	v_mov_b32_e32 v31, v2
	v_mov_b32_e32 v32, v2
	v_mov_b32_e32 v33, v2
	v_mov_b32_e32 v42, v2
	v_mov_b32_e32 v43, v2
	v_mov_b32_e32 v44, v2
	v_mov_b32_e32 v45, v2
	v_mov_b32_e32 v46, v2
	v_mov_b32_e32 v47, v2
	v_mov_b32_e32 v48, v2
	v_mov_b32_e32 v49, v2
	v_mov_b32_e32 v58, v2
	v_mov_b32_e32 v59, v2
	v_mov_b32_e32 v60, v2
	v_mov_b32_e32 v61, v2
	v_mov_b32_e32 v62, v2
	v_mov_b32_e32 v63, v2
	v_mov_b32_e32 v64, v2
	v_mov_b32_e32 v65, v2
	v_mov_b32_e32 v66, v2
	v_mov_b32_e32 v67, v2
	v_mov_b32_e32 v68, v2
	v_mov_b32_e32 v69, v2
	v_mov_b32_e32 v70, v2
	v_mov_b32_e32 v71, v2
	v_mov_b32_e32 v72, v2
	v_mov_b32_e32 v73, v2
	v_mov_b32_e32 v82, v2
	v_mov_b32_e32 v83, v2
	v_mov_b32_e32 v84, v2
	v_mov_b32_e32 v85, v2
	v_mov_b32_e32 v86, v2
	v_mov_b32_e32 v87, v2
	v_mov_b32_e32 v88, v2
	v_mov_b32_e32 v89, v2
	v_mov_b32_e32 v98, v2
	v_mov_b32_e32 v99, v2
	v_mov_b32_e32 v100, v2
	v_mov_b32_e32 v101, v2
	v_mov_b32_e32 v102, v2
	v_mov_b32_e32 v103, v2
	v_mov_b32_e32 v104, v2
	v_mov_b32_e32 v105, v2
	v_mov_b32_e32 v114, v2
	v_mov_b32_e32 v115, v2
	v_mov_b32_e32 v116, v2
	v_mov_b32_e32 v117, v2
	v_mov_b32_e32 v118, v2
	v_mov_b32_e32 v119, v2
	v_mov_b32_e32 v120, v2
	v_mov_b32_e32 v121, v2
	v_mov_b32_e32 v74, v2
	v_mov_b32_e32 v75, v2
	v_mov_b32_e32 v76, v2
	v_mov_b32_e32 v77, v2
	v_mov_b32_e32 v78, v2
	v_mov_b32_e32 v79, v2
	v_mov_b32_e32 v80, v2
	v_mov_b32_e32 v81, v2
	v_mov_b32_e32 v90, v2
	v_mov_b32_e32 v91, v2
	v_mov_b32_e32 v92, v2
	v_mov_b32_e32 v93, v2
	v_mov_b32_e32 v94, v2
	v_mov_b32_e32 v95, v2
	v_mov_b32_e32 v96, v2
	v_mov_b32_e32 v97, v2
	v_mov_b32_e32 v106, v2
	v_mov_b32_e32 v107, v2
	v_mov_b32_e32 v108, v2
	v_mov_b32_e32 v109, v2
	v_mov_b32_e32 v110, v2
	v_mov_b32_e32 v111, v2
	v_mov_b32_e32 v112, v2
	v_mov_b32_e32 v113, v2
	v_mov_b32_e32 v122, v2
	v_mov_b32_e32 v123, v2
	v_mov_b32_e32 v124, v2
	v_mov_b32_e32 v125, v2
	v_mov_b32_e32 v126, v2
	v_mov_b32_e32 v127, v2
	v_mov_b32_e32 v128, v2
	v_mov_b32_e32 v129, v2
	v_and_b32_e32 v234, 0x3ff, v0
	v_and_b32_e32 v233, 63, v234
	v_readfirstlane_b32 s83, v234
	v_lshrrev_b32_e32 v232, 2, v233
	v_and_b32_e32 v231, 3, v233
	v_lshlrev_b32_e32 v231, 4, v231
	v_lshrrev_b32_e32 v230, 5, v233
	v_lshlrev_b32_e32 v230, 5, v230
	v_xor_b32_e32 v231, v231, v230
	v_lshl_or_b32 v201, v232, 12, v231
	v_add_u32_e32 v230, 64, v201
	v_lshrrev_b32_e32 v233, 2, v232
	v_and_b32_e32 v234, 3, v232
	v_lshl_or_b32 v233, v233, 3, v234
	v_lshl_or_b32 v231, v233, 12, v231
	v_add_u32_e32 v232, 64, v231
	v_add_u32_e32 v233, 0x4000, v231
	v_add_u32_e32 v234, 0x4040, v231
	s_lshr_b32 s83, s83, 6
	s_lshr_b32 s84, s83, 2
	s_and_b32 s83, s83, 3
	s_lshl_b32 s32, s84, 2
	s_add_i32 s32, s32, s83
	s_lshl_b32 s32, s32, 11
	s_xor_b32 s69, s84, 1
	s_mul_i32 s78, s69, 0xc000
	s_add_i32 s78, s78, 0x10000
	s_lshl_b32 s79, s69, 14
	s_sub_i32 s79, 0x18000, s79
	s_lshl_b32 s82, s83, 12
	s_add_i32 s78, s78, s82
	s_add_i32 s79, s79, s82
	s_lshl_b32 s69, s69, 19
	s_lshl_b32 s82, s83, 17
	s_add_i32 s69, s69, s82
	s_mul_i32 s80, s84, 0x45
	s_add_i32 s80, s80, 30
	s_mul_i32 s81, s84, 0x47
	s_sub_i32 s81, 0x63, s81
	s_lshl_b32 s82, s32, 5
	s_add_u32 s74, s24, s82
	s_addc_u32 s75, s25, 0
	s_sub_u32 s70, s74, 0x80000
	s_subb_u32 s71, s75, 0
	s_sub_i32 s82, s84, 1
	s_lshl_b32 s82, s82, 7
	s_add_i32 s82, s82, s69
	s_add_u32 s76, s59, s82
	s_addc_u32 s77, s64, 0
	s_mov_b32 s82, 0
; #define PG8_STAGE(bufoff, gbase, voff) do { _Pragma("unroll") for (int _i = 0; _i < 2; ++_i) \
;         __builtin_amdgcn_global_load_lds((const unsigned*)((const char*)(gbase) + (voff)[_i]), (PG8_LAS unsigned*)(lds + (bufoff) + ldsw + _i * 8192), 16, 0, 0); } while (0)
; #define PG8_LDA(dst, b, h) do { _Pragma("unroll") for (int m = 0; m < 4; ++m) _Pragma("unroll") for (int k = 0; k < 2; ++k) dst[m][k] = *(const PG8_LAS bf16x8*)(lds + PG8_SA(b, h) + aoff + m * 2048 + k * 1024); } while (0)
; #define PG8_LDB(dst, b, h) do { _Pragma("unroll") for (int n = 0; n < 2; ++n) _Pragma("unroll") for (int k = 0; k < 2; ++k) dst[n][k] = *(const PG8_LAS bf16x8*)(lds + PG8_SB(b, h) + boff + n * 2048 + k * 1024); } while (0)
; #define PG8_MMA(ai, bj, At, Bt) do { __builtin_amdgcn_s_setprio(1); _Pragma("unroll") for (int m = 0; m < 4; ++m) _Pragma("unroll") for (int n = 0; n < 2; ++n) _Pragma("unroll") for (int k = 0; k < 2; ++k) \
;         acc[ai][bj][m][n] = __builtin_amdgcn_mfma_f32_16x16x32_bf16(Bt[n][k], At[m][k], acc[ai][bj][m][n], 0, 0, 0); __builtin_amdgcn_s_setprio(0); } while (0)
; #define PG8_WAIT_V(n) asm volatile("s_waitcnt vmcnt(" #n ")" ::: "memory")
; #define PG8_BAR __builtin_amdgcn_s_barrier()
; template <class Epi, class Sched, bool ALIGN_EPI = false, bool SP2 = false>
; __device__ __forceinline__ void gemm_phase(PG8_LAS unsigned char* lds, const Gemm g, const Sched& S, const Epi& E) {
;     ...
;         for (int t = 0; t < nt; t += 2) {
;             const bool last = (t == nt - 2);
;             const char* a1 = cA + (size_t)(t + 1) * kstep;
;             const char* a2 = last ? nA : cA + (size_t)(t + 2) * kstep; const char* b2 = last ? nB : cB + (size_t)(t + 2) * kstep;
;             const char* a3 = a2 + kstep; const char* b3 = b2 + kstep;
;             if (last && has_next) S.a_ready(nxt);
;             if constexpr (SP2) {
;             PG8_LDB(B0, 0, 0); PG8_LDB(B1, 0, 1); PG8_SCHED; PG8_LDA(At, 0, 0); PG8_STAGE(PG8_SA(1, 1), a1 + hstep, voffA);
;             PG8_WAIT_V(8); PG8_WAIT_L(0); PG8_BAR; PG8_MMA(0, 0, At, B0); PG8_MMA(0, 1, At, B1); PG8_BAR; PG8_SCHED;
;             PG8_LDA(At, 0, 1); PG8_STAGE(PG8_SB(0, 0), b2, voffB); PG8_STAGE(PG8_SB(0, 1), b2 + hstep, voffB); PG8_STAGE(PG8_SA(0, 0), a2, voffA);
;             PG8_WAIT_V(8); PG8_WAIT_L(0); PG8_BAR; PG8_MMA(1, 0, At, B0); PG8_MMA(1, 1, At, B1); PG8_BAR; PG8_SCHED;
.Lsp4_loop_3:
	s_add_i32 m0, s32, 0x8000
	s_nop 0
	global_load_lds_dwordx4 v201, s[70:71]
	s_add_i32 m0, s32, 0x8400
	s_nop 0
	global_load_lds_dwordx4 v230, s[70:71]
	s_add_i32 m0, s32, 0xc000
	s_nop 0
	global_load_lds_dwordx4 v201, s[74:75]
	s_add_i32 m0, s32, 0xc400
	s_nop 0
	global_load_lds_dwordx4 v230, s[74:75]
	ds_read_b128 v[146:149], v153
	ds_read_b128 v[158:161], v153 offset:1024
	ds_read_b128 v[162:165], v153 offset:2048
	ds_read_b128 v[166:169], v153 offset:3072
	ds_read_b128 v[170:173], v153 offset:16384
	ds_read_b128 v[174:177], v153 offset:17408
	ds_read_b128 v[178:181], v153 offset:18432
	ds_read_b128 v[182:185], v153 offset:19456
	ds_read_b128 v[186:189], v155
	ds_read_b128 v[190:193], v155 offset:1024
	ds_read_b128 v[194:197], v155 offset:2048
	ds_read_b128 v[202:205], v155 offset:3072
	ds_read_b128 v[206:209], v155 offset:4096
	ds_read_b128 v[210:213], v155 offset:5120
	ds_read_b128 v[214:217], v155 offset:6144
	ds_read_b128 v[218:221], v155 offset:7168
	s_waitcnt lgkmcnt(8)
	s_add_i32 m0, s78, 0x0
	s_nop 0
	global_load_lds_dwordx4 v231, s[76:77]
	s_add_i32 m0, s78, 0x400
	s_nop 0
	global_load_lds_dwordx4 v232, s[76:77]
	s_add_i32 m0, s78, 0x800
	s_nop 0
	global_load_lds_dwordx4 v233, s[76:77]
	s_add_i32 m0, s78, 0xc00
	s_nop 0
	global_load_lds_dwordx4 v234, s[76:77]
	s_add_u32 s70, s70, 0x80
	s_addc_u32 s71, s71, 0
	s_add_u32 s74, s74, 0x80
	s_addc_u32 s75, s75, 0
	s_add_u32 s76, s76, 0x80
	s_addc_u32 s77, s77, 0
	s_cmp_lg_u32 s82, 30
	s_cbranch_scc1 .Lsp4_noA_3
	s_lshl_b32 s83, s32, 5
	s_add_u32 s70, s57, s83
	s_addc_u32 s71, s19, 0
	s_add_u32 s74, s70, 0x80000
	s_addc_u32 s75, s71, 0
.Lsp4_noA_3:
	s_cmp_lg_u32 s82, s80
	s_cbranch_scc1 .Lsp4_noB0_3
	s_add_u32 s76, s58, s69
	s_addc_u32 s77, s17, 0
.Lsp4_noB0_3:
	s_waitcnt lgkmcnt(0)
	s_barrier
	s_setprio 1
	v_mfma_f32_16x16x32_bf16 v[126:129], v[146:149], v[186:189], v[126:129]
	v_mfma_f32_16x16x32_bf16 v[122:125], v[162:165], v[186:189], v[122:125]
	v_mfma_f32_16x16x32_bf16 v[118:121], v[170:173], v[186:189], v[118:121]
	v_mfma_f32_16x16x32_bf16 v[114:117], v[178:181], v[186:189], v[114:117]
	ds_read_b128 v[186:189], v155 offset:16384
	v_mfma_f32_16x16x32_bf16 v[110:113], v[146:149], v[194:197], v[110:113]
	v_mfma_f32_16x16x32_bf16 v[106:109], v[162:165], v[194:197], v[106:109]
	v_mfma_f32_16x16x32_bf16 v[102:105], v[170:173], v[194:197], v[102:105]
	v_mfma_f32_16x16x32_bf16 v[98:101], v[178:181], v[194:197], v[98:101]
	ds_read_b128 v[194:197], v155 offset:18432
	v_mfma_f32_16x16x32_bf16 v[94:97], v[146:149], v[206:209], v[94:97]
	v_mfma_f32_16x16x32_bf16 v[90:93], v[162:165], v[206:209], v[90:93]
	v_mfma_f32_16x16x32_bf16 v[86:89], v[170:173], v[206:209], v[86:89]
	v_mfma_f32_16x16x32_bf16 v[82:85], v[178:181], v[206:209], v[82:85]
	ds_read_b128 v[206:209], v155 offset:20480
	v_mfma_f32_16x16x32_bf16 v[78:81], v[146:149], v[214:217], v[78:81]
	v_mfma_f32_16x16x32_bf16 v[74:77], v[162:165], v[214:217], v[74:77]
	v_mfma_f32_16x16x32_bf16 v[70:73], v[170:173], v[214:217], v[70:73]
	v_mfma_f32_16x16x32_bf16 v[66:69], v[178:181], v[214:217], v[66:69]
	ds_read_b128 v[214:217], v155 offset:22528
	v_mfma_f32_16x16x32_bf16 v[126:129], v[158:161], v[190:193], v[126:129]
	v_mfma_f32_16x16x32_bf16 v[122:125], v[166:169], v[190:193], v[122:125]
	v_mfma_f32_16x16x32_bf16 v[118:121], v[174:177], v[190:193], v[118:121]
	v_mfma_f32_16x16x32_bf16 v[114:117], v[182:185], v[190:193], v[114:117]
	ds_read_b128 v[190:193], v155 offset:17408
	v_mfma_f32_16x16x32_bf16 v[110:113], v[158:161], v[202:205], v[110:113]
	v_mfma_f32_16x16x32_bf16 v[106:109], v[166:169], v[202:205], v[106:109]
	v_mfma_f32_16x16x32_bf16 v[102:105], v[174:177], v[202:205], v[102:105]
	v_mfma_f32_16x16x32_bf16 v[98:101], v[182:185], v[202:205], v[98:101]
	ds_read_b128 v[202:205], v155 offset:19456
	v_mfma_f32_16x16x32_bf16 v[94:97], v[158:161], v[210:213], v[94:97]
	v_mfma_f32_16x16x32_bf16 v[90:93], v[166:169], v[210:213], v[90:93]
	v_mfma_f32_16x16x32_bf16 v[86:89], v[174:177], v[210:213], v[86:89]
	v_mfma_f32_16x16x32_bf16 v[82:85], v[182:185], v[210:213], v[82:85]
	ds_read_b128 v[210:213], v155 offset:21504
	v_mfma_f32_16x16x32_bf16 v[78:81], v[158:161], v[218:221], v[78:81]
	v_mfma_f32_16x16x32_bf16 v[74:77], v[166:169], v[218:221], v[74:77]
	v_mfma_f32_16x16x32_bf16 v[70:73], v[174:177], v[218:221], v[70:73]
	v_mfma_f32_16x16x32_bf16 v[66:69], v[182:185], v[218:221], v[66:69]
	ds_read_b128 v[218:221], v155 offset:23552
	s_waitcnt lgkmcnt(4)
	v_mfma_f32_16x16x32_bf16 v[62:65], v[146:149], v[186:189], v[62:65]
	v_mfma_f32_16x16x32_bf16 v[58:61], v[162:165], v[186:189], v[58:61]
	v_mfma_f32_16x16x32_bf16 v[54:57], v[170:173], v[186:189], v[54:57]
	v_mfma_f32_16x16x32_bf16 v[50:53], v[178:181], v[186:189], v[50:53]
	v_mfma_f32_16x16x32_bf16 v[46:49], v[146:149], v[194:197], v[46:49]
	v_mfma_f32_16x16x32_bf16 v[42:45], v[162:165], v[194:197], v[42:45]
	v_mfma_f32_16x16x32_bf16 v[38:41], v[170:173], v[194:197], v[38:41]
	v_mfma_f32_16x16x32_bf16 v[34:37], v[178:181], v[194:197], v[34:37]
	v_mfma_f32_16x16x32_bf16 v[30:33], v[146:149], v[206:209], v[30:33]
	v_mfma_f32_16x16x32_bf16 v[26:29], v[162:165], v[206:209], v[26:29]
	v_mfma_f32_16x16x32_bf16 v[22:25], v[170:173], v[206:209], v[22:25]
	v_mfma_f32_16x16x32_bf16 v[18:21], v[178:181], v[206:209], v[18:21]
	v_mfma_f32_16x16x32_bf16 v[14:17], v[146:149], v[214:217], v[14:17]
	v_mfma_f32_16x16x32_bf16 v[10:13], v[162:165], v[214:217], v[10:13]
	v_mfma_f32_16x16x32_bf16 v[6:9], v[170:173], v[214:217], v[6:9]
	v_mfma_f32_16x16x32_bf16 v[2:5], v[178:181], v[214:217], v[2:5]
	s_waitcnt lgkmcnt(0)
	v_mfma_f32_16x16x32_bf16 v[62:65], v[158:161], v[190:193], v[62:65]
	v_mfma_f32_16x16x32_bf16 v[58:61], v[166:169], v[190:193], v[58:61]
	v_mfma_f32_16x16x32_bf16 v[54:57], v[174:177], v[190:193], v[54:57]
	v_mfma_f32_16x16x32_bf16 v[50:53], v[182:185], v[190:193], v[50:53]
	v_mfma_f32_16x16x32_bf16 v[46:49], v[158:161], v[202:205], v[46:49]
	v_mfma_f32_16x16x32_bf16 v[42:45], v[166:169], v[202:205], v[42:45]
	v_mfma_f32_16x16x32_bf16 v[38:41], v[174:177], v[202:205], v[38:41]
	v_mfma_f32_16x16x32_bf16 v[34:37], v[182:185], v[202:205], v[34:37]
	v_mfma_f32_16x16x32_bf16 v[30:33], v[158:161], v[210:213], v[30:33]
	v_mfma_f32_16x16x32_bf16 v[26:29], v[166:169], v[210:213], v[26:29]
	v_mfma_f32_16x16x32_bf16 v[22:25], v[174:177], v[210:213], v[22:25]
	v_mfma_f32_16x16x32_bf16 v[18:21], v[182:185], v[210:213], v[18:21]
	v_mfma_f32_16x16x32_bf16 v[14:17], v[158:161], v[218:221], v[14:17]
	v_mfma_f32_16x16x32_bf16 v[10:13], v[166:169], v[218:221], v[10:13]
	v_mfma_f32_16x16x32_bf16 v[6:9], v[174:177], v[218:221], v[6:9]
	v_mfma_f32_16x16x32_bf16 v[2:5], v[182:185], v[218:221], v[2:5]
	s_setprio 0
	s_waitcnt vmcnt(0)
	s_barrier
; #define PG8_STAGE(bufoff, gbase, voff) do { _Pragma("unroll") for (int _i = 0; _i < 2; ++_i) \
;         __builtin_amdgcn_global_load_lds((const unsigned*)((const char*)(gbase) + (voff)[_i]), (PG8_LAS unsigned*)(lds + (bufoff) + ldsw + _i * 8192), 16, 0, 0); } while (0)
; #define PG8_LDA(dst, b, h) do { _Pragma("unroll") for (int m = 0; m < 4; ++m) _Pragma("unroll") for (int k = 0; k < 2; ++k) dst[m][k] = *(const PG8_LAS bf16x8*)(lds + PG8_SA(b, h) + aoff + m * 2048 + k * 1024); } while (0)
; #define PG8_LDB(dst, b, h) do { _Pragma("unroll") for (int n = 0; n < 2; ++n) _Pragma("unroll") for (int k = 0; k < 2; ++k) dst[n][k] = *(const PG8_LAS bf16x8*)(lds + PG8_SB(b, h) + boff + n * 2048 + k * 1024); } while (0)
; template <class Epi, class Sched, bool ALIGN_EPI = false, bool SP2 = false>
; __device__ __forceinline__ void gemm_phase(PG8_LAS unsigned char* lds, const Gemm g, const Sched& S, const Epi& E) {
;     ...
;         for (int t = 0; t < nt; t += 2) {
;             const bool last = (t == nt - 2);
;             const char* a1 = cA + (size_t)(t + 1) * kstep;
;             const char* a2 = last ? nA : cA + (size_t)(t + 2) * kstep; const char* b2 = last ? nB : cB + (size_t)(t + 2) * kstep;
;             const char* a3 = a2 + kstep; const char* b3 = b2 + kstep;
;             if (last && has_next) S.a_ready(nxt);
;             if constexpr (SP2) {
;             PG8_LDB(B0, 0, 0); PG8_LDB(B1, 0, 1); PG8_SCHED; PG8_LDA(At, 0, 0); PG8_STAGE(PG8_SA(1, 1), a1 + hstep, voffA);
;             PG8_WAIT_V(8); PG8_WAIT_L(0); PG8_BAR; PG8_MMA(0, 0, At, B0); PG8_MMA(0, 1, At, B1); PG8_BAR; PG8_SCHED;
;             PG8_LDA(At, 0, 1); PG8_STAGE(PG8_SB(0, 0), b2, voffB); PG8_STAGE(PG8_SB(0, 1), b2 + hstep, voffB); PG8_STAGE(PG8_SA(0, 0), a2, voffA);
;             PG8_WAIT_V(8); PG8_WAIT_L(0); PG8_BAR; PG8_MMA(1, 0, At, B0); PG8_MMA(1, 1, At, B1); PG8_BAR; PG8_SCHED;
;             PG8_LDB(B0, 1, 0); PG8_LDB(B1, 1, 1); PG8_SCHED; PG8_LDA(At, 1, 0); PG8_STAGE(PG8_SA(0, 1), a2 + hstep, voffA);
;             PG8_WAIT_V(8); PG8_WAIT_L(0); PG8_BAR; PG8_MMA(0, 0, At, B0); PG8_MMA(0, 1, At, B1); PG8_BAR; PG8_SCHED;
;             PG8_LDA(At, 1, 1); PG8_STAGE(PG8_SB(1, 0), b3, voffB); PG8_STAGE(PG8_SB(1, 1), b3 + hstep, voffB); PG8_STAGE(PG8_SA(1, 0), a3, voffA);
;             PG8_WAIT_V(8); PG8_WAIT_L(0); PG8_BAR; PG8_MMA(1, 0, At, B0); PG8_MMA(1, 1, At, B1); PG8_BAR; PG8_SCHED;
	s_add_i32 m0, s32, 0x0
	s_nop 0
	global_load_lds_dwordx4 v201, s[70:71]
	s_add_i32 m0, s32, 0x400
	s_nop 0
	global_load_lds_dwordx4 v230, s[70:71]
	s_add_i32 m0, s32, 0x4000
	s_nop 0
	global_load_lds_dwordx4 v201, s[74:75]
	s_add_i32 m0, s32, 0x4400
	s_nop 0
	global_load_lds_dwordx4 v230, s[74:75]
	ds_read_b128 v[146:149], v153 offset:32768
	ds_read_b128 v[158:161], v153 offset:33792
	ds_read_b128 v[162:165], v153 offset:34816
	ds_read_b128 v[166:169], v153 offset:35840
	ds_read_b128 v[170:173], v153 offset:49152
	ds_read_b128 v[174:177], v153 offset:50176
	ds_read_b128 v[178:181], v153 offset:51200
	ds_read_b128 v[182:185], v153 offset:52224
	ds_read_b128 v[186:189], v155 offset:32768
	ds_read_b128 v[190:193], v155 offset:33792
	ds_read_b128 v[194:197], v155 offset:34816
	ds_read_b128 v[202:205], v155 offset:35840
	ds_read_b128 v[206:209], v155 offset:36864
	ds_read_b128 v[210:213], v155 offset:37888
	ds_read_b128 v[214:217], v155 offset:38912
	ds_read_b128 v[218:221], v155 offset:39936
	s_waitcnt lgkmcnt(8)
	s_add_i32 m0, s79, 0x0
	s_nop 0
	global_load_lds_dwordx4 v231, s[76:77]
	s_add_i32 m0, s79, 0x400
	s_nop 0
	global_load_lds_dwordx4 v232, s[76:77]
	s_add_i32 m0, s79, 0x800
	s_nop 0
	global_load_lds_dwordx4 v233, s[76:77]
	s_add_i32 m0, s79, 0xc00
	s_nop 0
	global_load_lds_dwordx4 v234, s[76:77]
	s_add_u32 s70, s70, 0x80
	s_addc_u32 s71, s71, 0
	s_add_u32 s74, s74, 0x80
	s_addc_u32 s75, s75, 0
	s_add_u32 s76, s76, 0x80
	s_addc_u32 s77, s77, 0
	s_cmp_lg_u32 s82, s81
	s_cbranch_scc1 .Lsp4_noB1_3
	s_add_u32 s76, s58, s69
	s_addc_u32 s77, s17, 0
.Lsp4_noB1_3:
	s_waitcnt lgkmcnt(0)
	s_barrier
	s_setprio 1
	v_mfma_f32_16x16x32_bf16 v[126:129], v[146:149], v[186:189], v[126:129]
	v_mfma_f32_16x16x32_bf16 v[122:125], v[162:165], v[186:189], v[122:125]
	v_mfma_f32_16x16x32_bf16 v[118:121], v[170:173], v[186:189], v[118:121]
	v_mfma_f32_16x16x32_bf16 v[114:117], v[178:181], v[186:189], v[114:117]
	ds_read_b128 v[186:189], v155 offset:49152
	v_mfma_f32_16x16x32_bf16 v[110:113], v[146:149], v[194:197], v[110:113]
	v_mfma_f32_16x16x32_bf16 v[106:109], v[162:165], v[194:197], v[106:109]
	v_mfma_f32_16x16x32_bf16 v[102:105], v[170:173], v[194:197], v[102:105]
	v_mfma_f32_16x16x32_bf16 v[98:101], v[178:181], v[194:197], v[98:101]
	ds_read_b128 v[194:197], v155 offset:51200
	v_mfma_f32_16x16x32_bf16 v[94:97], v[146:149], v[206:209], v[94:97]
	v_mfma_f32_16x16x32_bf16 v[90:93], v[162:165], v[206:209], v[90:93]
	v_mfma_f32_16x16x32_bf16 v[86:89], v[170:173], v[206:209], v[86:89]
	v_mfma_f32_16x16x32_bf16 v[82:85], v[178:181], v[206:209], v[82:85]
	ds_read_b128 v[206:209], v155 offset:53248
	v_mfma_f32_16x16x32_bf16 v[78:81], v[146:149], v[214:217], v[78:81]
	v_mfma_f32_16x16x32_bf16 v[74:77], v[162:165], v[214:217], v[74:77]
	v_mfma_f32_16x16x32_bf16 v[70:73], v[170:173], v[214:217], v[70:73]
	v_mfma_f32_16x16x32_bf16 v[66:69], v[178:181], v[214:217], v[66:69]
	ds_read_b128 v[214:217], v155 offset:55296
	v_mfma_f32_16x16x32_bf16 v[126:129], v[158:161], v[190:193], v[126:129]
	v_mfma_f32_16x16x32_bf16 v[122:125], v[166:169], v[190:193], v[122:125]
	v_mfma_f32_16x16x32_bf16 v[118:121], v[174:177], v[190:193], v[118:121]
	v_mfma_f32_16x16x32_bf16 v[114:117], v[182:185], v[190:193], v[114:117]
	ds_read_b128 v[190:193], v155 offset:50176
	v_mfma_f32_16x16x32_bf16 v[110:113], v[158:161], v[202:205], v[110:113]
	v_mfma_f32_16x16x32_bf16 v[106:109], v[166:169], v[202:205], v[106:109]
	v_mfma_f32_16x16x32_bf16 v[102:105], v[174:177], v[202:205], v[102:105]
	v_mfma_f32_16x16x32_bf16 v[98:101], v[182:185], v[202:205], v[98:101]
	ds_read_b128 v[202:205], v155 offset:52224
	v_mfma_f32_16x16x32_bf16 v[94:97], v[158:161], v[210:213], v[94:97]
	v_mfma_f32_16x16x32_bf16 v[90:93], v[166:169], v[210:213], v[90:93]
	v_mfma_f32_16x16x32_bf16 v[86:89], v[174:177], v[210:213], v[86:89]
	v_mfma_f32_16x16x32_bf16 v[82:85], v[182:185], v[210:213], v[82:85]
	ds_read_b128 v[210:213], v155 offset:54272
	v_mfma_f32_16x16x32_bf16 v[78:81], v[158:161], v[218:221], v[78:81]
	v_mfma_f32_16x16x32_bf16 v[74:77], v[166:169], v[218:221], v[74:77]
	v_mfma_f32_16x16x32_bf16 v[70:73], v[174:177], v[218:221], v[70:73]
	v_mfma_f32_16x16x32_bf16 v[66:69], v[182:185], v[218:221], v[66:69]
	ds_read_b128 v[218:221], v155 offset:56320
	s_waitcnt lgkmcnt(4)
	v_mfma_f32_16x16x32_bf16 v[62:65], v[146:149], v[186:189], v[62:65]
	v_mfma_f32_16x16x32_bf16 v[58:61], v[162:165], v[186:189], v[58:61]
	v_mfma_f32_16x16x32_bf16 v[54:57], v[170:173], v[186:189], v[54:57]
	v_mfma_f32_16x16x32_bf16 v[50:53], v[178:181], v[186:189], v[50:53]
	v_mfma_f32_16x16x32_bf16 v[46:49], v[146:149], v[194:197], v[46:49]
	v_mfma_f32_16x16x32_bf16 v[42:45], v[162:165], v[194:197], v[42:45]
	v_mfma_f32_16x16x32_bf16 v[38:41], v[170:173], v[194:197], v[38:41]
	v_mfma_f32_16x16x32_bf16 v[34:37], v[178:181], v[194:197], v[34:37]
	v_mfma_f32_16x16x32_bf16 v[30:33], v[146:149], v[206:209], v[30:33]
	v_mfma_f32_16x16x32_bf16 v[26:29], v[162:165], v[206:209], v[26:29]
	v_mfma_f32_16x16x32_bf16 v[22:25], v[170:173], v[206:209], v[22:25]
	v_mfma_f32_16x16x32_bf16 v[18:21], v[178:181], v[206:209], v[18:21]
	v_mfma_f32_16x16x32_bf16 v[14:17], v[146:149], v[214:217], v[14:17]
	v_mfma_f32_16x16x32_bf16 v[10:13], v[162:165], v[214:217], v[10:13]
	v_mfma_f32_16x16x32_bf16 v[6:9], v[170:173], v[214:217], v[6:9]
	v_mfma_f32_16x16x32_bf16 v[2:5], v[178:181], v[214:217], v[2:5]
	s_waitcnt lgkmcnt(0)
	v_mfma_f32_16x16x32_bf16 v[62:65], v[158:161], v[190:193], v[62:65]
	v_mfma_f32_16x16x32_bf16 v[58:61], v[166:169], v[190:193], v[58:61]
	v_mfma_f32_16x16x32_bf16 v[54:57], v[174:177], v[190:193], v[54:57]
	v_mfma_f32_16x16x32_bf16 v[50:53], v[182:185], v[190:193], v[50:53]
	v_mfma_f32_16x16x32_bf16 v[46:49], v[158:161], v[202:205], v[46:49]
	v_mfma_f32_16x16x32_bf16 v[42:45], v[166:169], v[202:205], v[42:45]
	v_mfma_f32_16x16x32_bf16 v[38:41], v[174:177], v[202:205], v[38:41]
	v_mfma_f32_16x16x32_bf16 v[34:37], v[182:185], v[202:205], v[34:37]
	v_mfma_f32_16x16x32_bf16 v[30:33], v[158:161], v[210:213], v[30:33]
	v_mfma_f32_16x16x32_bf16 v[26:29], v[166:169], v[210:213], v[26:29]
	v_mfma_f32_16x16x32_bf16 v[22:25], v[174:177], v[210:213], v[22:25]
	v_mfma_f32_16x16x32_bf16 v[18:21], v[182:185], v[210:213], v[18:21]
	v_mfma_f32_16x16x32_bf16 v[14:17], v[158:161], v[218:221], v[14:17]
	v_mfma_f32_16x16x32_bf16 v[10:13], v[166:169], v[218:221], v[10:13]
	v_mfma_f32_16x16x32_bf16 v[6:9], v[174:177], v[218:221], v[6:9]
	v_mfma_f32_16x16x32_bf16 v[2:5], v[182:185], v[218:221], v[2:5]
	s_setprio 0
	s_waitcnt vmcnt(0)
	s_barrier
	s_add_i32 s82, s82, 2
	s_cmp_lt_u32 s82, 32
	s_cbranch_scc1 .Lsp4_loop_3
	s_and_b64 vcc, exec, s[14:15]
	s_cbranch_vccz .LBB0_1180
	s_barrier

; __global__ void __launch_bounds__(NTHR, 2) hymba_fwd(Params P) {
	.amdhsa_kernel _Z9hymba_fwd6Params
		.amdhsa_group_segment_fixed_size 0
		.amdhsa_private_segment_fixed_size 0
		.amdhsa_kernarg_size 384
		.amdhsa_user_sgpr_count 2
		.amdhsa_user_sgpr_dispatch_ptr 0
		.amdhsa_user_sgpr_queue_ptr 0
		.amdhsa_user_sgpr_kernarg_segment_ptr 1
		.amdhsa_user_sgpr_dispatch_id 0
		.amdhsa_user_sgpr_kernarg_preload_length 0
		.amdhsa_user_sgpr_kernarg_preload_offset 0
		.amdhsa_user_sgpr_private_segment_size 0
		.amdhsa_uses_dynamic_stack 0
		.amdhsa_enable_private_segment 0
		.amdhsa_system_sgpr_workgroup_id_x 1
		.amdhsa_system_sgpr_workgroup_id_y 0
		.amdhsa_system_sgpr_workgroup_id_z 0
		.amdhsa_system_sgpr_workgroup_info 0
		.amdhsa_system_vgpr_workitem_id 2
		.amdhsa_next_free_vgpr 256
		.amdhsa_next_free_sgpr 102
		.amdhsa_accum_offset 256
		.amdhsa_reserve_vcc 1
		.amdhsa_float_round_mode_32 0
		.amdhsa_float_round_mode_16_64 0
		.amdhsa_float_denorm_mode_32 3
		.amdhsa_float_denorm_mode_16_64 3
		.amdhsa_dx10_clamp 1
		.amdhsa_ieee_mode 1
		.amdhsa_fp16_overflow 0
		.amdhsa_tg_split 0
		.amdhsa_exception_fp_ieee_invalid_op 0
		.amdhsa_exception_fp_denorm_src 0
		.amdhsa_exception_fp_ieee_div_zero 0
		.amdhsa_exception_fp_ieee_overflow 0
		.amdhsa_exception_fp_ieee_underflow 0
		.amdhsa_exception_fp_ieee_inexact 0
		.amdhsa_exception_int_div_zero 0
	.end_amdhsa_kernel

; __global__ void __launch_bounds__(NTHR, 2) hymba_fwd(Params P) {
amdhsa.kernels:
  - .agpr_count:     0
    .args:
      - .offset:         0
        .size:           128
        .value_kind:     by_value
      - .offset:         128
        .size:           4
        .value_kind:     hidden_block_count_x
      - .offset:         132
        .size:           4
        .value_kind:     hidden_block_count_y
      - .offset:         136
        .size:           4
        .value_kind:     hidden_block_count_z
      - .offset:         140
        .size:           2
        .value_kind:     hidden_group_size_x
      - .offset:         142
        .size:           2
        .value_kind:     hidden_group_size_y
      - .offset:         144
        .size:           2
        .value_kind:     hidden_group_size_z
      - .offset:         146
        .size:           2
        .value_kind:     hidden_remainder_x
      - .offset:         148
        .size:           2
        .value_kind:     hidden_remainder_y
      - .offset:         150
        .size:           2
        .value_kind:     hidden_remainder_z
      - .offset:         168
        .size:           8
        .value_kind:     hidden_global_offset_x
      - .offset:         176
        .size:           8
        .value_kind:     hidden_global_offset_y
      - .offset:         184
        .size:           8
        .value_kind:     hidden_global_offset_z
      - .offset:         192
        .size:           2
        .value_kind:     hidden_grid_dims
      - .offset:         216
        .size:           8
        .value_kind:     hidden_multigrid_sync_arg
      - .offset:         248
        .size:           4
        .value_kind:     hidden_dynamic_lds_size
    .group_segment_fixed_size: 0
    .kernarg_segment_align: 8
    .kernarg_segment_size: 384
    .language:       OpenCL C
    .language_version:
      - 2
      - 0
    .max_flat_workgroup_size: 512
    .name:           _Z9hymba_fwd6Params
    .private_segment_fixed_size: 0
    .sgpr_count:     108
    .sgpr_spill_count: 11
    .symbol:         _Z9hymba_fwd6Params.kd
    .uniform_work_group_size: 1
    .uses_dynamic_stack: false
    .vgpr_count:     256
    .vgpr_spill_count: 0
    .wavefront_size: 64
